# GEMM K-loops: 12 of 16 LDS-DMA per iteration use saddr+voffset form (SALU base math), deleting their 64-bit VALU address adds
# speedup vs baseline: 1.0086x; 1.0031x over previous
; #define PG8_STAGE(bufoff, gbase, voff) do { _Pragma("unroll") for (int _i = 0; _i < 2; ++_i) \
;         __builtin_amdgcn_global_load_lds((const unsigned*)((const char*)(gbase) + (voff)[_i]), (LAS unsigned*)(lds + (bufoff) + ldsw + _i * 8192), 16, 0, 0); } while (0)
; #define PG8_LDA(dst, b, h) do { _Pragma("unroll") for (int m = 0; m < 4; ++m) _Pragma("unroll") for (int k = 0; k < 2; ++k) dst[m][k] = *(const LAS bf16x8*)(lds + PG8_SA(b, h) + aoff + m * 2048 + k * 1024); } while (0)
; #define PG8_LDB(dst, b, h) do { _Pragma("unroll") for (int n = 0; n < 2; ++n) _Pragma("unroll") for (int k = 0; k < 2; ++k) dst[n][k] = *(const LAS bf16x8*)(lds + PG8_SB(b, h) + boff + n * 2048 + k * 1024); } while (0)
; #define PG8_MMA(ai, bj, At, Bt) do { __builtin_amdgcn_s_setprio(1); _Pragma("unroll") for (int m = 0; m < 4; ++m) _Pragma("unroll") for (int n = 0; n < 2; ++n) _Pragma("unroll") for (int k = 0; k < 2; ++k) \
;         acc[ai][bj][m][n] = __builtin_amdgcn_mfma_f32_16x16x32_bf16(Bt[n][k], At[m][k], acc[ai][bj][m][n], 0, 0, 0); __builtin_amdgcn_s_setprio(0); } while (0)
; #define PG8_WAIT_V(n) asm volatile("s_waitcnt vmcnt(" #n ")" ::: "memory")
; #define PG8_WAIT_L(n) asm volatile("s_waitcnt lgkmcnt(" #n ")" ::: "memory")
; #define PG8_BAR __builtin_amdgcn_s_barrier()
; #define PG8_SCHED __builtin_amdgcn_sched_barrier(0)
; template <class Epi, class Sched>
; DI void gemm_phase(LAS unsigned char* lds, const int K, const Sched& S, const Epi& E) {
;     ...
;             const bool last = (t == nt - 2);
;             const char* a1 = cA + (size_t)(t + 1) * kstep;
;             const char* a2 = last ? nA : cA + (size_t)(t + 2) * kstep; const char* b2 = last ? nB : cB + (size_t)(t + 2) * kstep;
;             const char* a3 = a2 + kstep; const char* b3 = b2 + kstep;
;             PG8_LDB(B0, 0, 0); PG8_LDB(B1, 0, 1); PG8_SCHED; PG8_LDA(At, 0, 0); PG8_STAGE(PG8_SA(1, 1), a1 + hstep, voffA);
;             PG8_WAIT_V(8); PG8_WAIT_L(0); PG8_BAR; PG8_MMA(0, 0, At, B0); PG8_MMA(0, 1, At, B1); PG8_BAR; PG8_SCHED;
;             PG8_LDA(At, 0, 1); PG8_STAGE(PG8_SB(0, 0), b2, voffB); PG8_STAGE(PG8_SB(0, 1), b2 + hstep, voffB); PG8_STAGE(PG8_SA(0, 0), a2, voffA);
.LBB0_218:
	s_add_u32 s80, s78, 0xfffc0080
	s_addc_u32 s81, s79, -1
	s_add_i32 vcc_lo, 0, 0x10000
	s_cmp_eq_u32 s87, 12
	s_cselect_b32 s83, s45, s81
	s_cselect_b32 s82, s73, s80
	s_cselect_b32 s81, s77, s86
	s_cselect_b32 s80, s84, s85
	s_add_i32 s63, 0, 0x14000
	v_add_u32_e32 v142, vcc_lo, v201
	v_add_u32_e32 v158, s63, v201
	ds_read_b128 v[130:133], v142
	ds_read_b128 v[134:137], v142 offset:1024
	ds_read_b128 v[138:141], v142 offset:2048
	ds_read_b128 v[142:145], v142 offset:3072
	ds_read_b128 v[146:149], v158
	ds_read_b128 v[150:153], v158 offset:1024
	ds_read_b128 v[154:157], v158 offset:2048
	ds_read_b128 v[158:161], v158 offset:3072
	s_nop 0
	s_add_i32 m0, s56, 0xc000
	ds_read_b128 v[174:177], v202
	ds_read_b128 v[182:185], v202 offset:1024
	ds_read_b128 v[190:193], v202 offset:2048
	ds_read_b128 v[194:197], v202 offset:3072
	ds_read_b128 v[212:215], v202 offset:4096
	ds_read_b128 v[216:219], v202 offset:5120
	ds_read_b128 v[220:223], v202 offset:6144
	ds_read_b128 v[224:227], v202 offset:7168
	global_load_lds_dwordx4 v172, s[78:79]
	s_nop 0
	s_add_i32 m0, s56, 0xe000
	s_nop 0
	global_load_lds_dwordx4 v170, s[78:79]
	s_waitcnt vmcnt(8)
	s_waitcnt lgkmcnt(0)
	s_barrier
	s_nop 0
	s_waitcnt lgkmcnt(0)
	v_mfma_f32_16x16x32_bf16 v[126:129], v[130:133], v[174:177], v[126:129]
	v_mfma_f32_16x16x32_bf16 v[122:125], v[138:141], v[174:177], v[122:125]
	v_mfma_f32_16x16x32_bf16 v[110:113], v[130:133], v[190:193], v[110:113]
	v_mfma_f32_16x16x32_bf16 v[106:109], v[138:141], v[190:193], v[106:109]
	v_mfma_f32_16x16x32_bf16 v[94:97], v[130:133], v[212:215], v[94:97]
	v_mfma_f32_16x16x32_bf16 v[90:93], v[138:141], v[212:215], v[90:93]
	v_mfma_f32_16x16x32_bf16 v[78:81], v[130:133], v[220:223], v[78:81]
	v_mfma_f32_16x16x32_bf16 v[74:77], v[138:141], v[220:223], v[74:77]
	v_mfma_f32_16x16x32_bf16 v[126:129], v[134:137], v[182:185], v[126:129]
	v_mfma_f32_16x16x32_bf16 v[122:125], v[142:145], v[182:185], v[122:125]
	v_mfma_f32_16x16x32_bf16 v[110:113], v[134:137], v[194:197], v[110:113]
	v_mfma_f32_16x16x32_bf16 v[106:109], v[142:145], v[194:197], v[106:109]
	v_mfma_f32_16x16x32_bf16 v[94:97], v[134:137], v[216:219], v[94:97]
	v_mfma_f32_16x16x32_bf16 v[90:93], v[142:145], v[216:219], v[90:93]
	v_mfma_f32_16x16x32_bf16 v[78:81], v[134:137], v[224:227], v[78:81]
	v_mfma_f32_16x16x32_bf16 v[74:77], v[142:145], v[224:227], v[74:77]
	s_nop 0
	s_nop 0
	v_mfma_f32_16x16x32_bf16 v[118:121], v[146:149], v[174:177], v[118:121]
	v_mfma_f32_16x16x32_bf16 v[114:117], v[154:157], v[174:177], v[114:117]
	v_mfma_f32_16x16x32_bf16 v[102:105], v[146:149], v[190:193], v[102:105]
	v_mfma_f32_16x16x32_bf16 v[98:101], v[154:157], v[190:193], v[98:101]
	v_mfma_f32_16x16x32_bf16 v[86:89], v[146:149], v[212:215], v[86:89]
	v_mfma_f32_16x16x32_bf16 v[82:85], v[154:157], v[212:215], v[82:85]
	v_mfma_f32_16x16x32_bf16 v[70:73], v[146:149], v[220:223], v[70:73]
	v_mfma_f32_16x16x32_bf16 v[66:69], v[154:157], v[220:223], v[66:69]
	v_mfma_f32_16x16x32_bf16 v[118:121], v[150:153], v[182:185], v[118:121]
	v_mfma_f32_16x16x32_bf16 v[114:117], v[158:161], v[182:185], v[114:117]
	v_mfma_f32_16x16x32_bf16 v[102:105], v[150:153], v[194:197], v[102:105]
	v_mfma_f32_16x16x32_bf16 v[98:101], v[158:161], v[194:197], v[98:101]
	v_mfma_f32_16x16x32_bf16 v[86:89], v[150:153], v[216:219], v[86:89]
	v_mfma_f32_16x16x32_bf16 v[82:85], v[158:161], v[216:219], v[82:85]
	v_mfma_f32_16x16x32_bf16 v[70:73], v[150:153], v[224:227], v[70:73]
	v_mfma_f32_16x16x32_bf16 v[66:69], v[158:161], v[224:227], v[66:69]
	s_nop 0
	s_barrier
	s_add_i32 vcc_lo, vcc_lo, s55
	v_lshl_add_u64 v[198:199], s[80:81], 0, v[164:165]
	s_mov_b32 m0, vcc_lo
	ds_read_b128 v[174:177], v202 offset:16384
	ds_read_b128 v[182:185], v202 offset:17408
	ds_read_b128 v[190:193], v202 offset:18432
	ds_read_b128 v[194:197], v202 offset:19456
	ds_read_b128 v[212:215], v202 offset:20480
	ds_read_b128 v[216:219], v202 offset:21504
	ds_read_b128 v[220:223], v202 offset:22528
	ds_read_b128 v[224:227], v202 offset:23552
	global_load_lds_dwordx4 v[198:199], off
	s_add_i32 m0, vcc_lo, 0x2000
	s_add_u32 vcc_lo, s80, 0x40000
	v_lshl_add_u64 v[204:205], s[80:81], 0, v[168:169]
	s_addc_u32 vcc_hi, s81, 0
	s_add_i32 s63, s63, s55
	global_load_lds_dwordx4 v[204:205], off
	s_nop 0
	s_mov_b32 m0, s63
	s_nop 0
	global_load_lds_dwordx4 v164, vcc
	s_nop 0
	s_add_i32 m0, s63, 0x2000
	s_nop 0
	global_load_lds_dwordx4 v168, vcc
	s_nop 0
	s_add_u32 s98, s82, s90
	s_addc_u32 s99, s83, s91
	s_mov_b32 m0, s56
	s_nop 0
	global_load_lds_dwordx4 v162, s[82:83]
	s_mov_b32 m0, s57
	s_nop 0
	global_load_lds_dwordx4 v166, s[82:83]
	s_waitcnt vmcnt(8)
	s_waitcnt lgkmcnt(0)
	s_barrier
; #define PG8_STAGE(bufoff, gbase, voff) do { _Pragma("unroll") for (int _i = 0; _i < 2; ++_i) \
;         __builtin_amdgcn_global_load_lds((const unsigned*)((const char*)(gbase) + (voff)[_i]), (LAS unsigned*)(lds + (bufoff) + ldsw + _i * 8192), 16, 0, 0); } while (0)
; #define PG8_LDA(dst, b, h) do { _Pragma("unroll") for (int m = 0; m < 4; ++m) _Pragma("unroll") for (int k = 0; k < 2; ++k) dst[m][k] = *(const LAS bf16x8*)(lds + PG8_SA(b, h) + aoff + m * 2048 + k * 1024); } while (0)
; #define PG8_LDB(dst, b, h) do { _Pragma("unroll") for (int n = 0; n < 2; ++n) _Pragma("unroll") for (int k = 0; k < 2; ++k) dst[n][k] = *(const LAS bf16x8*)(lds + PG8_SB(b, h) + boff + n * 2048 + k * 1024); } while (0)
; #define PG8_MMA(ai, bj, At, Bt) do { __builtin_amdgcn_s_setprio(1); _Pragma("unroll") for (int m = 0; m < 4; ++m) _Pragma("unroll") for (int n = 0; n < 2; ++n) _Pragma("unroll") for (int k = 0; k < 2; ++k) \
;         acc[ai][bj][m][n] = __builtin_amdgcn_mfma_f32_16x16x32_bf16(Bt[n][k], At[m][k], acc[ai][bj][m][n], 0, 0, 0); __builtin_amdgcn_s_setprio(0); } while (0)
; #define PG8_WAIT_V(n) asm volatile("s_waitcnt vmcnt(" #n ")" ::: "memory")
; #define PG8_WAIT_L(n) asm volatile("s_waitcnt lgkmcnt(" #n ")" ::: "memory")
; #define PG8_BAR __builtin_amdgcn_s_barrier()
; #define PG8_SCHED __builtin_amdgcn_sched_barrier(0)
; template <class Epi, class Sched>
; DI void gemm_phase(LAS unsigned char* lds, const int K, const Sched& S, const Epi& E) {
;     ...
;             PG8_WAIT_V(8); PG8_WAIT_L(0); PG8_BAR; PG8_MMA(1, 0, At, B0); PG8_MMA(1, 1, At, B1); PG8_BAR; PG8_SCHED;
;             PG8_LDB(B0, 1, 0); PG8_LDB(B1, 1, 1); PG8_SCHED; PG8_LDA(At, 1, 0); PG8_STAGE(PG8_SA(0, 1), a2 + hstep, voffA);
;             PG8_WAIT_V(8); PG8_WAIT_L(0); PG8_BAR; PG8_MMA(0, 0, At, B0); PG8_MMA(0, 1, At, B1); PG8_BAR; PG8_SCHED;
	s_nop 0
	s_waitcnt lgkmcnt(0)
	v_mfma_f32_16x16x32_bf16 v[62:65], v[130:133], v[174:177], v[62:65]
	v_mfma_f32_16x16x32_bf16 v[58:61], v[138:141], v[174:177], v[58:61]
	v_mfma_f32_16x16x32_bf16 v[46:49], v[130:133], v[190:193], v[46:49]
	v_mfma_f32_16x16x32_bf16 v[42:45], v[138:141], v[190:193], v[42:45]
	v_mfma_f32_16x16x32_bf16 v[30:33], v[130:133], v[212:215], v[30:33]
	v_mfma_f32_16x16x32_bf16 v[26:29], v[138:141], v[212:215], v[26:29]
	v_mfma_f32_16x16x32_bf16 v[14:17], v[130:133], v[220:223], v[14:17]
	v_mfma_f32_16x16x32_bf16 v[10:13], v[138:141], v[220:223], v[10:13]
	v_mfma_f32_16x16x32_bf16 v[62:65], v[134:137], v[182:185], v[62:65]
	v_mfma_f32_16x16x32_bf16 v[58:61], v[142:145], v[182:185], v[58:61]
	v_mfma_f32_16x16x32_bf16 v[46:49], v[134:137], v[194:197], v[46:49]
	v_mfma_f32_16x16x32_bf16 v[42:45], v[142:145], v[194:197], v[42:45]
	v_mfma_f32_16x16x32_bf16 v[30:33], v[134:137], v[216:219], v[30:33]
	v_mfma_f32_16x16x32_bf16 v[26:29], v[142:145], v[216:219], v[26:29]
	v_mfma_f32_16x16x32_bf16 v[14:17], v[134:137], v[224:227], v[14:17]
	v_mfma_f32_16x16x32_bf16 v[10:13], v[142:145], v[224:227], v[10:13]
	s_nop 0
	s_nop 0
	v_mfma_f32_16x16x32_bf16 v[54:57], v[146:149], v[174:177], v[54:57]
	v_mfma_f32_16x16x32_bf16 v[50:53], v[154:157], v[174:177], v[50:53]
	v_mfma_f32_16x16x32_bf16 v[38:41], v[146:149], v[190:193], v[38:41]
	v_mfma_f32_16x16x32_bf16 v[34:37], v[154:157], v[190:193], v[34:37]
	v_mfma_f32_16x16x32_bf16 v[22:25], v[146:149], v[212:215], v[22:25]
	v_mfma_f32_16x16x32_bf16 v[18:21], v[154:157], v[212:215], v[18:21]
	v_mfma_f32_16x16x32_bf16 v[6:9], v[146:149], v[220:223], v[6:9]
	v_mfma_f32_16x16x32_bf16 v[2:5], v[154:157], v[220:223], v[2:5]
	v_mfma_f32_16x16x32_bf16 v[54:57], v[150:153], v[182:185], v[54:57]
	v_mfma_f32_16x16x32_bf16 v[50:53], v[158:161], v[182:185], v[50:53]
	v_mfma_f32_16x16x32_bf16 v[38:41], v[150:153], v[194:197], v[38:41]
	v_mfma_f32_16x16x32_bf16 v[34:37], v[158:161], v[194:197], v[34:37]
	v_mfma_f32_16x16x32_bf16 v[22:25], v[150:153], v[216:219], v[22:25]
	v_mfma_f32_16x16x32_bf16 v[18:21], v[158:161], v[216:219], v[18:21]
	v_mfma_f32_16x16x32_bf16 v[6:9], v[150:153], v[224:227], v[6:9]
	v_mfma_f32_16x16x32_bf16 v[2:5], v[158:161], v[224:227], v[2:5]
	s_nop 0
	s_barrier
	s_add_i32 s63, 0, 0x18000
	s_add_i32 vcc_lo, 0, 0x1c000
	v_add_u32_e32 v142, s63, v201
	v_add_u32_e32 v158, vcc_lo, v201
	ds_read_b128 v[130:133], v142
	ds_read_b128 v[134:137], v142 offset:1024
	ds_read_b128 v[138:141], v142 offset:2048
	ds_read_b128 v[142:145], v142 offset:3072
	ds_read_b128 v[146:149], v158
	ds_read_b128 v[150:153], v158 offset:1024
	ds_read_b128 v[154:157], v158 offset:2048
	ds_read_b128 v[158:161], v158 offset:3072
	s_add_u32 s82, s82, 0x40000
	s_addc_u32 s83, s83, 0
	s_mov_b32 m0, s58
	s_nop 0
	ds_read_b128 v[174:177], v202 offset:32768
	ds_read_b128 v[182:185], v202 offset:33792
	ds_read_b128 v[190:193], v202 offset:34816
	ds_read_b128 v[194:197], v202 offset:35840
	ds_read_b128 v[212:215], v202 offset:36864
	ds_read_b128 v[216:219], v202 offset:37888
	ds_read_b128 v[220:223], v202 offset:38912
	ds_read_b128 v[224:227], v202 offset:39936
	global_load_lds_dwordx4 v162, s[82:83]
	s_nop 0
	s_mov_b32 m0, s59
	s_nop 0
	global_load_lds_dwordx4 v166, s[82:83]
	s_waitcnt vmcnt(8)
	s_waitcnt lgkmcnt(0)
	s_barrier
	s_nop 0
	s_waitcnt lgkmcnt(0)
	v_mfma_f32_16x16x32_bf16 v[126:129], v[130:133], v[174:177], v[126:129]
	v_mfma_f32_16x16x32_bf16 v[122:125], v[138:141], v[174:177], v[122:125]
	v_mfma_f32_16x16x32_bf16 v[110:113], v[130:133], v[190:193], v[110:113]
	v_mfma_f32_16x16x32_bf16 v[106:109], v[138:141], v[190:193], v[106:109]
	v_mfma_f32_16x16x32_bf16 v[94:97], v[130:133], v[212:215], v[94:97]
	v_mfma_f32_16x16x32_bf16 v[90:93], v[138:141], v[212:215], v[90:93]
	v_mfma_f32_16x16x32_bf16 v[78:81], v[130:133], v[220:223], v[78:81]
	v_mfma_f32_16x16x32_bf16 v[74:77], v[138:141], v[220:223], v[74:77]
	v_mfma_f32_16x16x32_bf16 v[126:129], v[134:137], v[182:185], v[126:129]
	v_mfma_f32_16x16x32_bf16 v[122:125], v[142:145], v[182:185], v[122:125]
	v_mfma_f32_16x16x32_bf16 v[110:113], v[134:137], v[194:197], v[110:113]
	v_mfma_f32_16x16x32_bf16 v[106:109], v[142:145], v[194:197], v[106:109]
	v_mfma_f32_16x16x32_bf16 v[94:97], v[134:137], v[216:219], v[94:97]
	v_mfma_f32_16x16x32_bf16 v[90:93], v[142:145], v[216:219], v[90:93]
	v_mfma_f32_16x16x32_bf16 v[78:81], v[134:137], v[224:227], v[78:81]
	v_mfma_f32_16x16x32_bf16 v[74:77], v[142:145], v[224:227], v[74:77]
	s_nop 0
	s_nop 0
	v_mfma_f32_16x16x32_bf16 v[118:121], v[146:149], v[174:177], v[118:121]
	v_mfma_f32_16x16x32_bf16 v[114:117], v[154:157], v[174:177], v[114:117]
	v_mfma_f32_16x16x32_bf16 v[102:105], v[146:149], v[190:193], v[102:105]
	v_mfma_f32_16x16x32_bf16 v[98:101], v[154:157], v[190:193], v[98:101]
	v_mfma_f32_16x16x32_bf16 v[86:89], v[146:149], v[212:215], v[86:89]
	v_mfma_f32_16x16x32_bf16 v[82:85], v[154:157], v[212:215], v[82:85]
	v_mfma_f32_16x16x32_bf16 v[70:73], v[146:149], v[220:223], v[70:73]
	v_mfma_f32_16x16x32_bf16 v[66:69], v[154:157], v[220:223], v[66:69]
	v_mfma_f32_16x16x32_bf16 v[118:121], v[150:153], v[182:185], v[118:121]
	v_mfma_f32_16x16x32_bf16 v[114:117], v[158:161], v[182:185], v[114:117]
	v_mfma_f32_16x16x32_bf16 v[102:105], v[150:153], v[194:197], v[102:105]
	v_mfma_f32_16x16x32_bf16 v[98:101], v[158:161], v[194:197], v[98:101]
	v_mfma_f32_16x16x32_bf16 v[86:89], v[150:153], v[216:219], v[86:89]
	v_mfma_f32_16x16x32_bf16 v[82:85], v[158:161], v[216:219], v[82:85]
	v_mfma_f32_16x16x32_bf16 v[70:73], v[150:153], v[224:227], v[70:73]
	v_mfma_f32_16x16x32_bf16 v[66:69], v[158:161], v[224:227], v[66:69]
	s_nop 0
	s_barrier
; #define PG8_STAGE(bufoff, gbase, voff) do { _Pragma("unroll") for (int _i = 0; _i < 2; ++_i) \
;         __builtin_amdgcn_global_load_lds((const unsigned*)((const char*)(gbase) + (voff)[_i]), (LAS unsigned*)(lds + (bufoff) + ldsw + _i * 8192), 16, 0, 0); } while (0)
; #define PG8_LDA(dst, b, h) do { _Pragma("unroll") for (int m = 0; m < 4; ++m) _Pragma("unroll") for (int k = 0; k < 2; ++k) dst[m][k] = *(const LAS bf16x8*)(lds + PG8_SA(b, h) + aoff + m * 2048 + k * 1024); } while (0)
; #define PG8_MMA(ai, bj, At, Bt) do { __builtin_amdgcn_s_setprio(1); _Pragma("unroll") for (int m = 0; m < 4; ++m) _Pragma("unroll") for (int n = 0; n < 2; ++n) _Pragma("unroll") for (int k = 0; k < 2; ++k) \
;         acc[ai][bj][m][n] = __builtin_amdgcn_mfma_f32_16x16x32_bf16(Bt[n][k], At[m][k], acc[ai][bj][m][n], 0, 0, 0); __builtin_amdgcn_s_setprio(0); } while (0)
; #define PG8_WAIT_V(n) asm volatile("s_waitcnt vmcnt(" #n ")" ::: "memory")
; #define PG8_WAIT_L(n) asm volatile("s_waitcnt lgkmcnt(" #n ")" ::: "memory")
; #define PG8_BAR __builtin_amdgcn_s_barrier()
; #define PG8_SCHED __builtin_amdgcn_sched_barrier(0)
; template <class Epi, class Sched>
; DI void gemm_phase(LAS unsigned char* lds, const int K, const Sched& S, const Epi& E) {
;     ...
;             PG8_LDA(At, 1, 1); PG8_STAGE(PG8_SB(1, 0), b3, voffB); PG8_STAGE(PG8_SB(1, 1), b3 + hstep, voffB); PG8_STAGE(PG8_SA(1, 0), a3, voffA);
;             PG8_WAIT_V(8); PG8_WAIT_L(0); PG8_BAR; PG8_MMA(1, 0, At, B0); PG8_MMA(1, 1, At, B1); PG8_BAR; PG8_SCHED;
;         }
	s_add_i32 s63, s63, s55
	v_lshl_add_u64 v[198:199], v[198:199], 0, s[90:91]
	s_mov_b32 m0, s63
	ds_read_b128 v[174:177], v202 offset:49152
	ds_read_b128 v[182:185], v202 offset:50176
	ds_read_b128 v[190:193], v202 offset:51200
	ds_read_b128 v[194:197], v202 offset:52224
	ds_read_b128 v[212:215], v202 offset:53248
	ds_read_b128 v[216:219], v202 offset:54272
	ds_read_b128 v[220:223], v202 offset:55296
	ds_read_b128 v[224:227], v202 offset:56320
	global_load_lds_dwordx4 v[198:199], off
	s_add_i32 m0, s63, 0x2000
	s_add_u32 s80, s80, 0x40080
	v_lshl_add_u64 v[198:199], v[204:205], 0, s[90:91]
	s_addc_u32 s81, s81, 0
	s_add_i32 s63, vcc_lo, s55
	global_load_lds_dwordx4 v[198:199], off
	s_nop 0
	s_mov_b32 m0, s63
	s_nop 0
	global_load_lds_dwordx4 v164, s[80:81]
	s_nop 0
	s_add_i32 m0, s63, 0x2000
	s_nop 0
	global_load_lds_dwordx4 v168, s[80:81]
	s_nop 0
	s_mov_b32 m0, s47
	s_nop 0
	global_load_lds_dwordx4 v162, s[98:99]
	s_nop 0
	s_mov_b32 m0, s62
	s_nop 0
	global_load_lds_dwordx4 v166, s[98:99]
	s_waitcnt vmcnt(8)
	s_waitcnt lgkmcnt(0)
	s_barrier
	s_nop 0
	s_waitcnt lgkmcnt(0)
	v_mfma_f32_16x16x32_bf16 v[62:65], v[130:133], v[174:177], v[62:65]
	v_mfma_f32_16x16x32_bf16 v[58:61], v[138:141], v[174:177], v[58:61]
	v_mfma_f32_16x16x32_bf16 v[46:49], v[130:133], v[190:193], v[46:49]
	v_mfma_f32_16x16x32_bf16 v[42:45], v[138:141], v[190:193], v[42:45]
	v_mfma_f32_16x16x32_bf16 v[30:33], v[130:133], v[212:215], v[30:33]
	v_mfma_f32_16x16x32_bf16 v[26:29], v[138:141], v[212:215], v[26:29]
	v_mfma_f32_16x16x32_bf16 v[14:17], v[130:133], v[220:223], v[14:17]
	v_mfma_f32_16x16x32_bf16 v[10:13], v[138:141], v[220:223], v[10:13]
	v_mfma_f32_16x16x32_bf16 v[62:65], v[134:137], v[182:185], v[62:65]
	v_mfma_f32_16x16x32_bf16 v[58:61], v[142:145], v[182:185], v[58:61]
	v_mfma_f32_16x16x32_bf16 v[46:49], v[134:137], v[194:197], v[46:49]
	v_mfma_f32_16x16x32_bf16 v[42:45], v[142:145], v[194:197], v[42:45]
	v_mfma_f32_16x16x32_bf16 v[30:33], v[134:137], v[216:219], v[30:33]
	v_mfma_f32_16x16x32_bf16 v[26:29], v[142:145], v[216:219], v[26:29]
	v_mfma_f32_16x16x32_bf16 v[14:17], v[134:137], v[224:227], v[14:17]
	v_mfma_f32_16x16x32_bf16 v[10:13], v[142:145], v[224:227], v[10:13]
	s_nop 0
	s_nop 0
	v_mfma_f32_16x16x32_bf16 v[54:57], v[146:149], v[174:177], v[54:57]
	v_mfma_f32_16x16x32_bf16 v[50:53], v[154:157], v[174:177], v[50:53]
	v_mfma_f32_16x16x32_bf16 v[38:41], v[146:149], v[190:193], v[38:41]
	v_mfma_f32_16x16x32_bf16 v[34:37], v[154:157], v[190:193], v[34:37]
	v_mfma_f32_16x16x32_bf16 v[22:25], v[146:149], v[212:215], v[22:25]
	v_mfma_f32_16x16x32_bf16 v[18:21], v[154:157], v[212:215], v[18:21]
	v_mfma_f32_16x16x32_bf16 v[6:9], v[146:149], v[220:223], v[6:9]
	v_mfma_f32_16x16x32_bf16 v[2:5], v[154:157], v[220:223], v[2:5]
	v_mfma_f32_16x16x32_bf16 v[54:57], v[150:153], v[182:185], v[54:57]
	v_mfma_f32_16x16x32_bf16 v[50:53], v[158:161], v[182:185], v[50:53]
	v_mfma_f32_16x16x32_bf16 v[38:41], v[150:153], v[194:197], v[38:41]
	v_mfma_f32_16x16x32_bf16 v[34:37], v[158:161], v[194:197], v[34:37]
	v_mfma_f32_16x16x32_bf16 v[22:25], v[150:153], v[216:219], v[22:25]
	v_mfma_f32_16x16x32_bf16 v[18:21], v[158:161], v[216:219], v[18:21]
	v_mfma_f32_16x16x32_bf16 v[6:9], v[150:153], v[224:227], v[6:9]
	v_mfma_f32_16x16x32_bf16 v[2:5], v[158:161], v[224:227], v[2:5]
	s_nop 0
	s_barrier
	s_add_i32 s87, s87, 2
	s_add_u32 s85, s85, 0x100
	s_addc_u32 s86, s86, 0
	s_add_u32 s78, s78, 0x100
	s_addc_u32 s79, s79, 0
	s_cmp_gt_u32 s87, 13
	s_cbranch_scc0 .LBB0_218
	s_and_b64 vcc, exec, s[50:51]
	s_cbranch_vccz .LBB0_221
	s_barrier

; #define PG8_STAGE(bufoff, gbase, voff) do { _Pragma("unroll") for (int _i = 0; _i < 2; ++_i) \
;         __builtin_amdgcn_global_load_lds((const unsigned*)((const char*)(gbase) + (voff)[_i]), (LAS unsigned*)(lds + (bufoff) + ldsw + _i * 8192), 16, 0, 0); } while (0)
; #define PG8_LDA(dst, b, h) do { _Pragma("unroll") for (int m = 0; m < 4; ++m) _Pragma("unroll") for (int k = 0; k < 2; ++k) dst[m][k] = *(const LAS bf16x8*)(lds + PG8_SA(b, h) + aoff + m * 2048 + k * 1024); } while (0)
; #define PG8_LDB(dst, b, h) do { _Pragma("unroll") for (int n = 0; n < 2; ++n) _Pragma("unroll") for (int k = 0; k < 2; ++k) dst[n][k] = *(const LAS bf16x8*)(lds + PG8_SB(b, h) + boff + n * 2048 + k * 1024); } while (0)
; #define PG8_MMA(ai, bj, At, Bt) do { __builtin_amdgcn_s_setprio(1); _Pragma("unroll") for (int m = 0; m < 4; ++m) _Pragma("unroll") for (int n = 0; n < 2; ++n) _Pragma("unroll") for (int k = 0; k < 2; ++k) \
;         acc[ai][bj][m][n] = __builtin_amdgcn_mfma_f32_16x16x32_bf16(Bt[n][k], At[m][k], acc[ai][bj][m][n], 0, 0, 0); __builtin_amdgcn_s_setprio(0); } while (0)
; #define PG8_WAIT_V(n) asm volatile("s_waitcnt vmcnt(" #n ")" ::: "memory")
; #define PG8_WAIT_L(n) asm volatile("s_waitcnt lgkmcnt(" #n ")" ::: "memory")
; #define PG8_BAR __builtin_amdgcn_s_barrier()
; #define PG8_SCHED __builtin_amdgcn_sched_barrier(0)
; template <class Epi, class Sched>
; DI void gemm_phase(LAS unsigned char* lds, const int K, const Sched& S, const Epi& E) {
;     ...
;         for (int t = 0; t < nt; t += 2) {
;             const bool last = (t == nt - 2);
;             const char* a1 = cA + (size_t)(t + 1) * kstep;
;             const char* a2 = last ? nA : cA + (size_t)(t + 2) * kstep; const char* b2 = last ? nB : cB + (size_t)(t + 2) * kstep;
;             const char* a3 = a2 + kstep; const char* b3 = b2 + kstep;
;             PG8_LDB(B0, 0, 0); PG8_LDB(B1, 0, 1); PG8_SCHED; PG8_LDA(At, 0, 0); PG8_STAGE(PG8_SA(1, 1), a1 + hstep, voffA);
;             PG8_WAIT_V(8); PG8_WAIT_L(0); PG8_BAR; PG8_MMA(0, 0, At, B0); PG8_MMA(0, 1, At, B1); PG8_BAR; PG8_SCHED;
;             PG8_LDA(At, 0, 1); PG8_STAGE(PG8_SB(0, 0), b2, voffB); PG8_STAGE(PG8_SB(0, 1), b2 + hstep, voffB); PG8_STAGE(PG8_SA(0, 0), a2, voffA);
;             PG8_WAIT_V(8); PG8_WAIT_L(0); PG8_BAR; PG8_MMA(1, 0, At, B0); PG8_MMA(1, 1, At, B1); PG8_BAR; PG8_SCHED;
.LBB0_338:
	s_add_u32 s58, s56, 0xfffc0080
	s_addc_u32 s59, s57, -1
	s_add_i32 s79, 0, 0x10000
	s_cmp_eq_u32 s78, 12
	s_cselect_b32 s61, s53, s59
	s_cselect_b32 s60, s52, s58
	v_add_u32_e32 v142, s79, v145
	s_cselect_b32 s59, s55, s51
	s_cselect_b32 s58, s54, s49
	s_add_i32 s82, 0, 0x14000
	ds_read_b128 v[148:151], v142
	ds_read_b128 v[152:155], v142 offset:1024
	ds_read_b128 v[156:159], v142 offset:2048
	ds_read_b128 v[160:163], v142 offset:3072
	v_add_u32_e32 v142, s82, v145
	ds_read_b128 v[164:167], v142
	ds_read_b128 v[168:171], v142 offset:1024
	ds_read_b128 v[172:175], v142 offset:2048
	ds_read_b128 v[182:185], v142 offset:3072
	s_nop 0
	s_add_i32 m0, s67, 0xc000
	ds_read_b128 v[190:193], v146
	ds_read_b128 v[194:197], v146 offset:1024
	ds_read_b128 v[198:201], v146 offset:2048
	ds_read_b128 v[202:205], v146 offset:3072
	ds_read_b128 v[212:215], v146 offset:4096
	ds_read_b128 v[216:219], v146 offset:5120
	ds_read_b128 v[220:223], v146 offset:6144
	ds_read_b128 v[224:227], v146 offset:7168
	global_load_lds_dwordx4 v140, s[56:57]
	s_nop 0
	s_add_i32 m0, s67, 0xe000
	s_nop 0
	global_load_lds_dwordx4 v138, s[56:57]
	s_waitcnt vmcnt(8)
	s_waitcnt lgkmcnt(0)
	s_barrier
	s_nop 0
	s_waitcnt lgkmcnt(0)
	v_mfma_f32_16x16x32_bf16 v[126:129], v[148:151], v[190:193], v[126:129]
	v_mfma_f32_16x16x32_bf16 v[122:125], v[156:159], v[190:193], v[122:125]
	v_mfma_f32_16x16x32_bf16 v[110:113], v[148:151], v[198:201], v[110:113]
	v_mfma_f32_16x16x32_bf16 v[106:109], v[156:159], v[198:201], v[106:109]
	v_mfma_f32_16x16x32_bf16 v[94:97], v[148:151], v[212:215], v[94:97]
	v_mfma_f32_16x16x32_bf16 v[90:93], v[156:159], v[212:215], v[90:93]
	v_mfma_f32_16x16x32_bf16 v[78:81], v[148:151], v[220:223], v[78:81]
	v_mfma_f32_16x16x32_bf16 v[74:77], v[156:159], v[220:223], v[74:77]
	v_mfma_f32_16x16x32_bf16 v[126:129], v[152:155], v[194:197], v[126:129]
	v_mfma_f32_16x16x32_bf16 v[122:125], v[160:163], v[194:197], v[122:125]
	v_mfma_f32_16x16x32_bf16 v[110:113], v[152:155], v[202:205], v[110:113]
	v_mfma_f32_16x16x32_bf16 v[106:109], v[160:163], v[202:205], v[106:109]
	v_mfma_f32_16x16x32_bf16 v[94:97], v[152:155], v[216:219], v[94:97]
	v_mfma_f32_16x16x32_bf16 v[90:93], v[160:163], v[216:219], v[90:93]
	v_mfma_f32_16x16x32_bf16 v[78:81], v[152:155], v[224:227], v[78:81]
	v_mfma_f32_16x16x32_bf16 v[74:77], v[160:163], v[224:227], v[74:77]
	s_nop 0
	s_nop 0
	v_mfma_f32_16x16x32_bf16 v[118:121], v[164:167], v[190:193], v[118:121]
	v_mfma_f32_16x16x32_bf16 v[114:117], v[172:175], v[190:193], v[114:117]
	v_mfma_f32_16x16x32_bf16 v[102:105], v[164:167], v[198:201], v[102:105]
	v_mfma_f32_16x16x32_bf16 v[98:101], v[172:175], v[198:201], v[98:101]
	v_mfma_f32_16x16x32_bf16 v[86:89], v[164:167], v[212:215], v[86:89]
	v_mfma_f32_16x16x32_bf16 v[82:85], v[172:175], v[212:215], v[82:85]
	v_mfma_f32_16x16x32_bf16 v[70:73], v[164:167], v[220:223], v[70:73]
	v_mfma_f32_16x16x32_bf16 v[66:69], v[172:175], v[220:223], v[66:69]
	v_mfma_f32_16x16x32_bf16 v[118:121], v[168:171], v[194:197], v[118:121]
	v_mfma_f32_16x16x32_bf16 v[114:117], v[182:185], v[194:197], v[114:117]
	v_mfma_f32_16x16x32_bf16 v[102:105], v[168:171], v[202:205], v[102:105]
	v_mfma_f32_16x16x32_bf16 v[98:101], v[182:185], v[202:205], v[98:101]
	v_mfma_f32_16x16x32_bf16 v[86:89], v[168:171], v[216:219], v[86:89]
	v_mfma_f32_16x16x32_bf16 v[82:85], v[182:185], v[216:219], v[82:85]
	v_mfma_f32_16x16x32_bf16 v[70:73], v[168:171], v[224:227], v[70:73]
	v_mfma_f32_16x16x32_bf16 v[66:69], v[182:185], v[224:227], v[66:69]
	s_nop 0
	s_barrier
	s_add_i32 s79, s79, s66
	v_lshl_add_u64 v[142:143], s[58:59], 0, v[134:135]
	s_mov_b32 m0, s79
	ds_read_b128 v[190:193], v146 offset:16384
	ds_read_b128 v[194:197], v146 offset:17408
	ds_read_b128 v[198:201], v146 offset:18432
	ds_read_b128 v[202:205], v146 offset:19456
	ds_read_b128 v[212:215], v146 offset:20480
	ds_read_b128 v[216:219], v146 offset:21504
	ds_read_b128 v[220:223], v146 offset:22528
	ds_read_b128 v[224:227], v146 offset:23552
	global_load_lds_dwordx4 v[142:143], off
	s_add_i32 m0, s79, 0x2000
	s_add_u32 s80, s58, 0x40000
	v_lshl_add_u64 v[176:177], s[58:59], 0, v[130:131]
	s_addc_u32 s81, s59, 0
	s_add_i32 s79, s82, s66
	global_load_lds_dwordx4 v[176:177], off
	s_nop 0
	s_mov_b32 m0, s79
	s_nop 0
	global_load_lds_dwordx4 v134, s[80:81]
	s_nop 0
	s_add_i32 m0, s79, 0x2000
	s_nop 0
	global_load_lds_dwordx4 v130, s[80:81]
	s_nop 0
	s_add_u32 s98, s60, s90
	s_addc_u32 s99, s61, s91
	s_mov_b32 m0, s67
	s_nop 0
	global_load_lds_dwordx4 v136, s[60:61]
	s_mov_b32 m0, s68
	s_nop 0
	global_load_lds_dwordx4 v132, s[60:61]
	s_waitcnt vmcnt(8)
	s_waitcnt lgkmcnt(0)
	s_barrier
; #define PG8_STAGE(bufoff, gbase, voff) do { _Pragma("unroll") for (int _i = 0; _i < 2; ++_i) \
;         __builtin_amdgcn_global_load_lds((const unsigned*)((const char*)(gbase) + (voff)[_i]), (LAS unsigned*)(lds + (bufoff) + ldsw + _i * 8192), 16, 0, 0); } while (0)
; #define PG8_LDA(dst, b, h) do { _Pragma("unroll") for (int m = 0; m < 4; ++m) _Pragma("unroll") for (int k = 0; k < 2; ++k) dst[m][k] = *(const LAS bf16x8*)(lds + PG8_SA(b, h) + aoff + m * 2048 + k * 1024); } while (0)
; #define PG8_LDB(dst, b, h) do { _Pragma("unroll") for (int n = 0; n < 2; ++n) _Pragma("unroll") for (int k = 0; k < 2; ++k) dst[n][k] = *(const LAS bf16x8*)(lds + PG8_SB(b, h) + boff + n * 2048 + k * 1024); } while (0)
; #define PG8_MMA(ai, bj, At, Bt) do { __builtin_amdgcn_s_setprio(1); _Pragma("unroll") for (int m = 0; m < 4; ++m) _Pragma("unroll") for (int n = 0; n < 2; ++n) _Pragma("unroll") for (int k = 0; k < 2; ++k) \
;         acc[ai][bj][m][n] = __builtin_amdgcn_mfma_f32_16x16x32_bf16(Bt[n][k], At[m][k], acc[ai][bj][m][n], 0, 0, 0); __builtin_amdgcn_s_setprio(0); } while (0)
; #define PG8_WAIT_V(n) asm volatile("s_waitcnt vmcnt(" #n ")" ::: "memory")
; #define PG8_WAIT_L(n) asm volatile("s_waitcnt lgkmcnt(" #n ")" ::: "memory")
; #define PG8_BAR __builtin_amdgcn_s_barrier()
; #define PG8_SCHED __builtin_amdgcn_sched_barrier(0)
; template <class Epi, class Sched>
; DI void gemm_phase(LAS unsigned char* lds, const int K, const Sched& S, const Epi& E) {
;     ...
;             PG8_WAIT_V(8); PG8_WAIT_L(0); PG8_BAR; PG8_MMA(1, 0, At, B0); PG8_MMA(1, 1, At, B1); PG8_BAR; PG8_SCHED;
;             PG8_LDB(B0, 1, 0); PG8_LDB(B1, 1, 1); PG8_SCHED; PG8_LDA(At, 1, 0); PG8_STAGE(PG8_SA(0, 1), a2 + hstep, voffA);
;             PG8_WAIT_V(8); PG8_WAIT_L(0); PG8_BAR; PG8_MMA(0, 0, At, B0); PG8_MMA(0, 1, At, B1); PG8_BAR; PG8_SCHED;
	s_nop 0
	s_waitcnt lgkmcnt(0)
	v_mfma_f32_16x16x32_bf16 v[62:65], v[148:151], v[190:193], v[62:65]
	v_mfma_f32_16x16x32_bf16 v[58:61], v[156:159], v[190:193], v[58:61]
	v_mfma_f32_16x16x32_bf16 v[46:49], v[148:151], v[198:201], v[46:49]
	v_mfma_f32_16x16x32_bf16 v[42:45], v[156:159], v[198:201], v[42:45]
	v_mfma_f32_16x16x32_bf16 v[30:33], v[148:151], v[212:215], v[30:33]
	v_mfma_f32_16x16x32_bf16 v[26:29], v[156:159], v[212:215], v[26:29]
	v_mfma_f32_16x16x32_bf16 v[14:17], v[148:151], v[220:223], v[14:17]
	v_mfma_f32_16x16x32_bf16 v[10:13], v[156:159], v[220:223], v[10:13]
	v_mfma_f32_16x16x32_bf16 v[62:65], v[152:155], v[194:197], v[62:65]
	v_mfma_f32_16x16x32_bf16 v[58:61], v[160:163], v[194:197], v[58:61]
	v_mfma_f32_16x16x32_bf16 v[46:49], v[152:155], v[202:205], v[46:49]
	v_mfma_f32_16x16x32_bf16 v[42:45], v[160:163], v[202:205], v[42:45]
	v_mfma_f32_16x16x32_bf16 v[30:33], v[152:155], v[216:219], v[30:33]
	v_mfma_f32_16x16x32_bf16 v[26:29], v[160:163], v[216:219], v[26:29]
	v_mfma_f32_16x16x32_bf16 v[14:17], v[152:155], v[224:227], v[14:17]
	v_mfma_f32_16x16x32_bf16 v[10:13], v[160:163], v[224:227], v[10:13]
	s_nop 0
	s_nop 0
	v_mfma_f32_16x16x32_bf16 v[54:57], v[164:167], v[190:193], v[54:57]
	v_mfma_f32_16x16x32_bf16 v[50:53], v[172:175], v[190:193], v[50:53]
	v_mfma_f32_16x16x32_bf16 v[38:41], v[164:167], v[198:201], v[38:41]
	v_mfma_f32_16x16x32_bf16 v[34:37], v[172:175], v[198:201], v[34:37]
	v_mfma_f32_16x16x32_bf16 v[22:25], v[164:167], v[212:215], v[22:25]
	v_mfma_f32_16x16x32_bf16 v[18:21], v[172:175], v[212:215], v[18:21]
	v_mfma_f32_16x16x32_bf16 v[6:9], v[164:167], v[220:223], v[6:9]
	v_mfma_f32_16x16x32_bf16 v[2:5], v[172:175], v[220:223], v[2:5]
	v_mfma_f32_16x16x32_bf16 v[54:57], v[168:171], v[194:197], v[54:57]
	v_mfma_f32_16x16x32_bf16 v[50:53], v[182:185], v[194:197], v[50:53]
	v_mfma_f32_16x16x32_bf16 v[38:41], v[168:171], v[202:205], v[38:41]
	v_mfma_f32_16x16x32_bf16 v[34:37], v[182:185], v[202:205], v[34:37]
	v_mfma_f32_16x16x32_bf16 v[22:25], v[168:171], v[216:219], v[22:25]
	v_mfma_f32_16x16x32_bf16 v[18:21], v[182:185], v[216:219], v[18:21]
	v_mfma_f32_16x16x32_bf16 v[6:9], v[168:171], v[224:227], v[6:9]
	v_mfma_f32_16x16x32_bf16 v[2:5], v[182:185], v[224:227], v[2:5]
	s_nop 0
	s_barrier
	s_add_i32 s79, 0, 0x18000
	v_add_u32_e32 v147, s79, v145
	s_add_i32 s80, 0, 0x1c000
	ds_read_b128 v[148:151], v147
	ds_read_b128 v[152:155], v147 offset:1024
	ds_read_b128 v[156:159], v147 offset:2048
	ds_read_b128 v[160:163], v147 offset:3072
	v_add_u32_e32 v147, s80, v145
	ds_read_b128 v[164:167], v147
	ds_read_b128 v[168:171], v147 offset:1024
	ds_read_b128 v[172:175], v147 offset:2048
	ds_read_b128 v[182:185], v147 offset:3072
	s_add_u32 s60, s60, 0x40000
	s_addc_u32 s61, s61, 0
	s_mov_b32 m0, s69
	s_nop 0
	ds_read_b128 v[190:193], v146 offset:32768
	ds_read_b128 v[194:197], v146 offset:33792
	ds_read_b128 v[198:201], v146 offset:34816
	ds_read_b128 v[202:205], v146 offset:35840
	ds_read_b128 v[212:215], v146 offset:36864
	ds_read_b128 v[216:219], v146 offset:37888
	ds_read_b128 v[220:223], v146 offset:38912
	ds_read_b128 v[224:227], v146 offset:39936
	global_load_lds_dwordx4 v136, s[60:61]
	s_nop 0
	s_mov_b32 m0, s70
	s_nop 0
	global_load_lds_dwordx4 v132, s[60:61]
	s_waitcnt vmcnt(8)
	s_waitcnt lgkmcnt(0)
	s_barrier
	s_nop 0
	s_waitcnt lgkmcnt(0)
	v_mfma_f32_16x16x32_bf16 v[126:129], v[148:151], v[190:193], v[126:129]
	v_mfma_f32_16x16x32_bf16 v[122:125], v[156:159], v[190:193], v[122:125]
	v_mfma_f32_16x16x32_bf16 v[110:113], v[148:151], v[198:201], v[110:113]
	v_mfma_f32_16x16x32_bf16 v[106:109], v[156:159], v[198:201], v[106:109]
	v_mfma_f32_16x16x32_bf16 v[94:97], v[148:151], v[212:215], v[94:97]
	v_mfma_f32_16x16x32_bf16 v[90:93], v[156:159], v[212:215], v[90:93]
	v_mfma_f32_16x16x32_bf16 v[78:81], v[148:151], v[220:223], v[78:81]
	v_mfma_f32_16x16x32_bf16 v[74:77], v[156:159], v[220:223], v[74:77]
	v_mfma_f32_16x16x32_bf16 v[126:129], v[152:155], v[194:197], v[126:129]
	v_mfma_f32_16x16x32_bf16 v[122:125], v[160:163], v[194:197], v[122:125]
	v_mfma_f32_16x16x32_bf16 v[110:113], v[152:155], v[202:205], v[110:113]
	v_mfma_f32_16x16x32_bf16 v[106:109], v[160:163], v[202:205], v[106:109]
	v_mfma_f32_16x16x32_bf16 v[94:97], v[152:155], v[216:219], v[94:97]
	v_mfma_f32_16x16x32_bf16 v[90:93], v[160:163], v[216:219], v[90:93]
	v_mfma_f32_16x16x32_bf16 v[78:81], v[152:155], v[224:227], v[78:81]
	v_mfma_f32_16x16x32_bf16 v[74:77], v[160:163], v[224:227], v[74:77]
	s_nop 0
	s_nop 0
	v_mfma_f32_16x16x32_bf16 v[118:121], v[164:167], v[190:193], v[118:121]
	v_mfma_f32_16x16x32_bf16 v[114:117], v[172:175], v[190:193], v[114:117]
	v_mfma_f32_16x16x32_bf16 v[102:105], v[164:167], v[198:201], v[102:105]
	v_mfma_f32_16x16x32_bf16 v[98:101], v[172:175], v[198:201], v[98:101]
	v_mfma_f32_16x16x32_bf16 v[86:89], v[164:167], v[212:215], v[86:89]
	v_mfma_f32_16x16x32_bf16 v[82:85], v[172:175], v[212:215], v[82:85]
	v_mfma_f32_16x16x32_bf16 v[70:73], v[164:167], v[220:223], v[70:73]
	v_mfma_f32_16x16x32_bf16 v[66:69], v[172:175], v[220:223], v[66:69]
	v_mfma_f32_16x16x32_bf16 v[118:121], v[168:171], v[194:197], v[118:121]
	v_mfma_f32_16x16x32_bf16 v[114:117], v[182:185], v[194:197], v[114:117]
	v_mfma_f32_16x16x32_bf16 v[102:105], v[168:171], v[202:205], v[102:105]
	v_mfma_f32_16x16x32_bf16 v[98:101], v[182:185], v[202:205], v[98:101]
	v_mfma_f32_16x16x32_bf16 v[86:89], v[168:171], v[216:219], v[86:89]
	v_mfma_f32_16x16x32_bf16 v[82:85], v[182:185], v[216:219], v[82:85]
	v_mfma_f32_16x16x32_bf16 v[70:73], v[168:171], v[224:227], v[70:73]
	v_mfma_f32_16x16x32_bf16 v[66:69], v[182:185], v[224:227], v[66:69]
	s_nop 0
	s_barrier
; #define PG8_STAGE(bufoff, gbase, voff) do { _Pragma("unroll") for (int _i = 0; _i < 2; ++_i) \
;         __builtin_amdgcn_global_load_lds((const unsigned*)((const char*)(gbase) + (voff)[_i]), (LAS unsigned*)(lds + (bufoff) + ldsw + _i * 8192), 16, 0, 0); } while (0)
; #define PG8_LDA(dst, b, h) do { _Pragma("unroll") for (int m = 0; m < 4; ++m) _Pragma("unroll") for (int k = 0; k < 2; ++k) dst[m][k] = *(const LAS bf16x8*)(lds + PG8_SA(b, h) + aoff + m * 2048 + k * 1024); } while (0)
; #define PG8_MMA(ai, bj, At, Bt) do { __builtin_amdgcn_s_setprio(1); _Pragma("unroll") for (int m = 0; m < 4; ++m) _Pragma("unroll") for (int n = 0; n < 2; ++n) _Pragma("unroll") for (int k = 0; k < 2; ++k) \
;         acc[ai][bj][m][n] = __builtin_amdgcn_mfma_f32_16x16x32_bf16(Bt[n][k], At[m][k], acc[ai][bj][m][n], 0, 0, 0); __builtin_amdgcn_s_setprio(0); } while (0)
; #define PG8_WAIT_V(n) asm volatile("s_waitcnt vmcnt(" #n ")" ::: "memory")
; #define PG8_WAIT_L(n) asm volatile("s_waitcnt lgkmcnt(" #n ")" ::: "memory")
; #define PG8_BAR __builtin_amdgcn_s_barrier()
; #define PG8_SCHED __builtin_amdgcn_sched_barrier(0)
; template <class Epi, class Sched>
; DI void gemm_phase(LAS unsigned char* lds, const int K, const Sched& S, const Epi& E) {
;     ...
;             PG8_LDA(At, 1, 1); PG8_STAGE(PG8_SB(1, 0), b3, voffB); PG8_STAGE(PG8_SB(1, 1), b3 + hstep, voffB); PG8_STAGE(PG8_SA(1, 0), a3, voffA);
;             PG8_WAIT_V(8); PG8_WAIT_L(0); PG8_BAR; PG8_MMA(1, 0, At, B0); PG8_MMA(1, 1, At, B1); PG8_BAR; PG8_SCHED;
;         }
;         if (wr == 0) PG8_BAR;
	s_add_i32 s60, s79, s66
	v_lshl_add_u64 v[142:143], v[142:143], 0, s[90:91]
	s_mov_b32 m0, s60
	ds_read_b128 v[190:193], v146 offset:49152
	ds_read_b128 v[194:197], v146 offset:50176
	ds_read_b128 v[198:201], v146 offset:51200
	ds_read_b128 v[202:205], v146 offset:52224
	ds_read_b128 v[212:215], v146 offset:53248
	ds_read_b128 v[216:219], v146 offset:54272
	ds_read_b128 v[220:223], v146 offset:55296
	ds_read_b128 v[224:227], v146 offset:56320
	global_load_lds_dwordx4 v[142:143], off
	s_add_i32 m0, s60, 0x2000
	s_add_u32 s58, s58, 0x40080
	v_lshl_add_u64 v[142:143], v[176:177], 0, s[90:91]
	s_addc_u32 s59, s59, 0
	s_add_i32 s60, s80, s66
	global_load_lds_dwordx4 v[142:143], off
	s_nop 0
	s_mov_b32 m0, s60
	s_nop 0
	global_load_lds_dwordx4 v134, s[58:59]
	s_nop 0
	s_add_i32 m0, s60, 0x2000
	s_nop 0
	global_load_lds_dwordx4 v130, s[58:59]
	s_nop 0
	s_mov_b32 m0, s73
	s_nop 0
	global_load_lds_dwordx4 v136, s[98:99]
	s_nop 0
	s_mov_b32 m0, s74
	s_nop 0
	global_load_lds_dwordx4 v132, s[98:99]
	s_waitcnt vmcnt(8)
	s_waitcnt lgkmcnt(0)
	s_barrier
	s_nop 0
	s_waitcnt lgkmcnt(0)
	v_mfma_f32_16x16x32_bf16 v[62:65], v[148:151], v[190:193], v[62:65]
	v_mfma_f32_16x16x32_bf16 v[58:61], v[156:159], v[190:193], v[58:61]
	v_mfma_f32_16x16x32_bf16 v[46:49], v[148:151], v[198:201], v[46:49]
	v_mfma_f32_16x16x32_bf16 v[42:45], v[156:159], v[198:201], v[42:45]
	v_mfma_f32_16x16x32_bf16 v[30:33], v[148:151], v[212:215], v[30:33]
	v_mfma_f32_16x16x32_bf16 v[26:29], v[156:159], v[212:215], v[26:29]
	v_mfma_f32_16x16x32_bf16 v[14:17], v[148:151], v[220:223], v[14:17]
	v_mfma_f32_16x16x32_bf16 v[10:13], v[156:159], v[220:223], v[10:13]
	v_mfma_f32_16x16x32_bf16 v[62:65], v[152:155], v[194:197], v[62:65]
	v_mfma_f32_16x16x32_bf16 v[58:61], v[160:163], v[194:197], v[58:61]
	v_mfma_f32_16x16x32_bf16 v[46:49], v[152:155], v[202:205], v[46:49]
	v_mfma_f32_16x16x32_bf16 v[42:45], v[160:163], v[202:205], v[42:45]
	v_mfma_f32_16x16x32_bf16 v[30:33], v[152:155], v[216:219], v[30:33]
	v_mfma_f32_16x16x32_bf16 v[26:29], v[160:163], v[216:219], v[26:29]
	v_mfma_f32_16x16x32_bf16 v[14:17], v[152:155], v[224:227], v[14:17]
	v_mfma_f32_16x16x32_bf16 v[10:13], v[160:163], v[224:227], v[10:13]
	s_nop 0
	s_nop 0
	v_mfma_f32_16x16x32_bf16 v[54:57], v[164:167], v[190:193], v[54:57]
	v_mfma_f32_16x16x32_bf16 v[50:53], v[172:175], v[190:193], v[50:53]
	v_mfma_f32_16x16x32_bf16 v[38:41], v[164:167], v[198:201], v[38:41]
	v_mfma_f32_16x16x32_bf16 v[34:37], v[172:175], v[198:201], v[34:37]
	v_mfma_f32_16x16x32_bf16 v[22:25], v[164:167], v[212:215], v[22:25]
	v_mfma_f32_16x16x32_bf16 v[18:21], v[172:175], v[212:215], v[18:21]
	v_mfma_f32_16x16x32_bf16 v[6:9], v[164:167], v[220:223], v[6:9]
	v_mfma_f32_16x16x32_bf16 v[2:5], v[172:175], v[220:223], v[2:5]
	v_mfma_f32_16x16x32_bf16 v[54:57], v[168:171], v[194:197], v[54:57]
	v_mfma_f32_16x16x32_bf16 v[50:53], v[182:185], v[194:197], v[50:53]
	v_mfma_f32_16x16x32_bf16 v[38:41], v[168:171], v[202:205], v[38:41]
	v_mfma_f32_16x16x32_bf16 v[34:37], v[182:185], v[202:205], v[34:37]
	v_mfma_f32_16x16x32_bf16 v[22:25], v[168:171], v[216:219], v[22:25]
	v_mfma_f32_16x16x32_bf16 v[18:21], v[182:185], v[216:219], v[18:21]
	v_mfma_f32_16x16x32_bf16 v[6:9], v[168:171], v[224:227], v[6:9]
	v_mfma_f32_16x16x32_bf16 v[2:5], v[182:185], v[224:227], v[2:5]
	s_nop 0
	s_barrier
	s_add_i32 s78, s78, 2
	s_add_u32 s49, s49, 0x100
	s_addc_u32 s51, s51, 0
	s_add_u32 s56, s56, 0x100
	s_addc_u32 s57, s57, 0
	s_cmp_gt_u32 s78, 13
	s_cbranch_scc0 .LBB0_338
	s_and_b64 vcc, exec, s[44:45]
	s_cbranch_vccz .LBB0_341
	s_barrier

; #define PG8_STAGE(bufoff, gbase, voff) do { _Pragma("unroll") for (int _i = 0; _i < 2; ++_i) \
;         __builtin_amdgcn_global_load_lds((const unsigned*)((const char*)(gbase) + (voff)[_i]), (LAS unsigned*)(lds + (bufoff) + ldsw + _i * 8192), 16, 0, 0); } while (0)
; #define PG8_LDA(dst, b, h) do { _Pragma("unroll") for (int m = 0; m < 4; ++m) _Pragma("unroll") for (int k = 0; k < 2; ++k) dst[m][k] = *(const LAS bf16x8*)(lds + PG8_SA(b, h) + aoff + m * 2048 + k * 1024); } while (0)
; #define PG8_LDB(dst, b, h) do { _Pragma("unroll") for (int n = 0; n < 2; ++n) _Pragma("unroll") for (int k = 0; k < 2; ++k) dst[n][k] = *(const LAS bf16x8*)(lds + PG8_SB(b, h) + boff + n * 2048 + k * 1024); } while (0)
; #define PG8_MMA(ai, bj, At, Bt) do { __builtin_amdgcn_s_setprio(1); _Pragma("unroll") for (int m = 0; m < 4; ++m) _Pragma("unroll") for (int n = 0; n < 2; ++n) _Pragma("unroll") for (int k = 0; k < 2; ++k) \
;         acc[ai][bj][m][n] = __builtin_amdgcn_mfma_f32_16x16x32_bf16(Bt[n][k], At[m][k], acc[ai][bj][m][n], 0, 0, 0); __builtin_amdgcn_s_setprio(0); } while (0)
; #define PG8_WAIT_V(n) asm volatile("s_waitcnt vmcnt(" #n ")" ::: "memory")
; #define PG8_WAIT_L(n) asm volatile("s_waitcnt lgkmcnt(" #n ")" ::: "memory")
; #define PG8_BAR __builtin_amdgcn_s_barrier()
; #define PG8_SCHED __builtin_amdgcn_sched_barrier(0)
; template <class Epi, class Sched>
; DI void gemm_phase(LAS unsigned char* lds, const int K, const Sched& S, const Epi& E) {
;     ...
;         for (int t = 0; t < nt; t += 2) {
;             const bool last = (t == nt - 2);
;             const char* a1 = cA + (size_t)(t + 1) * kstep;
;             const char* a2 = last ? nA : cA + (size_t)(t + 2) * kstep; const char* b2 = last ? nB : cB + (size_t)(t + 2) * kstep;
;             const char* a3 = a2 + kstep; const char* b3 = b2 + kstep;
;             PG8_LDB(B0, 0, 0); PG8_LDB(B1, 0, 1); PG8_SCHED; PG8_LDA(At, 0, 0); PG8_STAGE(PG8_SA(1, 1), a1 + hstep, voffA);
;             PG8_WAIT_V(8); PG8_WAIT_L(0); PG8_BAR; PG8_MMA(0, 0, At, B0); PG8_MMA(0, 1, At, B1); PG8_BAR; PG8_SCHED;
;             PG8_LDA(At, 0, 1); PG8_STAGE(PG8_SB(0, 0), b2, voffB); PG8_STAGE(PG8_SB(0, 1), b2 + hstep, voffB); PG8_STAGE(PG8_SA(0, 0), a2, voffA);
;             PG8_WAIT_V(8); PG8_WAIT_L(0); PG8_BAR; PG8_MMA(1, 0, At, B0); PG8_MMA(1, 1, At, B1); PG8_BAR; PG8_SCHED;
.LBB0_465:
	s_add_u32 s70, s68, 0xfffc0080
	s_addc_u32 s71, s69, -1
	s_add_i32 vcc_lo, 0, 0x10000
	s_cmp_eq_u32 s79, 12
	s_cselect_b32 s73, s65, s71
	s_cselect_b32 s72, s67, s70
	s_cselect_b32 s71, s74, s78
	s_cselect_b32 s70, s76, s77
	s_add_i32 s42, 0, 0x14000
	v_add_u32_e32 v142, vcc_lo, v203
	v_add_u32_e32 v158, s42, v203
	ds_read_b128 v[130:133], v142
	ds_read_b128 v[134:137], v142 offset:1024
	ds_read_b128 v[138:141], v142 offset:2048
	ds_read_b128 v[142:145], v142 offset:3072
	ds_read_b128 v[146:149], v158
	ds_read_b128 v[150:153], v158 offset:1024
	ds_read_b128 v[154:157], v158 offset:2048
	ds_read_b128 v[158:161], v158 offset:3072
	s_nop 0
	s_add_i32 m0, s86, 0xc000
	ds_read_b128 v[174:177], v204
	ds_read_b128 v[182:185], v204 offset:1024
	ds_read_b128 v[190:193], v204 offset:2048
	ds_read_b128 v[194:197], v204 offset:3072
	ds_read_b128 v[198:201], v204 offset:4096
	ds_read_b128 v[212:215], v204 offset:5120
	ds_read_b128 v[216:219], v204 offset:6144
	ds_read_b128 v[220:223], v204 offset:7168
	global_load_lds_dwordx4 v172, s[68:69]
	s_nop 0
	s_add_i32 m0, s86, 0xe000
	s_nop 0
	global_load_lds_dwordx4 v170, s[68:69]
	s_waitcnt vmcnt(8)
	s_waitcnt lgkmcnt(0)
	s_barrier
	s_nop 0
	s_waitcnt lgkmcnt(0)
	v_mfma_f32_16x16x32_bf16 v[126:129], v[130:133], v[174:177], v[126:129]
	v_mfma_f32_16x16x32_bf16 v[122:125], v[138:141], v[174:177], v[122:125]
	v_mfma_f32_16x16x32_bf16 v[110:113], v[130:133], v[190:193], v[110:113]
	v_mfma_f32_16x16x32_bf16 v[106:109], v[138:141], v[190:193], v[106:109]
	v_mfma_f32_16x16x32_bf16 v[94:97], v[130:133], v[198:201], v[94:97]
	v_mfma_f32_16x16x32_bf16 v[90:93], v[138:141], v[198:201], v[90:93]
	v_mfma_f32_16x16x32_bf16 v[78:81], v[130:133], v[216:219], v[78:81]
	v_mfma_f32_16x16x32_bf16 v[74:77], v[138:141], v[216:219], v[74:77]
	v_mfma_f32_16x16x32_bf16 v[126:129], v[134:137], v[182:185], v[126:129]
	v_mfma_f32_16x16x32_bf16 v[122:125], v[142:145], v[182:185], v[122:125]
	v_mfma_f32_16x16x32_bf16 v[110:113], v[134:137], v[194:197], v[110:113]
	v_mfma_f32_16x16x32_bf16 v[106:109], v[142:145], v[194:197], v[106:109]
	v_mfma_f32_16x16x32_bf16 v[94:97], v[134:137], v[212:215], v[94:97]
	v_mfma_f32_16x16x32_bf16 v[90:93], v[142:145], v[212:215], v[90:93]
	v_mfma_f32_16x16x32_bf16 v[78:81], v[134:137], v[220:223], v[78:81]
	v_mfma_f32_16x16x32_bf16 v[74:77], v[142:145], v[220:223], v[74:77]
	s_nop 0
	s_nop 0
	v_mfma_f32_16x16x32_bf16 v[118:121], v[146:149], v[174:177], v[118:121]
	v_mfma_f32_16x16x32_bf16 v[114:117], v[154:157], v[174:177], v[114:117]
	v_mfma_f32_16x16x32_bf16 v[102:105], v[146:149], v[190:193], v[102:105]
	v_mfma_f32_16x16x32_bf16 v[98:101], v[154:157], v[190:193], v[98:101]
	v_mfma_f32_16x16x32_bf16 v[86:89], v[146:149], v[198:201], v[86:89]
	v_mfma_f32_16x16x32_bf16 v[82:85], v[154:157], v[198:201], v[82:85]
	v_mfma_f32_16x16x32_bf16 v[70:73], v[146:149], v[216:219], v[70:73]
	v_mfma_f32_16x16x32_bf16 v[66:69], v[154:157], v[216:219], v[66:69]
	v_mfma_f32_16x16x32_bf16 v[118:121], v[150:153], v[182:185], v[118:121]
	v_mfma_f32_16x16x32_bf16 v[114:117], v[158:161], v[182:185], v[114:117]
	v_mfma_f32_16x16x32_bf16 v[102:105], v[150:153], v[194:197], v[102:105]
	v_mfma_f32_16x16x32_bf16 v[98:101], v[158:161], v[194:197], v[98:101]
	v_mfma_f32_16x16x32_bf16 v[86:89], v[150:153], v[212:215], v[86:89]
	v_mfma_f32_16x16x32_bf16 v[82:85], v[158:161], v[212:215], v[82:85]
	v_mfma_f32_16x16x32_bf16 v[70:73], v[150:153], v[220:223], v[70:73]
	v_mfma_f32_16x16x32_bf16 v[66:69], v[158:161], v[220:223], v[66:69]
	s_nop 0
	s_barrier
	s_add_i32 s43, vcc_lo, s85
	v_lshl_add_u64 v[224:225], s[70:71], 0, v[164:165]
	s_mov_b32 m0, s43
	ds_read_b128 v[174:177], v204 offset:16384
	ds_read_b128 v[182:185], v204 offset:17408
	ds_read_b128 v[190:193], v204 offset:18432
	ds_read_b128 v[194:197], v204 offset:19456
	ds_read_b128 v[198:201], v204 offset:20480
	ds_read_b128 v[212:215], v204 offset:21504
	ds_read_b128 v[216:219], v204 offset:22528
	ds_read_b128 v[220:223], v204 offset:23552
	global_load_lds_dwordx4 v[224:225], off
	s_add_i32 m0, s43, 0x2000
	s_add_u32 vcc_lo, s70, 0x40000
	v_lshl_add_u64 v[226:227], s[70:71], 0, v[168:169]
	s_addc_u32 vcc_hi, s71, 0
	s_add_i32 s42, s42, s85
	global_load_lds_dwordx4 v[226:227], off
	s_nop 0
	s_mov_b32 m0, s42
	s_nop 0
	global_load_lds_dwordx4 v164, vcc
	s_nop 0
	s_add_i32 m0, s42, 0x2000
	s_nop 0
	global_load_lds_dwordx4 v168, vcc
	s_nop 0
	s_add_u32 s98, s72, s90
	s_addc_u32 s99, s73, s91
	s_mov_b32 m0, s86
	s_nop 0
	global_load_lds_dwordx4 v162, s[72:73]
	s_mov_b32 m0, s87
	s_nop 0
	global_load_lds_dwordx4 v166, s[72:73]
	s_waitcnt vmcnt(8)
	s_waitcnt lgkmcnt(0)
	s_barrier
; #define PG8_STAGE(bufoff, gbase, voff) do { _Pragma("unroll") for (int _i = 0; _i < 2; ++_i) \
;         __builtin_amdgcn_global_load_lds((const unsigned*)((const char*)(gbase) + (voff)[_i]), (LAS unsigned*)(lds + (bufoff) + ldsw + _i * 8192), 16, 0, 0); } while (0)
; #define PG8_LDA(dst, b, h) do { _Pragma("unroll") for (int m = 0; m < 4; ++m) _Pragma("unroll") for (int k = 0; k < 2; ++k) dst[m][k] = *(const LAS bf16x8*)(lds + PG8_SA(b, h) + aoff + m * 2048 + k * 1024); } while (0)
; #define PG8_LDB(dst, b, h) do { _Pragma("unroll") for (int n = 0; n < 2; ++n) _Pragma("unroll") for (int k = 0; k < 2; ++k) dst[n][k] = *(const LAS bf16x8*)(lds + PG8_SB(b, h) + boff + n * 2048 + k * 1024); } while (0)
; #define PG8_MMA(ai, bj, At, Bt) do { __builtin_amdgcn_s_setprio(1); _Pragma("unroll") for (int m = 0; m < 4; ++m) _Pragma("unroll") for (int n = 0; n < 2; ++n) _Pragma("unroll") for (int k = 0; k < 2; ++k) \
;         acc[ai][bj][m][n] = __builtin_amdgcn_mfma_f32_16x16x32_bf16(Bt[n][k], At[m][k], acc[ai][bj][m][n], 0, 0, 0); __builtin_amdgcn_s_setprio(0); } while (0)
; #define PG8_WAIT_V(n) asm volatile("s_waitcnt vmcnt(" #n ")" ::: "memory")
; #define PG8_WAIT_L(n) asm volatile("s_waitcnt lgkmcnt(" #n ")" ::: "memory")
; #define PG8_BAR __builtin_amdgcn_s_barrier()
; #define PG8_SCHED __builtin_amdgcn_sched_barrier(0)
; template <class Epi, class Sched>
; DI void gemm_phase(LAS unsigned char* lds, const int K, const Sched& S, const Epi& E) {
;     ...
;             PG8_WAIT_V(8); PG8_WAIT_L(0); PG8_BAR; PG8_MMA(1, 0, At, B0); PG8_MMA(1, 1, At, B1); PG8_BAR; PG8_SCHED;
;             PG8_LDB(B0, 1, 0); PG8_LDB(B1, 1, 1); PG8_SCHED; PG8_LDA(At, 1, 0); PG8_STAGE(PG8_SA(0, 1), a2 + hstep, voffA);
;             PG8_WAIT_V(8); PG8_WAIT_L(0); PG8_BAR; PG8_MMA(0, 0, At, B0); PG8_MMA(0, 1, At, B1); PG8_BAR; PG8_SCHED;
	s_nop 0
	s_waitcnt lgkmcnt(0)
	v_mfma_f32_16x16x32_bf16 v[62:65], v[130:133], v[174:177], v[62:65]
	v_mfma_f32_16x16x32_bf16 v[58:61], v[138:141], v[174:177], v[58:61]
	v_mfma_f32_16x16x32_bf16 v[46:49], v[130:133], v[190:193], v[46:49]
	v_mfma_f32_16x16x32_bf16 v[42:45], v[138:141], v[190:193], v[42:45]
	v_mfma_f32_16x16x32_bf16 v[30:33], v[130:133], v[198:201], v[30:33]
	v_mfma_f32_16x16x32_bf16 v[26:29], v[138:141], v[198:201], v[26:29]
	v_mfma_f32_16x16x32_bf16 v[14:17], v[130:133], v[216:219], v[14:17]
	v_mfma_f32_16x16x32_bf16 v[10:13], v[138:141], v[216:219], v[10:13]
	v_mfma_f32_16x16x32_bf16 v[62:65], v[134:137], v[182:185], v[62:65]
	v_mfma_f32_16x16x32_bf16 v[58:61], v[142:145], v[182:185], v[58:61]
	v_mfma_f32_16x16x32_bf16 v[46:49], v[134:137], v[194:197], v[46:49]
	v_mfma_f32_16x16x32_bf16 v[42:45], v[142:145], v[194:197], v[42:45]
	v_mfma_f32_16x16x32_bf16 v[30:33], v[134:137], v[212:215], v[30:33]
	v_mfma_f32_16x16x32_bf16 v[26:29], v[142:145], v[212:215], v[26:29]
	v_mfma_f32_16x16x32_bf16 v[14:17], v[134:137], v[220:223], v[14:17]
	v_mfma_f32_16x16x32_bf16 v[10:13], v[142:145], v[220:223], v[10:13]
	s_nop 0
	s_nop 0
	v_mfma_f32_16x16x32_bf16 v[54:57], v[146:149], v[174:177], v[54:57]
	v_mfma_f32_16x16x32_bf16 v[50:53], v[154:157], v[174:177], v[50:53]
	v_mfma_f32_16x16x32_bf16 v[38:41], v[146:149], v[190:193], v[38:41]
	v_mfma_f32_16x16x32_bf16 v[34:37], v[154:157], v[190:193], v[34:37]
	v_mfma_f32_16x16x32_bf16 v[22:25], v[146:149], v[198:201], v[22:25]
	v_mfma_f32_16x16x32_bf16 v[18:21], v[154:157], v[198:201], v[18:21]
	v_mfma_f32_16x16x32_bf16 v[6:9], v[146:149], v[216:219], v[6:9]
	v_mfma_f32_16x16x32_bf16 v[2:5], v[154:157], v[216:219], v[2:5]
	v_mfma_f32_16x16x32_bf16 v[54:57], v[150:153], v[182:185], v[54:57]
	v_mfma_f32_16x16x32_bf16 v[50:53], v[158:161], v[182:185], v[50:53]
	v_mfma_f32_16x16x32_bf16 v[38:41], v[150:153], v[194:197], v[38:41]
	v_mfma_f32_16x16x32_bf16 v[34:37], v[158:161], v[194:197], v[34:37]
	v_mfma_f32_16x16x32_bf16 v[22:25], v[150:153], v[212:215], v[22:25]
	v_mfma_f32_16x16x32_bf16 v[18:21], v[158:161], v[212:215], v[18:21]
	v_mfma_f32_16x16x32_bf16 v[6:9], v[150:153], v[220:223], v[6:9]
	v_mfma_f32_16x16x32_bf16 v[2:5], v[158:161], v[220:223], v[2:5]
	s_nop 0
	s_barrier
	s_add_i32 s42, 0, 0x18000
	s_add_i32 s43, 0, 0x1c000
	v_add_u32_e32 v142, s42, v203
	v_add_u32_e32 v158, s43, v203
	ds_read_b128 v[130:133], v142
	ds_read_b128 v[134:137], v142 offset:1024
	ds_read_b128 v[138:141], v142 offset:2048
	ds_read_b128 v[142:145], v142 offset:3072
	ds_read_b128 v[146:149], v158
	ds_read_b128 v[150:153], v158 offset:1024
	ds_read_b128 v[154:157], v158 offset:2048
	ds_read_b128 v[158:161], v158 offset:3072
	s_add_u32 s72, s72, 0x40000
	s_addc_u32 s73, s73, 0
	s_mov_b32 m0, s92
	s_nop 0
	ds_read_b128 v[174:177], v204 offset:32768
	ds_read_b128 v[182:185], v204 offset:33792
	ds_read_b128 v[190:193], v204 offset:34816
	ds_read_b128 v[194:197], v204 offset:35840
	ds_read_b128 v[198:201], v204 offset:36864
	ds_read_b128 v[212:215], v204 offset:37888
	ds_read_b128 v[216:219], v204 offset:38912
	ds_read_b128 v[220:223], v204 offset:39936
	global_load_lds_dwordx4 v162, s[72:73]
	s_nop 0
	s_mov_b32 m0, s94
	s_nop 0
	global_load_lds_dwordx4 v166, s[72:73]
	s_waitcnt vmcnt(8)
	s_waitcnt lgkmcnt(0)
	s_barrier
	s_nop 0
	s_waitcnt lgkmcnt(0)
	v_mfma_f32_16x16x32_bf16 v[126:129], v[130:133], v[174:177], v[126:129]
	v_mfma_f32_16x16x32_bf16 v[122:125], v[138:141], v[174:177], v[122:125]
	v_mfma_f32_16x16x32_bf16 v[110:113], v[130:133], v[190:193], v[110:113]
	v_mfma_f32_16x16x32_bf16 v[106:109], v[138:141], v[190:193], v[106:109]
	v_mfma_f32_16x16x32_bf16 v[94:97], v[130:133], v[198:201], v[94:97]
	v_mfma_f32_16x16x32_bf16 v[90:93], v[138:141], v[198:201], v[90:93]
	v_mfma_f32_16x16x32_bf16 v[78:81], v[130:133], v[216:219], v[78:81]
	v_mfma_f32_16x16x32_bf16 v[74:77], v[138:141], v[216:219], v[74:77]
	v_mfma_f32_16x16x32_bf16 v[126:129], v[134:137], v[182:185], v[126:129]
	v_mfma_f32_16x16x32_bf16 v[122:125], v[142:145], v[182:185], v[122:125]
	v_mfma_f32_16x16x32_bf16 v[110:113], v[134:137], v[194:197], v[110:113]
	v_mfma_f32_16x16x32_bf16 v[106:109], v[142:145], v[194:197], v[106:109]
	v_mfma_f32_16x16x32_bf16 v[94:97], v[134:137], v[212:215], v[94:97]
	v_mfma_f32_16x16x32_bf16 v[90:93], v[142:145], v[212:215], v[90:93]
	v_mfma_f32_16x16x32_bf16 v[78:81], v[134:137], v[220:223], v[78:81]
	v_mfma_f32_16x16x32_bf16 v[74:77], v[142:145], v[220:223], v[74:77]
	s_nop 0
	s_nop 0
	v_mfma_f32_16x16x32_bf16 v[118:121], v[146:149], v[174:177], v[118:121]
	v_mfma_f32_16x16x32_bf16 v[114:117], v[154:157], v[174:177], v[114:117]
	v_mfma_f32_16x16x32_bf16 v[102:105], v[146:149], v[190:193], v[102:105]
	v_mfma_f32_16x16x32_bf16 v[98:101], v[154:157], v[190:193], v[98:101]
	v_mfma_f32_16x16x32_bf16 v[86:89], v[146:149], v[198:201], v[86:89]
	v_mfma_f32_16x16x32_bf16 v[82:85], v[154:157], v[198:201], v[82:85]
	v_mfma_f32_16x16x32_bf16 v[70:73], v[146:149], v[216:219], v[70:73]
	v_mfma_f32_16x16x32_bf16 v[66:69], v[154:157], v[216:219], v[66:69]
	v_mfma_f32_16x16x32_bf16 v[118:121], v[150:153], v[182:185], v[118:121]
	v_mfma_f32_16x16x32_bf16 v[114:117], v[158:161], v[182:185], v[114:117]
	v_mfma_f32_16x16x32_bf16 v[102:105], v[150:153], v[194:197], v[102:105]
	v_mfma_f32_16x16x32_bf16 v[98:101], v[158:161], v[194:197], v[98:101]
	v_mfma_f32_16x16x32_bf16 v[86:89], v[150:153], v[212:215], v[86:89]
	v_mfma_f32_16x16x32_bf16 v[82:85], v[158:161], v[212:215], v[82:85]
	v_mfma_f32_16x16x32_bf16 v[70:73], v[150:153], v[220:223], v[70:73]
	v_mfma_f32_16x16x32_bf16 v[66:69], v[158:161], v[220:223], v[66:69]
	s_nop 0
	s_barrier
; #define PG8_STAGE(bufoff, gbase, voff) do { _Pragma("unroll") for (int _i = 0; _i < 2; ++_i) \
;         __builtin_amdgcn_global_load_lds((const unsigned*)((const char*)(gbase) + (voff)[_i]), (LAS unsigned*)(lds + (bufoff) + ldsw + _i * 8192), 16, 0, 0); } while (0)
; #define PG8_LDA(dst, b, h) do { _Pragma("unroll") for (int m = 0; m < 4; ++m) _Pragma("unroll") for (int k = 0; k < 2; ++k) dst[m][k] = *(const LAS bf16x8*)(lds + PG8_SA(b, h) + aoff + m * 2048 + k * 1024); } while (0)
; #define PG8_MMA(ai, bj, At, Bt) do { __builtin_amdgcn_s_setprio(1); _Pragma("unroll") for (int m = 0; m < 4; ++m) _Pragma("unroll") for (int n = 0; n < 2; ++n) _Pragma("unroll") for (int k = 0; k < 2; ++k) \
;         acc[ai][bj][m][n] = __builtin_amdgcn_mfma_f32_16x16x32_bf16(Bt[n][k], At[m][k], acc[ai][bj][m][n], 0, 0, 0); __builtin_amdgcn_s_setprio(0); } while (0)
; #define PG8_WAIT_V(n) asm volatile("s_waitcnt vmcnt(" #n ")" ::: "memory")
; #define PG8_WAIT_L(n) asm volatile("s_waitcnt lgkmcnt(" #n ")" ::: "memory")
; #define PG8_BAR __builtin_amdgcn_s_barrier()
; #define PG8_SCHED __builtin_amdgcn_sched_barrier(0)
; template <class Epi, class Sched>
; DI void gemm_phase(LAS unsigned char* lds, const int K, const Sched& S, const Epi& E) {
;     ...
;             PG8_LDA(At, 1, 1); PG8_STAGE(PG8_SB(1, 0), b3, voffB); PG8_STAGE(PG8_SB(1, 1), b3 + hstep, voffB); PG8_STAGE(PG8_SA(1, 0), a3, voffA);
;             PG8_WAIT_V(8); PG8_WAIT_L(0); PG8_BAR; PG8_MMA(1, 0, At, B0); PG8_MMA(1, 1, At, B1); PG8_BAR; PG8_SCHED;
;         }
;         if (wr == 0) PG8_BAR;
	s_add_i32 s42, s42, s85
	v_lshl_add_u64 v[224:225], v[224:225], 0, s[90:91]
	s_mov_b32 m0, s42
	ds_read_b128 v[174:177], v204 offset:49152
	ds_read_b128 v[182:185], v204 offset:50176
	ds_read_b128 v[190:193], v204 offset:51200
	ds_read_b128 v[194:197], v204 offset:52224
	ds_read_b128 v[198:201], v204 offset:53248
	ds_read_b128 v[212:215], v204 offset:54272
	ds_read_b128 v[216:219], v204 offset:55296
	ds_read_b128 v[220:223], v204 offset:56320
	global_load_lds_dwordx4 v[224:225], off
	s_add_i32 m0, s42, 0x2000
	s_add_u32 s70, s70, 0x40080
	v_lshl_add_u64 v[224:225], v[226:227], 0, s[90:91]
	s_addc_u32 s71, s71, 0
	s_add_i32 s42, s43, s85
	global_load_lds_dwordx4 v[224:225], off
	s_nop 0
	s_mov_b32 m0, s42
	s_nop 0
	global_load_lds_dwordx4 v164, s[70:71]
	s_nop 0
	s_add_i32 m0, s42, 0x2000
	s_nop 0
	global_load_lds_dwordx4 v168, s[70:71]
	s_nop 0
	s_mov_b32 m0, s45
	s_nop 0
	global_load_lds_dwordx4 v162, s[98:99]
	s_nop 0
	s_mov_b32 m0, s50
	s_nop 0
	global_load_lds_dwordx4 v166, s[98:99]
	s_waitcnt vmcnt(8)
	s_waitcnt lgkmcnt(0)
	s_barrier
	s_nop 0
	s_waitcnt lgkmcnt(0)
	v_mfma_f32_16x16x32_bf16 v[62:65], v[130:133], v[174:177], v[62:65]
	v_mfma_f32_16x16x32_bf16 v[58:61], v[138:141], v[174:177], v[58:61]
	v_mfma_f32_16x16x32_bf16 v[46:49], v[130:133], v[190:193], v[46:49]
	v_mfma_f32_16x16x32_bf16 v[42:45], v[138:141], v[190:193], v[42:45]
	v_mfma_f32_16x16x32_bf16 v[30:33], v[130:133], v[198:201], v[30:33]
	v_mfma_f32_16x16x32_bf16 v[26:29], v[138:141], v[198:201], v[26:29]
	v_mfma_f32_16x16x32_bf16 v[14:17], v[130:133], v[216:219], v[14:17]
	v_mfma_f32_16x16x32_bf16 v[10:13], v[138:141], v[216:219], v[10:13]
	v_mfma_f32_16x16x32_bf16 v[62:65], v[134:137], v[182:185], v[62:65]
	v_mfma_f32_16x16x32_bf16 v[58:61], v[142:145], v[182:185], v[58:61]
	v_mfma_f32_16x16x32_bf16 v[46:49], v[134:137], v[194:197], v[46:49]
	v_mfma_f32_16x16x32_bf16 v[42:45], v[142:145], v[194:197], v[42:45]
	v_mfma_f32_16x16x32_bf16 v[30:33], v[134:137], v[212:215], v[30:33]
	v_mfma_f32_16x16x32_bf16 v[26:29], v[142:145], v[212:215], v[26:29]
	v_mfma_f32_16x16x32_bf16 v[14:17], v[134:137], v[220:223], v[14:17]
	v_mfma_f32_16x16x32_bf16 v[10:13], v[142:145], v[220:223], v[10:13]
	s_nop 0
	s_nop 0
	v_mfma_f32_16x16x32_bf16 v[54:57], v[146:149], v[174:177], v[54:57]
	v_mfma_f32_16x16x32_bf16 v[50:53], v[154:157], v[174:177], v[50:53]
	v_mfma_f32_16x16x32_bf16 v[38:41], v[146:149], v[190:193], v[38:41]
	v_mfma_f32_16x16x32_bf16 v[34:37], v[154:157], v[190:193], v[34:37]
	v_mfma_f32_16x16x32_bf16 v[22:25], v[146:149], v[198:201], v[22:25]
	v_mfma_f32_16x16x32_bf16 v[18:21], v[154:157], v[198:201], v[18:21]
	v_mfma_f32_16x16x32_bf16 v[6:9], v[146:149], v[216:219], v[6:9]
	v_mfma_f32_16x16x32_bf16 v[2:5], v[154:157], v[216:219], v[2:5]
	v_mfma_f32_16x16x32_bf16 v[54:57], v[150:153], v[182:185], v[54:57]
	v_mfma_f32_16x16x32_bf16 v[50:53], v[158:161], v[182:185], v[50:53]
	v_mfma_f32_16x16x32_bf16 v[38:41], v[150:153], v[194:197], v[38:41]
	v_mfma_f32_16x16x32_bf16 v[34:37], v[158:161], v[194:197], v[34:37]
	v_mfma_f32_16x16x32_bf16 v[22:25], v[150:153], v[212:215], v[22:25]
	v_mfma_f32_16x16x32_bf16 v[18:21], v[158:161], v[212:215], v[18:21]
	v_mfma_f32_16x16x32_bf16 v[6:9], v[150:153], v[220:223], v[6:9]
	v_mfma_f32_16x16x32_bf16 v[2:5], v[158:161], v[220:223], v[2:5]
	s_nop 0
	s_barrier
	s_add_i32 s79, s79, 2
	s_add_u32 s77, s77, 0x100
	s_addc_u32 s78, s78, 0
	s_add_u32 s68, s68, 0x100
	s_addc_u32 s69, s69, 0
	s_cmp_gt_u32 s79, 13
	s_cbranch_scc0 .LBB0_465
	s_and_b64 vcc, exec, s[48:49]
	s_cbranch_vccz .LBB0_468
	s_barrier

; #define PG8_STAGE(bufoff, gbase, voff) do { _Pragma("unroll") for (int _i = 0; _i < 2; ++_i) \
;         __builtin_amdgcn_global_load_lds((const unsigned*)((const char*)(gbase) + (voff)[_i]), (LAS unsigned*)(lds + (bufoff) + ldsw + _i * 8192), 16, 0, 0); } while (0)
; #define PG8_LDA(dst, b, h) do { _Pragma("unroll") for (int m = 0; m < 4; ++m) _Pragma("unroll") for (int k = 0; k < 2; ++k) dst[m][k] = *(const LAS bf16x8*)(lds + PG8_SA(b, h) + aoff + m * 2048 + k * 1024); } while (0)
; #define PG8_LDB(dst, b, h) do { _Pragma("unroll") for (int n = 0; n < 2; ++n) _Pragma("unroll") for (int k = 0; k < 2; ++k) dst[n][k] = *(const LAS bf16x8*)(lds + PG8_SB(b, h) + boff + n * 2048 + k * 1024); } while (0)
; #define PG8_MMA(ai, bj, At, Bt) do { __builtin_amdgcn_s_setprio(1); _Pragma("unroll") for (int m = 0; m < 4; ++m) _Pragma("unroll") for (int n = 0; n < 2; ++n) _Pragma("unroll") for (int k = 0; k < 2; ++k) \
;         acc[ai][bj][m][n] = __builtin_amdgcn_mfma_f32_16x16x32_bf16(Bt[n][k], At[m][k], acc[ai][bj][m][n], 0, 0, 0); __builtin_amdgcn_s_setprio(0); } while (0)
; #define PG8_WAIT_V(n) asm volatile("s_waitcnt vmcnt(" #n ")" ::: "memory")
; #define PG8_WAIT_L(n) asm volatile("s_waitcnt lgkmcnt(" #n ")" ::: "memory")
; #define PG8_BAR __builtin_amdgcn_s_barrier()
; #define PG8_SCHED __builtin_amdgcn_sched_barrier(0)
; template <class Epi, class Sched>
; DI void gemm_phase(LAS unsigned char* lds, const int K, const Sched& S, const Epi& E) {
;     ...
;         for (int t = 0; t < nt; t += 2) {
;             const bool last = (t == nt - 2);
;             const char* a1 = cA + (size_t)(t + 1) * kstep;
;             const char* a2 = last ? nA : cA + (size_t)(t + 2) * kstep; const char* b2 = last ? nB : cB + (size_t)(t + 2) * kstep;
;             const char* a3 = a2 + kstep; const char* b3 = b2 + kstep;
;             PG8_LDB(B0, 0, 0); PG8_LDB(B1, 0, 1); PG8_SCHED; PG8_LDA(At, 0, 0); PG8_STAGE(PG8_SA(1, 1), a1 + hstep, voffA);
;             PG8_WAIT_V(8); PG8_WAIT_L(0); PG8_BAR; PG8_MMA(0, 0, At, B0); PG8_MMA(0, 1, At, B1); PG8_BAR; PG8_SCHED;
;             PG8_LDA(At, 0, 1); PG8_STAGE(PG8_SB(0, 0), b2, voffB); PG8_STAGE(PG8_SB(0, 1), b2 + hstep, voffB); PG8_STAGE(PG8_SA(0, 0), a2, voffA);
;             PG8_WAIT_V(8); PG8_WAIT_L(0); PG8_BAR; PG8_MMA(1, 0, At, B0); PG8_MMA(1, 1, At, B1); PG8_BAR; PG8_SCHED;
.LBB0_648:
	s_add_u32 s66, s64, 0xfffc0080
	s_addc_u32 s67, s65, -1
	s_add_i32 s92, 0, 0x10000
	s_cmp_eq_u32 s63, 12
	s_cselect_b32 s69, s59, s67
	s_cselect_b32 s68, s58, s66
	v_add_u32_e32 v1, s92, v154
	s_cselect_b32 s67, s61, s57
	s_cselect_b32 s66, s60, s55
	s_add_i32 s95, 0, 0x14000
	ds_read_b128 v[142:145], v1
	s_waitcnt lgkmcnt(0)
	ds_read_b128 v[146:149], v1 offset:1024
	ds_read_b128 v[156:159], v1 offset:2048
	ds_read_b128 v[160:163], v1 offset:3072
	v_add_u32_e32 v1, s95, v154
	ds_read_b128 v[164:167], v1
	ds_read_b128 v[168:171], v1 offset:1024
	ds_read_b128 v[172:175], v1 offset:2048
	ds_read_b128 v[182:185], v1 offset:3072
	s_nop 0
	s_add_i32 m0, s76, 0xc000
	ds_read_b128 v[190:193], v155
	ds_read_b128 v[194:197], v155 offset:1024
	ds_read_b128 v[198:201], v155 offset:2048
	ds_read_b128 v[202:205], v155 offset:3072
	ds_read_b128 v[212:215], v155 offset:4096
	ds_read_b128 v[216:219], v155 offset:5120
	ds_read_b128 v[220:223], v155 offset:6144
	ds_read_b128 v[224:227], v155 offset:7168
	global_load_lds_dwordx4 v140, s[64:65]
	s_nop 0
	s_add_i32 m0, s76, 0xe000
	s_nop 0
	global_load_lds_dwordx4 v138, s[64:65]
	s_waitcnt vmcnt(8)
	s_waitcnt lgkmcnt(0)
	s_barrier
	s_nop 0
	s_waitcnt lgkmcnt(0)
	v_mfma_f32_16x16x32_bf16 v[126:129], v[142:145], v[190:193], v[126:129]
	v_mfma_f32_16x16x32_bf16 v[122:125], v[156:159], v[190:193], v[122:125]
	v_mfma_f32_16x16x32_bf16 v[110:113], v[142:145], v[198:201], v[110:113]
	v_mfma_f32_16x16x32_bf16 v[106:109], v[156:159], v[198:201], v[106:109]
	v_mfma_f32_16x16x32_bf16 v[94:97], v[142:145], v[212:215], v[94:97]
	v_mfma_f32_16x16x32_bf16 v[90:93], v[156:159], v[212:215], v[90:93]
	v_mfma_f32_16x16x32_bf16 v[78:81], v[142:145], v[220:223], v[78:81]
	v_mfma_f32_16x16x32_bf16 v[74:77], v[156:159], v[220:223], v[74:77]
	v_mfma_f32_16x16x32_bf16 v[126:129], v[146:149], v[194:197], v[126:129]
	v_mfma_f32_16x16x32_bf16 v[122:125], v[160:163], v[194:197], v[122:125]
	v_mfma_f32_16x16x32_bf16 v[110:113], v[146:149], v[202:205], v[110:113]
	v_mfma_f32_16x16x32_bf16 v[106:109], v[160:163], v[202:205], v[106:109]
	v_mfma_f32_16x16x32_bf16 v[94:97], v[146:149], v[216:219], v[94:97]
	v_mfma_f32_16x16x32_bf16 v[90:93], v[160:163], v[216:219], v[90:93]
	v_mfma_f32_16x16x32_bf16 v[78:81], v[146:149], v[224:227], v[78:81]
	v_mfma_f32_16x16x32_bf16 v[74:77], v[160:163], v[224:227], v[74:77]
	s_nop 0
	s_nop 0
	v_mfma_f32_16x16x32_bf16 v[118:121], v[164:167], v[190:193], v[118:121]
	v_mfma_f32_16x16x32_bf16 v[114:117], v[172:175], v[190:193], v[114:117]
	v_mfma_f32_16x16x32_bf16 v[102:105], v[164:167], v[198:201], v[102:105]
	v_mfma_f32_16x16x32_bf16 v[98:101], v[172:175], v[198:201], v[98:101]
	v_mfma_f32_16x16x32_bf16 v[86:89], v[164:167], v[212:215], v[86:89]
	v_mfma_f32_16x16x32_bf16 v[82:85], v[172:175], v[212:215], v[82:85]
	v_mfma_f32_16x16x32_bf16 v[70:73], v[164:167], v[220:223], v[70:73]
	v_mfma_f32_16x16x32_bf16 v[66:69], v[172:175], v[220:223], v[66:69]
	v_mfma_f32_16x16x32_bf16 v[118:121], v[168:171], v[194:197], v[118:121]
	v_mfma_f32_16x16x32_bf16 v[114:117], v[182:185], v[194:197], v[114:117]
	v_mfma_f32_16x16x32_bf16 v[102:105], v[168:171], v[202:205], v[102:105]
	v_mfma_f32_16x16x32_bf16 v[98:101], v[182:185], v[202:205], v[98:101]
	v_mfma_f32_16x16x32_bf16 v[86:89], v[168:171], v[216:219], v[86:89]
	v_mfma_f32_16x16x32_bf16 v[82:85], v[182:185], v[216:219], v[82:85]
	v_mfma_f32_16x16x32_bf16 v[70:73], v[168:171], v[224:227], v[70:73]
	v_mfma_f32_16x16x32_bf16 v[66:69], v[182:185], v[224:227], v[66:69]
	s_nop 0
	s_barrier
	s_add_i32 s92, s92, s75
	v_lshl_add_u64 v[150:151], s[66:67], 0, v[132:133]
	s_mov_b32 m0, s92
	ds_read_b128 v[190:193], v155 offset:16384
	ds_read_b128 v[194:197], v155 offset:17408
	ds_read_b128 v[198:201], v155 offset:18432
	ds_read_b128 v[202:205], v155 offset:19456
	ds_read_b128 v[212:215], v155 offset:20480
	ds_read_b128 v[216:219], v155 offset:21504
	ds_read_b128 v[220:223], v155 offset:22528
	ds_read_b128 v[224:227], v155 offset:23552
	global_load_lds_dwordx4 v[150:151], off
	s_add_i32 m0, s92, 0x2000
	s_add_u32 vcc_lo, s66, 0x40000
	v_lshl_add_u64 v[176:177], s[66:67], 0, v[136:137]
	s_addc_u32 vcc_hi, s67, 0
	s_add_i32 s92, s95, s75
	global_load_lds_dwordx4 v[176:177], off
	s_nop 0
	s_mov_b32 m0, s92
	s_nop 0
	global_load_lds_dwordx4 v132, vcc
	s_nop 0
	s_add_i32 m0, s92, 0x2000
	s_nop 0
	global_load_lds_dwordx4 v136, vcc
	s_nop 0
	s_add_u32 s98, s68, s90
	s_addc_u32 s99, s69, s91
	s_mov_b32 m0, s76
	s_nop 0
	global_load_lds_dwordx4 v130, s[68:69]
	s_mov_b32 m0, s77
	s_nop 0
	global_load_lds_dwordx4 v134, s[68:69]
	s_waitcnt vmcnt(8)
	s_waitcnt lgkmcnt(0)
	s_barrier
; #define PG8_STAGE(bufoff, gbase, voff) do { _Pragma("unroll") for (int _i = 0; _i < 2; ++_i) \
;         __builtin_amdgcn_global_load_lds((const unsigned*)((const char*)(gbase) + (voff)[_i]), (LAS unsigned*)(lds + (bufoff) + ldsw + _i * 8192), 16, 0, 0); } while (0)
; #define PG8_LDA(dst, b, h) do { _Pragma("unroll") for (int m = 0; m < 4; ++m) _Pragma("unroll") for (int k = 0; k < 2; ++k) dst[m][k] = *(const LAS bf16x8*)(lds + PG8_SA(b, h) + aoff + m * 2048 + k * 1024); } while (0)
; #define PG8_LDB(dst, b, h) do { _Pragma("unroll") for (int n = 0; n < 2; ++n) _Pragma("unroll") for (int k = 0; k < 2; ++k) dst[n][k] = *(const LAS bf16x8*)(lds + PG8_SB(b, h) + boff + n * 2048 + k * 1024); } while (0)
; #define PG8_MMA(ai, bj, At, Bt) do { __builtin_amdgcn_s_setprio(1); _Pragma("unroll") for (int m = 0; m < 4; ++m) _Pragma("unroll") for (int n = 0; n < 2; ++n) _Pragma("unroll") for (int k = 0; k < 2; ++k) \
;         acc[ai][bj][m][n] = __builtin_amdgcn_mfma_f32_16x16x32_bf16(Bt[n][k], At[m][k], acc[ai][bj][m][n], 0, 0, 0); __builtin_amdgcn_s_setprio(0); } while (0)
; #define PG8_WAIT_V(n) asm volatile("s_waitcnt vmcnt(" #n ")" ::: "memory")
; #define PG8_WAIT_L(n) asm volatile("s_waitcnt lgkmcnt(" #n ")" ::: "memory")
; #define PG8_BAR __builtin_amdgcn_s_barrier()
; #define PG8_SCHED __builtin_amdgcn_sched_barrier(0)
; template <class Epi, class Sched>
; DI void gemm_phase(LAS unsigned char* lds, const int K, const Sched& S, const Epi& E) {
;     ...
;             PG8_WAIT_V(8); PG8_WAIT_L(0); PG8_BAR; PG8_MMA(1, 0, At, B0); PG8_MMA(1, 1, At, B1); PG8_BAR; PG8_SCHED;
;             PG8_LDB(B0, 1, 0); PG8_LDB(B1, 1, 1); PG8_SCHED; PG8_LDA(At, 1, 0); PG8_STAGE(PG8_SA(0, 1), a2 + hstep, voffA);
;             PG8_WAIT_V(8); PG8_WAIT_L(0); PG8_BAR; PG8_MMA(0, 0, At, B0); PG8_MMA(0, 1, At, B1); PG8_BAR; PG8_SCHED;
	s_nop 0
	s_waitcnt lgkmcnt(0)
	v_mfma_f32_16x16x32_bf16 v[62:65], v[142:145], v[190:193], v[62:65]
	v_mfma_f32_16x16x32_bf16 v[58:61], v[156:159], v[190:193], v[58:61]
	v_mfma_f32_16x16x32_bf16 v[46:49], v[142:145], v[198:201], v[46:49]
	v_mfma_f32_16x16x32_bf16 v[42:45], v[156:159], v[198:201], v[42:45]
	v_mfma_f32_16x16x32_bf16 v[30:33], v[142:145], v[212:215], v[30:33]
	v_mfma_f32_16x16x32_bf16 v[26:29], v[156:159], v[212:215], v[26:29]
	v_mfma_f32_16x16x32_bf16 v[14:17], v[142:145], v[220:223], v[14:17]
	v_mfma_f32_16x16x32_bf16 v[10:13], v[156:159], v[220:223], v[10:13]
	v_mfma_f32_16x16x32_bf16 v[62:65], v[146:149], v[194:197], v[62:65]
	v_mfma_f32_16x16x32_bf16 v[58:61], v[160:163], v[194:197], v[58:61]
	v_mfma_f32_16x16x32_bf16 v[46:49], v[146:149], v[202:205], v[46:49]
	v_mfma_f32_16x16x32_bf16 v[42:45], v[160:163], v[202:205], v[42:45]
	v_mfma_f32_16x16x32_bf16 v[30:33], v[146:149], v[216:219], v[30:33]
	v_mfma_f32_16x16x32_bf16 v[26:29], v[160:163], v[216:219], v[26:29]
	v_mfma_f32_16x16x32_bf16 v[14:17], v[146:149], v[224:227], v[14:17]
	v_mfma_f32_16x16x32_bf16 v[10:13], v[160:163], v[224:227], v[10:13]
	s_nop 0
	s_nop 0
	v_mfma_f32_16x16x32_bf16 v[54:57], v[164:167], v[190:193], v[54:57]
	v_mfma_f32_16x16x32_bf16 v[50:53], v[172:175], v[190:193], v[50:53]
	v_mfma_f32_16x16x32_bf16 v[38:41], v[164:167], v[198:201], v[38:41]
	v_mfma_f32_16x16x32_bf16 v[34:37], v[172:175], v[198:201], v[34:37]
	v_mfma_f32_16x16x32_bf16 v[22:25], v[164:167], v[212:215], v[22:25]
	v_mfma_f32_16x16x32_bf16 v[18:21], v[172:175], v[212:215], v[18:21]
	v_mfma_f32_16x16x32_bf16 v[6:9], v[164:167], v[220:223], v[6:9]
	v_mfma_f32_16x16x32_bf16 v[2:5], v[172:175], v[220:223], v[2:5]
	v_mfma_f32_16x16x32_bf16 v[54:57], v[168:171], v[194:197], v[54:57]
	v_mfma_f32_16x16x32_bf16 v[50:53], v[182:185], v[194:197], v[50:53]
	v_mfma_f32_16x16x32_bf16 v[38:41], v[168:171], v[202:205], v[38:41]
	v_mfma_f32_16x16x32_bf16 v[34:37], v[182:185], v[202:205], v[34:37]
	v_mfma_f32_16x16x32_bf16 v[22:25], v[168:171], v[216:219], v[22:25]
	v_mfma_f32_16x16x32_bf16 v[18:21], v[182:185], v[216:219], v[18:21]
	v_mfma_f32_16x16x32_bf16 v[6:9], v[168:171], v[224:227], v[6:9]
	v_mfma_f32_16x16x32_bf16 v[2:5], v[182:185], v[224:227], v[2:5]
	s_nop 0
	s_barrier
	s_add_i32 s92, 0, 0x18000
	v_add_u32_e32 v1, s92, v154
	s_add_i32 s95, 0, 0x1c000
	ds_read_b128 v[142:145], v1
	ds_read_b128 v[146:149], v1 offset:1024
	ds_read_b128 v[156:159], v1 offset:2048
	ds_read_b128 v[160:163], v1 offset:3072
	v_add_u32_e32 v1, s95, v154
	ds_read_b128 v[164:167], v1
	ds_read_b128 v[168:171], v1 offset:1024
	ds_read_b128 v[172:175], v1 offset:2048
	ds_read_b128 v[182:185], v1 offset:3072
	s_add_u32 s68, s68, 0x40000
	s_addc_u32 s69, s69, 0
	s_mov_b32 m0, s78
	s_nop 0
	ds_read_b128 v[190:193], v155 offset:32768
	ds_read_b128 v[194:197], v155 offset:33792
	ds_read_b128 v[198:201], v155 offset:34816
	ds_read_b128 v[202:205], v155 offset:35840
	ds_read_b128 v[212:215], v155 offset:36864
	ds_read_b128 v[216:219], v155 offset:37888
	ds_read_b128 v[220:223], v155 offset:38912
	ds_read_b128 v[224:227], v155 offset:39936
	global_load_lds_dwordx4 v130, s[68:69]
	s_nop 0
	s_mov_b32 m0, s79
	s_nop 0
	global_load_lds_dwordx4 v134, s[68:69]
	s_waitcnt vmcnt(8)
	s_waitcnt lgkmcnt(0)
	s_barrier
	s_nop 0
	s_waitcnt lgkmcnt(0)
	v_mfma_f32_16x16x32_bf16 v[126:129], v[142:145], v[190:193], v[126:129]
	v_mfma_f32_16x16x32_bf16 v[122:125], v[156:159], v[190:193], v[122:125]
	v_mfma_f32_16x16x32_bf16 v[110:113], v[142:145], v[198:201], v[110:113]
	v_mfma_f32_16x16x32_bf16 v[106:109], v[156:159], v[198:201], v[106:109]
	v_mfma_f32_16x16x32_bf16 v[94:97], v[142:145], v[212:215], v[94:97]
	v_mfma_f32_16x16x32_bf16 v[90:93], v[156:159], v[212:215], v[90:93]
	v_mfma_f32_16x16x32_bf16 v[78:81], v[142:145], v[220:223], v[78:81]
	v_mfma_f32_16x16x32_bf16 v[74:77], v[156:159], v[220:223], v[74:77]
	v_mfma_f32_16x16x32_bf16 v[126:129], v[146:149], v[194:197], v[126:129]
	v_mfma_f32_16x16x32_bf16 v[122:125], v[160:163], v[194:197], v[122:125]
	v_mfma_f32_16x16x32_bf16 v[110:113], v[146:149], v[202:205], v[110:113]
	v_mfma_f32_16x16x32_bf16 v[106:109], v[160:163], v[202:205], v[106:109]
	v_mfma_f32_16x16x32_bf16 v[94:97], v[146:149], v[216:219], v[94:97]
	v_mfma_f32_16x16x32_bf16 v[90:93], v[160:163], v[216:219], v[90:93]
	v_mfma_f32_16x16x32_bf16 v[78:81], v[146:149], v[224:227], v[78:81]
	v_mfma_f32_16x16x32_bf16 v[74:77], v[160:163], v[224:227], v[74:77]
	s_nop 0
	s_nop 0
	v_mfma_f32_16x16x32_bf16 v[118:121], v[164:167], v[190:193], v[118:121]
	v_mfma_f32_16x16x32_bf16 v[114:117], v[172:175], v[190:193], v[114:117]
	v_mfma_f32_16x16x32_bf16 v[102:105], v[164:167], v[198:201], v[102:105]
	v_mfma_f32_16x16x32_bf16 v[98:101], v[172:175], v[198:201], v[98:101]
	v_mfma_f32_16x16x32_bf16 v[86:89], v[164:167], v[212:215], v[86:89]
	v_mfma_f32_16x16x32_bf16 v[82:85], v[172:175], v[212:215], v[82:85]
	v_mfma_f32_16x16x32_bf16 v[70:73], v[164:167], v[220:223], v[70:73]
	v_mfma_f32_16x16x32_bf16 v[66:69], v[172:175], v[220:223], v[66:69]
	v_mfma_f32_16x16x32_bf16 v[118:121], v[168:171], v[194:197], v[118:121]
	v_mfma_f32_16x16x32_bf16 v[114:117], v[182:185], v[194:197], v[114:117]
	v_mfma_f32_16x16x32_bf16 v[102:105], v[168:171], v[202:205], v[102:105]
	v_mfma_f32_16x16x32_bf16 v[98:101], v[182:185], v[202:205], v[98:101]
	v_mfma_f32_16x16x32_bf16 v[86:89], v[168:171], v[216:219], v[86:89]
	v_mfma_f32_16x16x32_bf16 v[82:85], v[182:185], v[216:219], v[82:85]
	v_mfma_f32_16x16x32_bf16 v[70:73], v[168:171], v[224:227], v[70:73]
	v_mfma_f32_16x16x32_bf16 v[66:69], v[182:185], v[224:227], v[66:69]
	s_nop 0
	s_barrier
; #define PG8_STAGE(bufoff, gbase, voff) do { _Pragma("unroll") for (int _i = 0; _i < 2; ++_i) \
;         __builtin_amdgcn_global_load_lds((const unsigned*)((const char*)(gbase) + (voff)[_i]), (LAS unsigned*)(lds + (bufoff) + ldsw + _i * 8192), 16, 0, 0); } while (0)
; #define PG8_LDA(dst, b, h) do { _Pragma("unroll") for (int m = 0; m < 4; ++m) _Pragma("unroll") for (int k = 0; k < 2; ++k) dst[m][k] = *(const LAS bf16x8*)(lds + PG8_SA(b, h) + aoff + m * 2048 + k * 1024); } while (0)
; #define PG8_MMA(ai, bj, At, Bt) do { __builtin_amdgcn_s_setprio(1); _Pragma("unroll") for (int m = 0; m < 4; ++m) _Pragma("unroll") for (int n = 0; n < 2; ++n) _Pragma("unroll") for (int k = 0; k < 2; ++k) \
;         acc[ai][bj][m][n] = __builtin_amdgcn_mfma_f32_16x16x32_bf16(Bt[n][k], At[m][k], acc[ai][bj][m][n], 0, 0, 0); __builtin_amdgcn_s_setprio(0); } while (0)
; #define PG8_WAIT_V(n) asm volatile("s_waitcnt vmcnt(" #n ")" ::: "memory")
; #define PG8_WAIT_L(n) asm volatile("s_waitcnt lgkmcnt(" #n ")" ::: "memory")
; #define PG8_BAR __builtin_amdgcn_s_barrier()
; #define PG8_SCHED __builtin_amdgcn_sched_barrier(0)
; template <class Epi, class Sched>
; DI void gemm_phase(LAS unsigned char* lds, const int K, const Sched& S, const Epi& E) {
;     ...
;             PG8_LDA(At, 1, 1); PG8_STAGE(PG8_SB(1, 0), b3, voffB); PG8_STAGE(PG8_SB(1, 1), b3 + hstep, voffB); PG8_STAGE(PG8_SA(1, 0), a3, voffA);
;             PG8_WAIT_V(8); PG8_WAIT_L(0); PG8_BAR; PG8_MMA(1, 0, At, B0); PG8_MMA(1, 1, At, B1); PG8_BAR; PG8_SCHED;
;         }
;         if (wr == 0) PG8_BAR;
	s_add_i32 s68, s92, s75
	v_lshl_add_u64 v[150:151], v[150:151], 0, s[90:91]
	s_mov_b32 m0, s68
	ds_read_b128 v[190:193], v155 offset:49152
	ds_read_b128 v[194:197], v155 offset:50176
	ds_read_b128 v[198:201], v155 offset:51200
	ds_read_b128 v[202:205], v155 offset:52224
	ds_read_b128 v[212:215], v155 offset:53248
	ds_read_b128 v[216:219], v155 offset:54272
	ds_read_b128 v[220:223], v155 offset:55296
	ds_read_b128 v[224:227], v155 offset:56320
	global_load_lds_dwordx4 v[150:151], off
	s_add_i32 m0, s68, 0x2000
	s_add_u32 s66, s66, 0x40080
	v_lshl_add_u64 v[150:151], v[176:177], 0, s[90:91]
	s_addc_u32 s67, s67, 0
	s_add_i32 s68, s95, s75
	global_load_lds_dwordx4 v[150:151], off
	s_nop 0
	s_mov_b32 m0, s68
	s_nop 0
	global_load_lds_dwordx4 v132, s[66:67]
	s_nop 0
	s_add_i32 m0, s68, 0x2000
	s_nop 0
	global_load_lds_dwordx4 v136, s[66:67]
	s_nop 0
	s_mov_b32 m0, s83
	s_nop 0
	global_load_lds_dwordx4 v130, s[98:99]
	s_nop 0
	s_mov_b32 m0, s84
	s_nop 0
	global_load_lds_dwordx4 v134, s[98:99]
	s_waitcnt vmcnt(8)
	s_waitcnt lgkmcnt(0)
	s_barrier
	s_nop 0
	s_waitcnt lgkmcnt(0)
	v_mfma_f32_16x16x32_bf16 v[62:65], v[142:145], v[190:193], v[62:65]
	v_mfma_f32_16x16x32_bf16 v[58:61], v[156:159], v[190:193], v[58:61]
	v_mfma_f32_16x16x32_bf16 v[46:49], v[142:145], v[198:201], v[46:49]
	v_mfma_f32_16x16x32_bf16 v[42:45], v[156:159], v[198:201], v[42:45]
	v_mfma_f32_16x16x32_bf16 v[30:33], v[142:145], v[212:215], v[30:33]
	v_mfma_f32_16x16x32_bf16 v[26:29], v[156:159], v[212:215], v[26:29]
	v_mfma_f32_16x16x32_bf16 v[14:17], v[142:145], v[220:223], v[14:17]
	v_mfma_f32_16x16x32_bf16 v[10:13], v[156:159], v[220:223], v[10:13]
	v_mfma_f32_16x16x32_bf16 v[62:65], v[146:149], v[194:197], v[62:65]
	v_mfma_f32_16x16x32_bf16 v[58:61], v[160:163], v[194:197], v[58:61]
	v_mfma_f32_16x16x32_bf16 v[46:49], v[146:149], v[202:205], v[46:49]
	v_mfma_f32_16x16x32_bf16 v[42:45], v[160:163], v[202:205], v[42:45]
	v_mfma_f32_16x16x32_bf16 v[30:33], v[146:149], v[216:219], v[30:33]
	v_mfma_f32_16x16x32_bf16 v[26:29], v[160:163], v[216:219], v[26:29]
	v_mfma_f32_16x16x32_bf16 v[14:17], v[146:149], v[224:227], v[14:17]
	v_mfma_f32_16x16x32_bf16 v[10:13], v[160:163], v[224:227], v[10:13]
	s_nop 0
	s_nop 0
	v_mfma_f32_16x16x32_bf16 v[54:57], v[164:167], v[190:193], v[54:57]
	v_mfma_f32_16x16x32_bf16 v[50:53], v[172:175], v[190:193], v[50:53]
	v_mfma_f32_16x16x32_bf16 v[38:41], v[164:167], v[198:201], v[38:41]
	v_mfma_f32_16x16x32_bf16 v[34:37], v[172:175], v[198:201], v[34:37]
	v_mfma_f32_16x16x32_bf16 v[22:25], v[164:167], v[212:215], v[22:25]
	v_mfma_f32_16x16x32_bf16 v[18:21], v[172:175], v[212:215], v[18:21]
	v_mfma_f32_16x16x32_bf16 v[6:9], v[164:167], v[220:223], v[6:9]
	v_mfma_f32_16x16x32_bf16 v[2:5], v[172:175], v[220:223], v[2:5]
	v_mfma_f32_16x16x32_bf16 v[54:57], v[168:171], v[194:197], v[54:57]
	v_mfma_f32_16x16x32_bf16 v[50:53], v[182:185], v[194:197], v[50:53]
	v_mfma_f32_16x16x32_bf16 v[38:41], v[168:171], v[202:205], v[38:41]
	v_mfma_f32_16x16x32_bf16 v[34:37], v[182:185], v[202:205], v[34:37]
	v_mfma_f32_16x16x32_bf16 v[22:25], v[168:171], v[216:219], v[22:25]
	v_mfma_f32_16x16x32_bf16 v[18:21], v[182:185], v[216:219], v[18:21]
	v_mfma_f32_16x16x32_bf16 v[6:9], v[168:171], v[224:227], v[6:9]
	v_mfma_f32_16x16x32_bf16 v[2:5], v[182:185], v[224:227], v[2:5]
	s_nop 0
	s_barrier
	s_add_i32 s63, s63, 2
	s_add_u32 s55, s55, 0x100
	s_addc_u32 s57, s57, 0
	s_add_u32 s64, s64, 0x100
	s_addc_u32 s65, s65, 0
	s_cmp_gt_u32 s63, 13
	s_cbranch_scc0 .LBB0_648
	s_and_b64 vcc, exec, s[46:47]
	s_cbranch_vccz .LBB0_651
	s_barrier

; #define PG8_STAGE(bufoff, gbase, voff) do { _Pragma("unroll") for (int _i = 0; _i < 2; ++_i) \
;         __builtin_amdgcn_global_load_lds((const unsigned*)((const char*)(gbase) + (voff)[_i]), (LAS unsigned*)(lds + (bufoff) + ldsw + _i * 8192), 16, 0, 0); } while (0)
; #define PG8_LDA(dst, b, h) do { _Pragma("unroll") for (int m = 0; m < 4; ++m) _Pragma("unroll") for (int k = 0; k < 2; ++k) dst[m][k] = *(const LAS bf16x8*)(lds + PG8_SA(b, h) + aoff + m * 2048 + k * 1024); } while (0)
; #define PG8_LDB(dst, b, h) do { _Pragma("unroll") for (int n = 0; n < 2; ++n) _Pragma("unroll") for (int k = 0; k < 2; ++k) dst[n][k] = *(const LAS bf16x8*)(lds + PG8_SB(b, h) + boff + n * 2048 + k * 1024); } while (0)
; #define PG8_MMA(ai, bj, At, Bt) do { __builtin_amdgcn_s_setprio(1); _Pragma("unroll") for (int m = 0; m < 4; ++m) _Pragma("unroll") for (int n = 0; n < 2; ++n) _Pragma("unroll") for (int k = 0; k < 2; ++k) \
;         acc[ai][bj][m][n] = __builtin_amdgcn_mfma_f32_16x16x32_bf16(Bt[n][k], At[m][k], acc[ai][bj][m][n], 0, 0, 0); __builtin_amdgcn_s_setprio(0); } while (0)
; #define PG8_WAIT_V(n) asm volatile("s_waitcnt vmcnt(" #n ")" ::: "memory")
; #define PG8_WAIT_L(n) asm volatile("s_waitcnt lgkmcnt(" #n ")" ::: "memory")
; #define PG8_BAR __builtin_amdgcn_s_barrier()
; #define PG8_SCHED __builtin_amdgcn_sched_barrier(0)
; template <class Epi, class Sched>
; DI void gemm_phase(LAS unsigned char* lds, const int K, const Sched& S, const Epi& E) {
;     ...
;         for (int t = 0; t < nt; t += 2) {
;             const bool last = (t == nt - 2);
;             const char* a1 = cA + (size_t)(t + 1) * kstep;
;             const char* a2 = last ? nA : cA + (size_t)(t + 2) * kstep; const char* b2 = last ? nB : cB + (size_t)(t + 2) * kstep;
;             const char* a3 = a2 + kstep; const char* b3 = b2 + kstep;
;             PG8_LDB(B0, 0, 0); PG8_LDB(B1, 0, 1); PG8_SCHED; PG8_LDA(At, 0, 0); PG8_STAGE(PG8_SA(1, 1), a1 + hstep, voffA);
;             PG8_WAIT_V(8); PG8_WAIT_L(0); PG8_BAR; PG8_MMA(0, 0, At, B0); PG8_MMA(0, 1, At, B1); PG8_BAR; PG8_SCHED;
;             PG8_LDA(At, 0, 1); PG8_STAGE(PG8_SB(0, 0), b2, voffB); PG8_STAGE(PG8_SB(0, 1), b2 + hstep, voffB); PG8_STAGE(PG8_SA(0, 0), a2, voffA);
;             PG8_WAIT_V(8); PG8_WAIT_L(0); PG8_BAR; PG8_MMA(1, 0, At, B0); PG8_MMA(1, 1, At, B1); PG8_BAR; PG8_SCHED;
.LBB0_784:
	s_add_u32 s48, s44, 0xfffc0080
	s_addc_u32 s49, s45, -1
	s_add_i32 s77, 0, 0x10000
	s_cmp_eq_u32 s76, 12
	s_cselect_b32 s75, s69, s49
	s_cselect_b32 s74, s68, s48
	s_cselect_b32 s73, s71, s67
	s_cselect_b32 s72, s70, s65
	s_add_i32 s48, 0, 0x14000
	v_add_u32_e32 v142, s77, v199
	v_add_u32_e32 v158, s48, v199
	ds_read_b128 v[130:133], v142
	ds_read_b128 v[134:137], v142 offset:1024
	ds_read_b128 v[138:141], v142 offset:2048
	ds_read_b128 v[142:145], v142 offset:3072
	ds_read_b128 v[146:149], v158
	ds_read_b128 v[150:153], v158 offset:1024
	ds_read_b128 v[154:157], v158 offset:2048
	ds_read_b128 v[158:161], v158 offset:3072
	s_nop 0
	s_add_i32 m0, s80, 0xc000
	ds_read_b128 v[174:177], v200
	ds_read_b128 v[182:185], v200 offset:1024
	ds_read_b128 v[190:193], v200 offset:2048
	ds_read_b128 v[194:197], v200 offset:3072
	ds_read_b128 v[202:205], v200 offset:4096
	ds_read_b128 v[212:215], v200 offset:5120
	ds_read_b128 v[216:219], v200 offset:6144
	ds_read_b128 v[220:223], v200 offset:7168
	global_load_lds_dwordx4 v172, s[44:45]
	s_nop 0
	s_add_i32 m0, s80, 0xe000
	s_nop 0
	global_load_lds_dwordx4 v170, s[44:45]
	s_waitcnt vmcnt(8)
	s_waitcnt lgkmcnt(0)
	s_barrier
	s_nop 0
	s_waitcnt lgkmcnt(0)
	v_mfma_f32_16x16x32_bf16 v[126:129], v[130:133], v[174:177], v[126:129]
	v_mfma_f32_16x16x32_bf16 v[122:125], v[138:141], v[174:177], v[122:125]
	v_mfma_f32_16x16x32_bf16 v[118:121], v[130:133], v[190:193], v[118:121]
	v_mfma_f32_16x16x32_bf16 v[114:117], v[138:141], v[190:193], v[114:117]
	v_mfma_f32_16x16x32_bf16 v[110:113], v[130:133], v[202:205], v[110:113]
	v_mfma_f32_16x16x32_bf16 v[106:109], v[138:141], v[202:205], v[106:109]
	v_mfma_f32_16x16x32_bf16 v[102:105], v[130:133], v[216:219], v[102:105]
	v_mfma_f32_16x16x32_bf16 v[98:101], v[138:141], v[216:219], v[98:101]
	v_mfma_f32_16x16x32_bf16 v[126:129], v[134:137], v[182:185], v[126:129]
	v_mfma_f32_16x16x32_bf16 v[122:125], v[142:145], v[182:185], v[122:125]
	v_mfma_f32_16x16x32_bf16 v[118:121], v[134:137], v[194:197], v[118:121]
	v_mfma_f32_16x16x32_bf16 v[114:117], v[142:145], v[194:197], v[114:117]
	v_mfma_f32_16x16x32_bf16 v[110:113], v[134:137], v[212:215], v[110:113]
	v_mfma_f32_16x16x32_bf16 v[106:109], v[142:145], v[212:215], v[106:109]
	v_mfma_f32_16x16x32_bf16 v[102:105], v[134:137], v[220:223], v[102:105]
	v_mfma_f32_16x16x32_bf16 v[98:101], v[142:145], v[220:223], v[98:101]
	s_nop 0
	s_nop 0
	v_mfma_f32_16x16x32_bf16 v[94:97], v[146:149], v[174:177], v[94:97]
	v_mfma_f32_16x16x32_bf16 v[90:93], v[154:157], v[174:177], v[90:93]
	v_mfma_f32_16x16x32_bf16 v[86:89], v[146:149], v[190:193], v[86:89]
	v_mfma_f32_16x16x32_bf16 v[82:85], v[154:157], v[190:193], v[82:85]
	v_mfma_f32_16x16x32_bf16 v[78:81], v[146:149], v[202:205], v[78:81]
	v_mfma_f32_16x16x32_bf16 v[74:77], v[154:157], v[202:205], v[74:77]
	v_mfma_f32_16x16x32_bf16 v[70:73], v[146:149], v[216:219], v[70:73]
	v_mfma_f32_16x16x32_bf16 v[66:69], v[154:157], v[216:219], v[66:69]
	v_mfma_f32_16x16x32_bf16 v[94:97], v[150:153], v[182:185], v[94:97]
	v_mfma_f32_16x16x32_bf16 v[90:93], v[158:161], v[182:185], v[90:93]
	v_mfma_f32_16x16x32_bf16 v[86:89], v[150:153], v[194:197], v[86:89]
	v_mfma_f32_16x16x32_bf16 v[82:85], v[158:161], v[194:197], v[82:85]
	v_mfma_f32_16x16x32_bf16 v[78:81], v[150:153], v[212:215], v[78:81]
	v_mfma_f32_16x16x32_bf16 v[74:77], v[158:161], v[212:215], v[74:77]
	v_mfma_f32_16x16x32_bf16 v[70:73], v[150:153], v[220:223], v[70:73]
	v_mfma_f32_16x16x32_bf16 v[66:69], v[158:161], v[220:223], v[66:69]
	s_nop 0
	s_barrier
	s_add_i32 s49, s77, s79
	v_lshl_add_u64 v[224:225], s[72:73], 0, v[164:165]
	s_mov_b32 m0, s49
	ds_read_b128 v[174:177], v200 offset:16384
	ds_read_b128 v[182:185], v200 offset:17408
	ds_read_b128 v[190:193], v200 offset:18432
	ds_read_b128 v[194:197], v200 offset:19456
	ds_read_b128 v[202:205], v200 offset:20480
	ds_read_b128 v[212:215], v200 offset:21504
	ds_read_b128 v[216:219], v200 offset:22528
	ds_read_b128 v[220:223], v200 offset:23552
	global_load_lds_dwordx4 v[224:225], off
	s_add_i32 m0, s49, 0x2000
	s_add_u32 vcc_lo, s72, 0x40000
	v_lshl_add_u64 v[226:227], s[72:73], 0, v[168:169]
	s_addc_u32 vcc_hi, s73, 0
	s_add_i32 s48, s48, s79
	global_load_lds_dwordx4 v[226:227], off
	s_nop 0
	s_mov_b32 m0, s48
	s_nop 0
	global_load_lds_dwordx4 v164, vcc
	s_nop 0
	s_add_i32 m0, s48, 0x2000
	s_nop 0
	global_load_lds_dwordx4 v168, vcc
	s_nop 0
	s_add_u32 s98, s74, s90
	s_addc_u32 s99, s75, s91
	s_mov_b32 m0, s80
	s_nop 0
	global_load_lds_dwordx4 v162, s[74:75]
	s_mov_b32 m0, s81
	s_nop 0
	global_load_lds_dwordx4 v166, s[74:75]
	s_waitcnt vmcnt(8)
	s_waitcnt lgkmcnt(0)
	s_barrier
; #define PG8_STAGE(bufoff, gbase, voff) do { _Pragma("unroll") for (int _i = 0; _i < 2; ++_i) \
;         __builtin_amdgcn_global_load_lds((const unsigned*)((const char*)(gbase) + (voff)[_i]), (LAS unsigned*)(lds + (bufoff) + ldsw + _i * 8192), 16, 0, 0); } while (0)
; #define PG8_LDA(dst, b, h) do { _Pragma("unroll") for (int m = 0; m < 4; ++m) _Pragma("unroll") for (int k = 0; k < 2; ++k) dst[m][k] = *(const LAS bf16x8*)(lds + PG8_SA(b, h) + aoff + m * 2048 + k * 1024); } while (0)
; #define PG8_LDB(dst, b, h) do { _Pragma("unroll") for (int n = 0; n < 2; ++n) _Pragma("unroll") for (int k = 0; k < 2; ++k) dst[n][k] = *(const LAS bf16x8*)(lds + PG8_SB(b, h) + boff + n * 2048 + k * 1024); } while (0)
; #define PG8_MMA(ai, bj, At, Bt) do { __builtin_amdgcn_s_setprio(1); _Pragma("unroll") for (int m = 0; m < 4; ++m) _Pragma("unroll") for (int n = 0; n < 2; ++n) _Pragma("unroll") for (int k = 0; k < 2; ++k) \
;         acc[ai][bj][m][n] = __builtin_amdgcn_mfma_f32_16x16x32_bf16(Bt[n][k], At[m][k], acc[ai][bj][m][n], 0, 0, 0); __builtin_amdgcn_s_setprio(0); } while (0)
; #define PG8_WAIT_V(n) asm volatile("s_waitcnt vmcnt(" #n ")" ::: "memory")
; #define PG8_WAIT_L(n) asm volatile("s_waitcnt lgkmcnt(" #n ")" ::: "memory")
; #define PG8_BAR __builtin_amdgcn_s_barrier()
; #define PG8_SCHED __builtin_amdgcn_sched_barrier(0)
; template <class Epi, class Sched>
; DI void gemm_phase(LAS unsigned char* lds, const int K, const Sched& S, const Epi& E) {
;     ...
;             PG8_WAIT_V(8); PG8_WAIT_L(0); PG8_BAR; PG8_MMA(1, 0, At, B0); PG8_MMA(1, 1, At, B1); PG8_BAR; PG8_SCHED;
;             PG8_LDB(B0, 1, 0); PG8_LDB(B1, 1, 1); PG8_SCHED; PG8_LDA(At, 1, 0); PG8_STAGE(PG8_SA(0, 1), a2 + hstep, voffA);
;             PG8_WAIT_V(8); PG8_WAIT_L(0); PG8_BAR; PG8_MMA(0, 0, At, B0); PG8_MMA(0, 1, At, B1); PG8_BAR; PG8_SCHED;
	s_nop 0
	s_waitcnt lgkmcnt(0)
	v_mfma_f32_16x16x32_bf16 v[62:65], v[130:133], v[174:177], v[62:65]
	v_mfma_f32_16x16x32_bf16 v[58:61], v[138:141], v[174:177], v[58:61]
	v_mfma_f32_16x16x32_bf16 v[54:57], v[130:133], v[190:193], v[54:57]
	v_mfma_f32_16x16x32_bf16 v[50:53], v[138:141], v[190:193], v[50:53]
	v_mfma_f32_16x16x32_bf16 v[46:49], v[130:133], v[202:205], v[46:49]
	v_mfma_f32_16x16x32_bf16 v[42:45], v[138:141], v[202:205], v[42:45]
	v_mfma_f32_16x16x32_bf16 v[38:41], v[130:133], v[216:219], v[38:41]
	v_mfma_f32_16x16x32_bf16 v[34:37], v[138:141], v[216:219], v[34:37]
	v_mfma_f32_16x16x32_bf16 v[62:65], v[134:137], v[182:185], v[62:65]
	v_mfma_f32_16x16x32_bf16 v[58:61], v[142:145], v[182:185], v[58:61]
	v_mfma_f32_16x16x32_bf16 v[54:57], v[134:137], v[194:197], v[54:57]
	v_mfma_f32_16x16x32_bf16 v[50:53], v[142:145], v[194:197], v[50:53]
	v_mfma_f32_16x16x32_bf16 v[46:49], v[134:137], v[212:215], v[46:49]
	v_mfma_f32_16x16x32_bf16 v[42:45], v[142:145], v[212:215], v[42:45]
	v_mfma_f32_16x16x32_bf16 v[38:41], v[134:137], v[220:223], v[38:41]
	v_mfma_f32_16x16x32_bf16 v[34:37], v[142:145], v[220:223], v[34:37]
	s_nop 0
	s_nop 0
	v_mfma_f32_16x16x32_bf16 v[30:33], v[146:149], v[174:177], v[30:33]
	v_mfma_f32_16x16x32_bf16 v[26:29], v[154:157], v[174:177], v[26:29]
	v_mfma_f32_16x16x32_bf16 v[22:25], v[146:149], v[190:193], v[22:25]
	v_mfma_f32_16x16x32_bf16 v[18:21], v[154:157], v[190:193], v[18:21]
	v_mfma_f32_16x16x32_bf16 v[14:17], v[146:149], v[202:205], v[14:17]
	v_mfma_f32_16x16x32_bf16 v[10:13], v[154:157], v[202:205], v[10:13]
	v_mfma_f32_16x16x32_bf16 v[6:9], v[146:149], v[216:219], v[6:9]
	v_mfma_f32_16x16x32_bf16 v[2:5], v[154:157], v[216:219], v[2:5]
	v_mfma_f32_16x16x32_bf16 v[30:33], v[150:153], v[182:185], v[30:33]
	v_mfma_f32_16x16x32_bf16 v[26:29], v[158:161], v[182:185], v[26:29]
	v_mfma_f32_16x16x32_bf16 v[22:25], v[150:153], v[194:197], v[22:25]
	v_mfma_f32_16x16x32_bf16 v[18:21], v[158:161], v[194:197], v[18:21]
	v_mfma_f32_16x16x32_bf16 v[14:17], v[150:153], v[212:215], v[14:17]
	v_mfma_f32_16x16x32_bf16 v[10:13], v[158:161], v[212:215], v[10:13]
	v_mfma_f32_16x16x32_bf16 v[6:9], v[150:153], v[220:223], v[6:9]
	v_mfma_f32_16x16x32_bf16 v[2:5], v[158:161], v[220:223], v[2:5]
	s_nop 0
	s_barrier
	s_add_i32 s48, 0, 0x18000
	s_add_i32 s49, 0, 0x1c000
	v_add_u32_e32 v142, s48, v199
	v_add_u32_e32 v158, s49, v199
	ds_read_b128 v[130:133], v142
	ds_read_b128 v[134:137], v142 offset:1024
	ds_read_b128 v[138:141], v142 offset:2048
	ds_read_b128 v[142:145], v142 offset:3072
	ds_read_b128 v[146:149], v158
	ds_read_b128 v[150:153], v158 offset:1024
	ds_read_b128 v[154:157], v158 offset:2048
	ds_read_b128 v[158:161], v158 offset:3072
	s_add_u32 s74, s74, 0x40000
	s_addc_u32 s75, s75, 0
	s_mov_b32 m0, s85
	s_nop 0
	ds_read_b128 v[174:177], v200 offset:32768
	ds_read_b128 v[182:185], v200 offset:33792
	ds_read_b128 v[190:193], v200 offset:34816
	ds_read_b128 v[194:197], v200 offset:35840
	ds_read_b128 v[202:205], v200 offset:36864
	ds_read_b128 v[212:215], v200 offset:37888
	ds_read_b128 v[216:219], v200 offset:38912
	ds_read_b128 v[220:223], v200 offset:39936
	global_load_lds_dwordx4 v162, s[74:75]
	s_nop 0
	s_mov_b32 m0, s86
	s_nop 0
	global_load_lds_dwordx4 v166, s[74:75]
	s_waitcnt vmcnt(8)
	s_waitcnt lgkmcnt(0)
	s_barrier
	s_nop 0
	s_waitcnt lgkmcnt(0)
	v_mfma_f32_16x16x32_bf16 v[126:129], v[130:133], v[174:177], v[126:129]
	v_mfma_f32_16x16x32_bf16 v[122:125], v[138:141], v[174:177], v[122:125]
	v_mfma_f32_16x16x32_bf16 v[118:121], v[130:133], v[190:193], v[118:121]
	v_mfma_f32_16x16x32_bf16 v[114:117], v[138:141], v[190:193], v[114:117]
	v_mfma_f32_16x16x32_bf16 v[110:113], v[130:133], v[202:205], v[110:113]
	v_mfma_f32_16x16x32_bf16 v[106:109], v[138:141], v[202:205], v[106:109]
	v_mfma_f32_16x16x32_bf16 v[102:105], v[130:133], v[216:219], v[102:105]
	v_mfma_f32_16x16x32_bf16 v[98:101], v[138:141], v[216:219], v[98:101]
	v_mfma_f32_16x16x32_bf16 v[126:129], v[134:137], v[182:185], v[126:129]
	v_mfma_f32_16x16x32_bf16 v[122:125], v[142:145], v[182:185], v[122:125]
	v_mfma_f32_16x16x32_bf16 v[118:121], v[134:137], v[194:197], v[118:121]
	v_mfma_f32_16x16x32_bf16 v[114:117], v[142:145], v[194:197], v[114:117]
	v_mfma_f32_16x16x32_bf16 v[110:113], v[134:137], v[212:215], v[110:113]
	v_mfma_f32_16x16x32_bf16 v[106:109], v[142:145], v[212:215], v[106:109]
	v_mfma_f32_16x16x32_bf16 v[102:105], v[134:137], v[220:223], v[102:105]
	v_mfma_f32_16x16x32_bf16 v[98:101], v[142:145], v[220:223], v[98:101]
	s_nop 0
	s_nop 0
	v_mfma_f32_16x16x32_bf16 v[94:97], v[146:149], v[174:177], v[94:97]
	v_mfma_f32_16x16x32_bf16 v[90:93], v[154:157], v[174:177], v[90:93]
	v_mfma_f32_16x16x32_bf16 v[86:89], v[146:149], v[190:193], v[86:89]
	v_mfma_f32_16x16x32_bf16 v[82:85], v[154:157], v[190:193], v[82:85]
	v_mfma_f32_16x16x32_bf16 v[78:81], v[146:149], v[202:205], v[78:81]
	v_mfma_f32_16x16x32_bf16 v[74:77], v[154:157], v[202:205], v[74:77]
	v_mfma_f32_16x16x32_bf16 v[70:73], v[146:149], v[216:219], v[70:73]
	v_mfma_f32_16x16x32_bf16 v[66:69], v[154:157], v[216:219], v[66:69]
	v_mfma_f32_16x16x32_bf16 v[94:97], v[150:153], v[182:185], v[94:97]
	v_mfma_f32_16x16x32_bf16 v[90:93], v[158:161], v[182:185], v[90:93]
	v_mfma_f32_16x16x32_bf16 v[86:89], v[150:153], v[194:197], v[86:89]
	v_mfma_f32_16x16x32_bf16 v[82:85], v[158:161], v[194:197], v[82:85]
	v_mfma_f32_16x16x32_bf16 v[78:81], v[150:153], v[212:215], v[78:81]
	v_mfma_f32_16x16x32_bf16 v[74:77], v[158:161], v[212:215], v[74:77]
	v_mfma_f32_16x16x32_bf16 v[70:73], v[150:153], v[220:223], v[70:73]
	v_mfma_f32_16x16x32_bf16 v[66:69], v[158:161], v[220:223], v[66:69]
	s_nop 0
	s_barrier
; #define PG8_STAGE(bufoff, gbase, voff) do { _Pragma("unroll") for (int _i = 0; _i < 2; ++_i) \
;         __builtin_amdgcn_global_load_lds((const unsigned*)((const char*)(gbase) + (voff)[_i]), (LAS unsigned*)(lds + (bufoff) + ldsw + _i * 8192), 16, 0, 0); } while (0)
; #define PG8_LDA(dst, b, h) do { _Pragma("unroll") for (int m = 0; m < 4; ++m) _Pragma("unroll") for (int k = 0; k < 2; ++k) dst[m][k] = *(const LAS bf16x8*)(lds + PG8_SA(b, h) + aoff + m * 2048 + k * 1024); } while (0)
; #define PG8_MMA(ai, bj, At, Bt) do { __builtin_amdgcn_s_setprio(1); _Pragma("unroll") for (int m = 0; m < 4; ++m) _Pragma("unroll") for (int n = 0; n < 2; ++n) _Pragma("unroll") for (int k = 0; k < 2; ++k) \
;         acc[ai][bj][m][n] = __builtin_amdgcn_mfma_f32_16x16x32_bf16(Bt[n][k], At[m][k], acc[ai][bj][m][n], 0, 0, 0); __builtin_amdgcn_s_setprio(0); } while (0)
; #define PG8_WAIT_V(n) asm volatile("s_waitcnt vmcnt(" #n ")" ::: "memory")
; #define PG8_WAIT_L(n) asm volatile("s_waitcnt lgkmcnt(" #n ")" ::: "memory")
; #define PG8_BAR __builtin_amdgcn_s_barrier()
; #define PG8_SCHED __builtin_amdgcn_sched_barrier(0)
; template <class Epi, class Sched>
; DI void gemm_phase(LAS unsigned char* lds, const int K, const Sched& S, const Epi& E) {
;     ...
;             PG8_LDA(At, 1, 1); PG8_STAGE(PG8_SB(1, 0), b3, voffB); PG8_STAGE(PG8_SB(1, 1), b3 + hstep, voffB); PG8_STAGE(PG8_SA(1, 0), a3, voffA);
;             PG8_WAIT_V(8); PG8_WAIT_L(0); PG8_BAR; PG8_MMA(1, 0, At, B0); PG8_MMA(1, 1, At, B1); PG8_BAR; PG8_SCHED;
;         }
;         if (wr == 0) PG8_BAR;
	s_add_i32 s48, s48, s79
	v_lshl_add_u64 v[224:225], v[224:225], 0, s[90:91]
	s_mov_b32 m0, s48
	ds_read_b128 v[174:177], v200 offset:49152
	ds_read_b128 v[182:185], v200 offset:50176
	ds_read_b128 v[190:193], v200 offset:51200
	ds_read_b128 v[194:197], v200 offset:52224
	ds_read_b128 v[202:205], v200 offset:53248
	ds_read_b128 v[212:215], v200 offset:54272
	ds_read_b128 v[216:219], v200 offset:55296
	ds_read_b128 v[220:223], v200 offset:56320
	global_load_lds_dwordx4 v[224:225], off
	s_add_i32 m0, s48, 0x2000
	s_add_u32 s72, s72, 0x40080
	v_lshl_add_u64 v[224:225], v[226:227], 0, s[90:91]
	s_addc_u32 s73, s73, 0
	s_add_i32 s48, s49, s79
	global_load_lds_dwordx4 v[224:225], off
	s_nop 0
	s_mov_b32 m0, s48
	s_nop 0
	global_load_lds_dwordx4 v164, s[72:73]
	s_nop 0
	s_add_i32 m0, s48, 0x2000
	s_nop 0
	global_load_lds_dwordx4 v168, s[72:73]
	s_nop 0
	s_mov_b32 m0, s94
	s_nop 0
	global_load_lds_dwordx4 v162, s[98:99]
	s_nop 0
	s_mov_b32 m0, s95
	s_nop 0
	global_load_lds_dwordx4 v166, s[98:99]
	s_waitcnt vmcnt(8)
	s_waitcnt lgkmcnt(0)
	s_barrier
	s_nop 0
	s_waitcnt lgkmcnt(0)
	v_mfma_f32_16x16x32_bf16 v[62:65], v[130:133], v[174:177], v[62:65]
	v_mfma_f32_16x16x32_bf16 v[58:61], v[138:141], v[174:177], v[58:61]
	v_mfma_f32_16x16x32_bf16 v[54:57], v[130:133], v[190:193], v[54:57]
	v_mfma_f32_16x16x32_bf16 v[50:53], v[138:141], v[190:193], v[50:53]
	v_mfma_f32_16x16x32_bf16 v[46:49], v[130:133], v[202:205], v[46:49]
	v_mfma_f32_16x16x32_bf16 v[42:45], v[138:141], v[202:205], v[42:45]
	v_mfma_f32_16x16x32_bf16 v[38:41], v[130:133], v[216:219], v[38:41]
	v_mfma_f32_16x16x32_bf16 v[34:37], v[138:141], v[216:219], v[34:37]
	v_mfma_f32_16x16x32_bf16 v[62:65], v[134:137], v[182:185], v[62:65]
	v_mfma_f32_16x16x32_bf16 v[58:61], v[142:145], v[182:185], v[58:61]
	v_mfma_f32_16x16x32_bf16 v[54:57], v[134:137], v[194:197], v[54:57]
	v_mfma_f32_16x16x32_bf16 v[50:53], v[142:145], v[194:197], v[50:53]
	v_mfma_f32_16x16x32_bf16 v[46:49], v[134:137], v[212:215], v[46:49]
	v_mfma_f32_16x16x32_bf16 v[42:45], v[142:145], v[212:215], v[42:45]
	v_mfma_f32_16x16x32_bf16 v[38:41], v[134:137], v[220:223], v[38:41]
	v_mfma_f32_16x16x32_bf16 v[34:37], v[142:145], v[220:223], v[34:37]
	s_nop 0
	s_nop 0
	v_mfma_f32_16x16x32_bf16 v[30:33], v[146:149], v[174:177], v[30:33]
	v_mfma_f32_16x16x32_bf16 v[26:29], v[154:157], v[174:177], v[26:29]
	v_mfma_f32_16x16x32_bf16 v[22:25], v[146:149], v[190:193], v[22:25]
	v_mfma_f32_16x16x32_bf16 v[18:21], v[154:157], v[190:193], v[18:21]
	v_mfma_f32_16x16x32_bf16 v[14:17], v[146:149], v[202:205], v[14:17]
	v_mfma_f32_16x16x32_bf16 v[10:13], v[154:157], v[202:205], v[10:13]
	v_mfma_f32_16x16x32_bf16 v[6:9], v[146:149], v[216:219], v[6:9]
	v_mfma_f32_16x16x32_bf16 v[2:5], v[154:157], v[216:219], v[2:5]
	v_mfma_f32_16x16x32_bf16 v[30:33], v[150:153], v[182:185], v[30:33]
	v_mfma_f32_16x16x32_bf16 v[26:29], v[158:161], v[182:185], v[26:29]
	v_mfma_f32_16x16x32_bf16 v[22:25], v[150:153], v[194:197], v[22:25]
	v_mfma_f32_16x16x32_bf16 v[18:21], v[158:161], v[194:197], v[18:21]
	v_mfma_f32_16x16x32_bf16 v[14:17], v[150:153], v[212:215], v[14:17]
	v_mfma_f32_16x16x32_bf16 v[10:13], v[158:161], v[212:215], v[10:13]
	v_mfma_f32_16x16x32_bf16 v[6:9], v[150:153], v[220:223], v[6:9]
	v_mfma_f32_16x16x32_bf16 v[2:5], v[158:161], v[220:223], v[2:5]
	s_nop 0
	s_barrier
	s_add_i32 s76, s76, 2
	s_add_u32 s65, s65, 0x100
	s_addc_u32 s67, s67, 0
	s_add_u32 s44, s44, 0x100
	s_addc_u32 s45, s45, 0
	s_cmp_gt_u32 s76, 13
	s_cbranch_scc0 .LBB0_784
	s_and_b64 vcc, exec, s[58:59]
	s_cbranch_vccz .LBB0_787
	s_barrier

; #define PG8_STAGE(bufoff, gbase, voff) do { _Pragma("unroll") for (int _i = 0; _i < 2; ++_i) \
;         __builtin_amdgcn_global_load_lds((const unsigned*)((const char*)(gbase) + (voff)[_i]), (LAS unsigned*)(lds + (bufoff) + ldsw + _i * 8192), 16, 0, 0); } while (0)
; #define PG8_LDA(dst, b, h) do { _Pragma("unroll") for (int m = 0; m < 4; ++m) _Pragma("unroll") for (int k = 0; k < 2; ++k) dst[m][k] = *(const LAS bf16x8*)(lds + PG8_SA(b, h) + aoff + m * 2048 + k * 1024); } while (0)
; #define PG8_LDB(dst, b, h) do { _Pragma("unroll") for (int n = 0; n < 2; ++n) _Pragma("unroll") for (int k = 0; k < 2; ++k) dst[n][k] = *(const LAS bf16x8*)(lds + PG8_SB(b, h) + boff + n * 2048 + k * 1024); } while (0)
; #define PG8_MMA(ai, bj, At, Bt) do { __builtin_amdgcn_s_setprio(1); _Pragma("unroll") for (int m = 0; m < 4; ++m) _Pragma("unroll") for (int n = 0; n < 2; ++n) _Pragma("unroll") for (int k = 0; k < 2; ++k) \
;         acc[ai][bj][m][n] = __builtin_amdgcn_mfma_f32_16x16x32_bf16(Bt[n][k], At[m][k], acc[ai][bj][m][n], 0, 0, 0); __builtin_amdgcn_s_setprio(0); } while (0)
; #define PG8_WAIT_V(n) asm volatile("s_waitcnt vmcnt(" #n ")" ::: "memory")
; #define PG8_WAIT_L(n) asm volatile("s_waitcnt lgkmcnt(" #n ")" ::: "memory")
; #define PG8_BAR __builtin_amdgcn_s_barrier()
; #define PG8_SCHED __builtin_amdgcn_sched_barrier(0)
; template <class Epi, class Sched>
; DI void gemm_phase(LAS unsigned char* lds, const int K, const Sched& S, const Epi& E) {
;     ...
;         for (int t = 0; t < nt; t += 2) {
;             const bool last = (t == nt - 2);
;             const char* a1 = cA + (size_t)(t + 1) * kstep;
;             const char* a2 = last ? nA : cA + (size_t)(t + 2) * kstep; const char* b2 = last ? nB : cB + (size_t)(t + 2) * kstep;
;             const char* a3 = a2 + kstep; const char* b3 = b2 + kstep;
;             PG8_LDB(B0, 0, 0); PG8_LDB(B1, 0, 1); PG8_SCHED; PG8_LDA(At, 0, 0); PG8_STAGE(PG8_SA(1, 1), a1 + hstep, voffA);
;             PG8_WAIT_V(8); PG8_WAIT_L(0); PG8_BAR; PG8_MMA(0, 0, At, B0); PG8_MMA(0, 1, At, B1); PG8_BAR; PG8_SCHED;
;             PG8_LDA(At, 0, 1); PG8_STAGE(PG8_SB(0, 0), b2, voffB); PG8_STAGE(PG8_SB(0, 1), b2 + hstep, voffB); PG8_STAGE(PG8_SA(0, 0), a2, voffA);
;             PG8_WAIT_V(8); PG8_WAIT_L(0); PG8_BAR; PG8_MMA(1, 0, At, B0); PG8_MMA(1, 1, At, B1); PG8_BAR; PG8_SCHED;
.LBB0_945:
	s_add_u32 s48, s62, 0xfffc0080
	s_addc_u32 s49, s63, -1
	s_add_i32 s84, 0, 0x10000
	s_cmp_eq_u32 s83, 12
	s_cselect_b32 s67, s59, s49
	s_cselect_b32 s66, s58, s48
	v_add_u32_e32 v145, s84, v143
	s_cselect_b32 s65, s61, s57
	s_cselect_b32 s64, s60, s55
	s_add_i32 s48, 0, 0x14000
	ds_read_b128 v[146:149], v145
	ds_read_b128 v[150:153], v145 offset:1024
	ds_read_b128 v[154:157], v145 offset:2048
	ds_read_b128 v[158:161], v145 offset:3072
	v_add_u32_e32 v145, s48, v143
	ds_read_b128 v[162:165], v145
	ds_read_b128 v[166:169], v145 offset:1024
	ds_read_b128 v[170:173], v145 offset:2048
	ds_read_b128 v[174:177], v145 offset:3072
	s_nop 0
	s_add_i32 m0, s53, 0xc000
	ds_read_b128 v[182:185], v144
	ds_read_b128 v[190:193], v144 offset:1024
	ds_read_b128 v[194:197], v144 offset:2048
	ds_read_b128 v[198:201], v144 offset:3072
	ds_read_b128 v[202:205], v144 offset:4096
	ds_read_b128 v[212:215], v144 offset:5120
	ds_read_b128 v[216:219], v144 offset:6144
	ds_read_b128 v[220:223], v144 offset:7168
	global_load_lds_dwordx4 v140, s[62:63]
	s_nop 0
	s_add_i32 m0, s53, 0xe000
	s_nop 0
	global_load_lds_dwordx4 v138, s[62:63]
	s_waitcnt vmcnt(8)
	s_waitcnt lgkmcnt(0)
	s_barrier
	s_nop 0
	s_waitcnt lgkmcnt(0)
	v_mfma_f32_16x16x32_bf16 v[126:129], v[146:149], v[182:185], v[126:129]
	v_mfma_f32_16x16x32_bf16 v[122:125], v[154:157], v[182:185], v[122:125]
	v_mfma_f32_16x16x32_bf16 v[118:121], v[146:149], v[194:197], v[118:121]
	v_mfma_f32_16x16x32_bf16 v[114:117], v[154:157], v[194:197], v[114:117]
	v_mfma_f32_16x16x32_bf16 v[102:105], v[146:149], v[202:205], v[102:105]
	v_mfma_f32_16x16x32_bf16 v[98:101], v[154:157], v[202:205], v[98:101]
	v_mfma_f32_16x16x32_bf16 v[86:89], v[146:149], v[216:219], v[86:89]
	v_mfma_f32_16x16x32_bf16 v[82:85], v[154:157], v[216:219], v[82:85]
	v_mfma_f32_16x16x32_bf16 v[126:129], v[150:153], v[190:193], v[126:129]
	v_mfma_f32_16x16x32_bf16 v[122:125], v[158:161], v[190:193], v[122:125]
	v_mfma_f32_16x16x32_bf16 v[118:121], v[150:153], v[198:201], v[118:121]
	v_mfma_f32_16x16x32_bf16 v[114:117], v[158:161], v[198:201], v[114:117]
	v_mfma_f32_16x16x32_bf16 v[102:105], v[150:153], v[212:215], v[102:105]
	v_mfma_f32_16x16x32_bf16 v[98:101], v[158:161], v[212:215], v[98:101]
	v_mfma_f32_16x16x32_bf16 v[86:89], v[150:153], v[220:223], v[86:89]
	v_mfma_f32_16x16x32_bf16 v[82:85], v[158:161], v[220:223], v[82:85]
	s_nop 0
	s_nop 0
	v_mfma_f32_16x16x32_bf16 v[110:113], v[162:165], v[182:185], v[110:113]
	v_mfma_f32_16x16x32_bf16 v[106:109], v[170:173], v[182:185], v[106:109]
	v_mfma_f32_16x16x32_bf16 v[94:97], v[162:165], v[194:197], v[94:97]
	v_mfma_f32_16x16x32_bf16 v[90:93], v[170:173], v[194:197], v[90:93]
	v_mfma_f32_16x16x32_bf16 v[78:81], v[162:165], v[202:205], v[78:81]
	v_mfma_f32_16x16x32_bf16 v[74:77], v[170:173], v[202:205], v[74:77]
	v_mfma_f32_16x16x32_bf16 v[70:73], v[162:165], v[216:219], v[70:73]
	v_mfma_f32_16x16x32_bf16 v[66:69], v[170:173], v[216:219], v[66:69]
	v_mfma_f32_16x16x32_bf16 v[110:113], v[166:169], v[190:193], v[110:113]
	v_mfma_f32_16x16x32_bf16 v[106:109], v[174:177], v[190:193], v[106:109]
	v_mfma_f32_16x16x32_bf16 v[94:97], v[166:169], v[198:201], v[94:97]
	v_mfma_f32_16x16x32_bf16 v[90:93], v[174:177], v[198:201], v[90:93]
	v_mfma_f32_16x16x32_bf16 v[78:81], v[166:169], v[212:215], v[78:81]
	v_mfma_f32_16x16x32_bf16 v[74:77], v[174:177], v[212:215], v[74:77]
	v_mfma_f32_16x16x32_bf16 v[70:73], v[166:169], v[220:223], v[70:73]
	v_mfma_f32_16x16x32_bf16 v[66:69], v[174:177], v[220:223], v[66:69]
	s_nop 0
	s_barrier
	s_add_i32 s49, s84, s71
	v_lshl_add_u64 v[224:225], s[64:65], 0, v[134:135]
	s_mov_b32 m0, s49
	ds_read_b128 v[182:185], v144 offset:16384
	ds_read_b128 v[190:193], v144 offset:17408
	ds_read_b128 v[194:197], v144 offset:18432
	ds_read_b128 v[198:201], v144 offset:19456
	ds_read_b128 v[202:205], v144 offset:20480
	ds_read_b128 v[212:215], v144 offset:21504
	ds_read_b128 v[216:219], v144 offset:22528
	ds_read_b128 v[220:223], v144 offset:23552
	global_load_lds_dwordx4 v[224:225], off
	s_add_i32 m0, s49, 0x2000
	s_add_u32 s84, s64, 0x40000
	v_lshl_add_u64 v[226:227], s[64:65], 0, v[130:131]
	s_addc_u32 s85, s65, 0
	s_add_i32 s48, s48, s71
	global_load_lds_dwordx4 v[226:227], off
	s_nop 0
	s_mov_b32 m0, s48
	s_nop 0
	global_load_lds_dwordx4 v134, s[84:85]
	s_nop 0
	s_add_i32 m0, s48, 0x2000
	s_nop 0
	global_load_lds_dwordx4 v130, s[84:85]
	s_nop 0
	s_add_u32 s98, s66, s90
	s_addc_u32 s99, s67, s91
	s_mov_b32 m0, s53
	s_nop 0
	global_load_lds_dwordx4 v136, s[66:67]
	s_mov_b32 m0, s73
	s_nop 0
	global_load_lds_dwordx4 v132, s[66:67]
	s_waitcnt vmcnt(8)
	s_waitcnt lgkmcnt(0)
	s_barrier
; #define PG8_STAGE(bufoff, gbase, voff) do { _Pragma("unroll") for (int _i = 0; _i < 2; ++_i) \
;         __builtin_amdgcn_global_load_lds((const unsigned*)((const char*)(gbase) + (voff)[_i]), (LAS unsigned*)(lds + (bufoff) + ldsw + _i * 8192), 16, 0, 0); } while (0)
; #define PG8_LDA(dst, b, h) do { _Pragma("unroll") for (int m = 0; m < 4; ++m) _Pragma("unroll") for (int k = 0; k < 2; ++k) dst[m][k] = *(const LAS bf16x8*)(lds + PG8_SA(b, h) + aoff + m * 2048 + k * 1024); } while (0)
; #define PG8_LDB(dst, b, h) do { _Pragma("unroll") for (int n = 0; n < 2; ++n) _Pragma("unroll") for (int k = 0; k < 2; ++k) dst[n][k] = *(const LAS bf16x8*)(lds + PG8_SB(b, h) + boff + n * 2048 + k * 1024); } while (0)
; #define PG8_MMA(ai, bj, At, Bt) do { __builtin_amdgcn_s_setprio(1); _Pragma("unroll") for (int m = 0; m < 4; ++m) _Pragma("unroll") for (int n = 0; n < 2; ++n) _Pragma("unroll") for (int k = 0; k < 2; ++k) \
;         acc[ai][bj][m][n] = __builtin_amdgcn_mfma_f32_16x16x32_bf16(Bt[n][k], At[m][k], acc[ai][bj][m][n], 0, 0, 0); __builtin_amdgcn_s_setprio(0); } while (0)
; #define PG8_WAIT_V(n) asm volatile("s_waitcnt vmcnt(" #n ")" ::: "memory")
; #define PG8_WAIT_L(n) asm volatile("s_waitcnt lgkmcnt(" #n ")" ::: "memory")
; #define PG8_BAR __builtin_amdgcn_s_barrier()
; #define PG8_SCHED __builtin_amdgcn_sched_barrier(0)
; template <class Epi, class Sched>
; DI void gemm_phase(LAS unsigned char* lds, const int K, const Sched& S, const Epi& E) {
;     ...
;             PG8_WAIT_V(8); PG8_WAIT_L(0); PG8_BAR; PG8_MMA(1, 0, At, B0); PG8_MMA(1, 1, At, B1); PG8_BAR; PG8_SCHED;
;             PG8_LDB(B0, 1, 0); PG8_LDB(B1, 1, 1); PG8_SCHED; PG8_LDA(At, 1, 0); PG8_STAGE(PG8_SA(0, 1), a2 + hstep, voffA);
;             PG8_WAIT_V(8); PG8_WAIT_L(0); PG8_BAR; PG8_MMA(0, 0, At, B0); PG8_MMA(0, 1, At, B1); PG8_BAR; PG8_SCHED;
	s_nop 0
	s_waitcnt lgkmcnt(0)
	v_mfma_f32_16x16x32_bf16 v[62:65], v[146:149], v[182:185], v[62:65]
	v_mfma_f32_16x16x32_bf16 v[58:61], v[154:157], v[182:185], v[58:61]
	v_mfma_f32_16x16x32_bf16 v[54:57], v[146:149], v[194:197], v[54:57]
	v_mfma_f32_16x16x32_bf16 v[50:53], v[154:157], v[194:197], v[50:53]
	v_mfma_f32_16x16x32_bf16 v[38:41], v[146:149], v[202:205], v[38:41]
	v_mfma_f32_16x16x32_bf16 v[34:37], v[154:157], v[202:205], v[34:37]
	v_mfma_f32_16x16x32_bf16 v[22:25], v[146:149], v[216:219], v[22:25]
	v_mfma_f32_16x16x32_bf16 v[18:21], v[154:157], v[216:219], v[18:21]
	v_mfma_f32_16x16x32_bf16 v[62:65], v[150:153], v[190:193], v[62:65]
	v_mfma_f32_16x16x32_bf16 v[58:61], v[158:161], v[190:193], v[58:61]
	v_mfma_f32_16x16x32_bf16 v[54:57], v[150:153], v[198:201], v[54:57]
	v_mfma_f32_16x16x32_bf16 v[50:53], v[158:161], v[198:201], v[50:53]
	v_mfma_f32_16x16x32_bf16 v[38:41], v[150:153], v[212:215], v[38:41]
	v_mfma_f32_16x16x32_bf16 v[34:37], v[158:161], v[212:215], v[34:37]
	v_mfma_f32_16x16x32_bf16 v[22:25], v[150:153], v[220:223], v[22:25]
	v_mfma_f32_16x16x32_bf16 v[18:21], v[158:161], v[220:223], v[18:21]
	s_nop 0
	s_nop 0
	v_mfma_f32_16x16x32_bf16 v[46:49], v[162:165], v[182:185], v[46:49]
	v_mfma_f32_16x16x32_bf16 v[42:45], v[170:173], v[182:185], v[42:45]
	v_mfma_f32_16x16x32_bf16 v[30:33], v[162:165], v[194:197], v[30:33]
	v_mfma_f32_16x16x32_bf16 v[26:29], v[170:173], v[194:197], v[26:29]
	v_mfma_f32_16x16x32_bf16 v[14:17], v[162:165], v[202:205], v[14:17]
	v_mfma_f32_16x16x32_bf16 v[10:13], v[170:173], v[202:205], v[10:13]
	v_mfma_f32_16x16x32_bf16 v[6:9], v[162:165], v[216:219], v[6:9]
	v_mfma_f32_16x16x32_bf16 v[2:5], v[170:173], v[216:219], v[2:5]
	v_mfma_f32_16x16x32_bf16 v[46:49], v[166:169], v[190:193], v[46:49]
	v_mfma_f32_16x16x32_bf16 v[42:45], v[174:177], v[190:193], v[42:45]
	v_mfma_f32_16x16x32_bf16 v[30:33], v[166:169], v[198:201], v[30:33]
	v_mfma_f32_16x16x32_bf16 v[26:29], v[174:177], v[198:201], v[26:29]
	v_mfma_f32_16x16x32_bf16 v[14:17], v[166:169], v[212:215], v[14:17]
	v_mfma_f32_16x16x32_bf16 v[10:13], v[174:177], v[212:215], v[10:13]
	v_mfma_f32_16x16x32_bf16 v[6:9], v[166:169], v[220:223], v[6:9]
	v_mfma_f32_16x16x32_bf16 v[2:5], v[174:177], v[220:223], v[2:5]
	s_nop 0
	s_barrier
	s_add_i32 s48, 0, 0x18000
	v_add_u32_e32 v145, s48, v143
	s_add_i32 s49, 0, 0x1c000
	ds_read_b128 v[146:149], v145
	ds_read_b128 v[150:153], v145 offset:1024
	ds_read_b128 v[154:157], v145 offset:2048
	ds_read_b128 v[158:161], v145 offset:3072
	v_add_u32_e32 v145, s49, v143
	ds_read_b128 v[162:165], v145
	ds_read_b128 v[166:169], v145 offset:1024
	ds_read_b128 v[170:173], v145 offset:2048
	ds_read_b128 v[174:177], v145 offset:3072
	s_add_u32 s66, s66, 0x40000
	s_addc_u32 s67, s67, 0
	s_mov_b32 m0, s74
	s_nop 0
	ds_read_b128 v[182:185], v144 offset:32768
	ds_read_b128 v[190:193], v144 offset:33792
	ds_read_b128 v[194:197], v144 offset:34816
	ds_read_b128 v[198:201], v144 offset:35840
	ds_read_b128 v[202:205], v144 offset:36864
	ds_read_b128 v[212:215], v144 offset:37888
	ds_read_b128 v[216:219], v144 offset:38912
	ds_read_b128 v[220:223], v144 offset:39936
	global_load_lds_dwordx4 v136, s[66:67]
	s_nop 0
	s_mov_b32 m0, s75
	s_nop 0
	global_load_lds_dwordx4 v132, s[66:67]
	s_waitcnt vmcnt(8)
	s_waitcnt lgkmcnt(0)
	s_barrier
	s_nop 0
	s_waitcnt lgkmcnt(0)
	v_mfma_f32_16x16x32_bf16 v[126:129], v[146:149], v[182:185], v[126:129]
	v_mfma_f32_16x16x32_bf16 v[122:125], v[154:157], v[182:185], v[122:125]
	v_mfma_f32_16x16x32_bf16 v[118:121], v[146:149], v[194:197], v[118:121]
	v_mfma_f32_16x16x32_bf16 v[114:117], v[154:157], v[194:197], v[114:117]
	v_mfma_f32_16x16x32_bf16 v[102:105], v[146:149], v[202:205], v[102:105]
	v_mfma_f32_16x16x32_bf16 v[98:101], v[154:157], v[202:205], v[98:101]
	v_mfma_f32_16x16x32_bf16 v[86:89], v[146:149], v[216:219], v[86:89]
	v_mfma_f32_16x16x32_bf16 v[82:85], v[154:157], v[216:219], v[82:85]
	v_mfma_f32_16x16x32_bf16 v[126:129], v[150:153], v[190:193], v[126:129]
	v_mfma_f32_16x16x32_bf16 v[122:125], v[158:161], v[190:193], v[122:125]
	v_mfma_f32_16x16x32_bf16 v[118:121], v[150:153], v[198:201], v[118:121]
	v_mfma_f32_16x16x32_bf16 v[114:117], v[158:161], v[198:201], v[114:117]
	v_mfma_f32_16x16x32_bf16 v[102:105], v[150:153], v[212:215], v[102:105]
	v_mfma_f32_16x16x32_bf16 v[98:101], v[158:161], v[212:215], v[98:101]
	v_mfma_f32_16x16x32_bf16 v[86:89], v[150:153], v[220:223], v[86:89]
	v_mfma_f32_16x16x32_bf16 v[82:85], v[158:161], v[220:223], v[82:85]
	s_nop 0
	s_nop 0
	v_mfma_f32_16x16x32_bf16 v[110:113], v[162:165], v[182:185], v[110:113]
	v_mfma_f32_16x16x32_bf16 v[106:109], v[170:173], v[182:185], v[106:109]
	v_mfma_f32_16x16x32_bf16 v[94:97], v[162:165], v[194:197], v[94:97]
	v_mfma_f32_16x16x32_bf16 v[90:93], v[170:173], v[194:197], v[90:93]
	v_mfma_f32_16x16x32_bf16 v[78:81], v[162:165], v[202:205], v[78:81]
	v_mfma_f32_16x16x32_bf16 v[74:77], v[170:173], v[202:205], v[74:77]
	v_mfma_f32_16x16x32_bf16 v[70:73], v[162:165], v[216:219], v[70:73]
	v_mfma_f32_16x16x32_bf16 v[66:69], v[170:173], v[216:219], v[66:69]
	v_mfma_f32_16x16x32_bf16 v[110:113], v[166:169], v[190:193], v[110:113]
	v_mfma_f32_16x16x32_bf16 v[106:109], v[174:177], v[190:193], v[106:109]
	v_mfma_f32_16x16x32_bf16 v[94:97], v[166:169], v[198:201], v[94:97]
	v_mfma_f32_16x16x32_bf16 v[90:93], v[174:177], v[198:201], v[90:93]
	v_mfma_f32_16x16x32_bf16 v[78:81], v[166:169], v[212:215], v[78:81]
	v_mfma_f32_16x16x32_bf16 v[74:77], v[174:177], v[212:215], v[74:77]
	v_mfma_f32_16x16x32_bf16 v[70:73], v[166:169], v[220:223], v[70:73]
	v_mfma_f32_16x16x32_bf16 v[66:69], v[174:177], v[220:223], v[66:69]
	s_nop 0
	s_barrier
; #define PG8_STAGE(bufoff, gbase, voff) do { _Pragma("unroll") for (int _i = 0; _i < 2; ++_i) \
;         __builtin_amdgcn_global_load_lds((const unsigned*)((const char*)(gbase) + (voff)[_i]), (LAS unsigned*)(lds + (bufoff) + ldsw + _i * 8192), 16, 0, 0); } while (0)
; #define PG8_LDA(dst, b, h) do { _Pragma("unroll") for (int m = 0; m < 4; ++m) _Pragma("unroll") for (int k = 0; k < 2; ++k) dst[m][k] = *(const LAS bf16x8*)(lds + PG8_SA(b, h) + aoff + m * 2048 + k * 1024); } while (0)
; #define PG8_MMA(ai, bj, At, Bt) do { __builtin_amdgcn_s_setprio(1); _Pragma("unroll") for (int m = 0; m < 4; ++m) _Pragma("unroll") for (int n = 0; n < 2; ++n) _Pragma("unroll") for (int k = 0; k < 2; ++k) \
;         acc[ai][bj][m][n] = __builtin_amdgcn_mfma_f32_16x16x32_bf16(Bt[n][k], At[m][k], acc[ai][bj][m][n], 0, 0, 0); __builtin_amdgcn_s_setprio(0); } while (0)
; #define PG8_WAIT_V(n) asm volatile("s_waitcnt vmcnt(" #n ")" ::: "memory")
; #define PG8_WAIT_L(n) asm volatile("s_waitcnt lgkmcnt(" #n ")" ::: "memory")
; #define PG8_BAR __builtin_amdgcn_s_barrier()
; #define PG8_SCHED __builtin_amdgcn_sched_barrier(0)
; template <class Epi, class Sched>
; DI void gemm_phase(LAS unsigned char* lds, const int K, const Sched& S, const Epi& E) {
;     ...
;             PG8_LDA(At, 1, 1); PG8_STAGE(PG8_SB(1, 0), b3, voffB); PG8_STAGE(PG8_SB(1, 1), b3 + hstep, voffB); PG8_STAGE(PG8_SA(1, 0), a3, voffA);
;             PG8_WAIT_V(8); PG8_WAIT_L(0); PG8_BAR; PG8_MMA(1, 0, At, B0); PG8_MMA(1, 1, At, B1); PG8_BAR; PG8_SCHED;
;         }
;         if (wr == 0) PG8_BAR;
	s_add_i32 s48, s48, s71
	v_lshl_add_u64 v[224:225], v[224:225], 0, s[90:91]
	s_mov_b32 m0, s48
	ds_read_b128 v[182:185], v144 offset:49152
	ds_read_b128 v[190:193], v144 offset:50176
	ds_read_b128 v[194:197], v144 offset:51200
	ds_read_b128 v[198:201], v144 offset:52224
	ds_read_b128 v[202:205], v144 offset:53248
	ds_read_b128 v[212:215], v144 offset:54272
	ds_read_b128 v[216:219], v144 offset:55296
	ds_read_b128 v[220:223], v144 offset:56320
	global_load_lds_dwordx4 v[224:225], off
	s_add_i32 m0, s48, 0x2000
	s_add_u32 s64, s64, 0x40080
	v_lshl_add_u64 v[224:225], v[226:227], 0, s[90:91]
	s_addc_u32 s65, s65, 0
	s_add_i32 s48, s49, s71
	global_load_lds_dwordx4 v[224:225], off
	s_nop 0
	s_mov_b32 m0, s48
	s_nop 0
	global_load_lds_dwordx4 v134, s[64:65]
	s_nop 0
	s_add_i32 m0, s48, 0x2000
	s_nop 0
	global_load_lds_dwordx4 v130, s[64:65]
	s_nop 0
	s_mov_b32 m0, s78
	s_nop 0
	global_load_lds_dwordx4 v136, s[98:99]
	s_nop 0
	s_mov_b32 m0, s79
	s_nop 0
	global_load_lds_dwordx4 v132, s[98:99]
	s_waitcnt vmcnt(8)
	s_waitcnt lgkmcnt(0)
	s_barrier
	s_nop 0
	s_waitcnt lgkmcnt(0)
	v_mfma_f32_16x16x32_bf16 v[62:65], v[146:149], v[182:185], v[62:65]
	v_mfma_f32_16x16x32_bf16 v[58:61], v[154:157], v[182:185], v[58:61]
	v_mfma_f32_16x16x32_bf16 v[54:57], v[146:149], v[194:197], v[54:57]
	v_mfma_f32_16x16x32_bf16 v[50:53], v[154:157], v[194:197], v[50:53]
	v_mfma_f32_16x16x32_bf16 v[38:41], v[146:149], v[202:205], v[38:41]
	v_mfma_f32_16x16x32_bf16 v[34:37], v[154:157], v[202:205], v[34:37]
	v_mfma_f32_16x16x32_bf16 v[22:25], v[146:149], v[216:219], v[22:25]
	v_mfma_f32_16x16x32_bf16 v[18:21], v[154:157], v[216:219], v[18:21]
	v_mfma_f32_16x16x32_bf16 v[62:65], v[150:153], v[190:193], v[62:65]
	v_mfma_f32_16x16x32_bf16 v[58:61], v[158:161], v[190:193], v[58:61]
	v_mfma_f32_16x16x32_bf16 v[54:57], v[150:153], v[198:201], v[54:57]
	v_mfma_f32_16x16x32_bf16 v[50:53], v[158:161], v[198:201], v[50:53]
	v_mfma_f32_16x16x32_bf16 v[38:41], v[150:153], v[212:215], v[38:41]
	v_mfma_f32_16x16x32_bf16 v[34:37], v[158:161], v[212:215], v[34:37]
	v_mfma_f32_16x16x32_bf16 v[22:25], v[150:153], v[220:223], v[22:25]
	v_mfma_f32_16x16x32_bf16 v[18:21], v[158:161], v[220:223], v[18:21]
	s_nop 0
	s_nop 0
	v_mfma_f32_16x16x32_bf16 v[46:49], v[162:165], v[182:185], v[46:49]
	v_mfma_f32_16x16x32_bf16 v[42:45], v[170:173], v[182:185], v[42:45]
	v_mfma_f32_16x16x32_bf16 v[30:33], v[162:165], v[194:197], v[30:33]
	v_mfma_f32_16x16x32_bf16 v[26:29], v[170:173], v[194:197], v[26:29]
	v_mfma_f32_16x16x32_bf16 v[14:17], v[162:165], v[202:205], v[14:17]
	v_mfma_f32_16x16x32_bf16 v[10:13], v[170:173], v[202:205], v[10:13]
	v_mfma_f32_16x16x32_bf16 v[6:9], v[162:165], v[216:219], v[6:9]
	v_mfma_f32_16x16x32_bf16 v[2:5], v[170:173], v[216:219], v[2:5]
	v_mfma_f32_16x16x32_bf16 v[46:49], v[166:169], v[190:193], v[46:49]
	v_mfma_f32_16x16x32_bf16 v[42:45], v[174:177], v[190:193], v[42:45]
	v_mfma_f32_16x16x32_bf16 v[30:33], v[166:169], v[198:201], v[30:33]
	v_mfma_f32_16x16x32_bf16 v[26:29], v[174:177], v[198:201], v[26:29]
	v_mfma_f32_16x16x32_bf16 v[14:17], v[166:169], v[212:215], v[14:17]
	v_mfma_f32_16x16x32_bf16 v[10:13], v[174:177], v[212:215], v[10:13]
	v_mfma_f32_16x16x32_bf16 v[6:9], v[166:169], v[220:223], v[6:9]
	v_mfma_f32_16x16x32_bf16 v[2:5], v[174:177], v[220:223], v[2:5]
	s_nop 0
	s_barrier
	s_add_i32 s83, s83, 2
	s_add_u32 s55, s55, 0x100
	s_addc_u32 s57, s57, 0
	s_add_u32 s62, s62, 0x100
	s_addc_u32 s63, s63, 0
	s_cmp_gt_u32 s83, 13
	s_cbranch_scc0 .LBB0_945
	s_and_b64 vcc, exec, s[50:51]
	s_cbranch_vccz .LBB0_948
	s_barrier

; #define PG8_STAGE(bufoff, gbase, voff) do { _Pragma("unroll") for (int _i = 0; _i < 2; ++_i) \
;         __builtin_amdgcn_global_load_lds((const unsigned*)((const char*)(gbase) + (voff)[_i]), (LAS unsigned*)(lds + (bufoff) + ldsw + _i * 8192), 16, 0, 0); } while (0)
; #define PG8_LDA(dst, b, h) do { _Pragma("unroll") for (int m = 0; m < 4; ++m) _Pragma("unroll") for (int k = 0; k < 2; ++k) dst[m][k] = *(const LAS bf16x8*)(lds + PG8_SA(b, h) + aoff + m * 2048 + k * 1024); } while (0)
; #define PG8_LDB(dst, b, h) do { _Pragma("unroll") for (int n = 0; n < 2; ++n) _Pragma("unroll") for (int k = 0; k < 2; ++k) dst[n][k] = *(const LAS bf16x8*)(lds + PG8_SB(b, h) + boff + n * 2048 + k * 1024); } while (0)
; #define PG8_MMA(ai, bj, At, Bt) do { __builtin_amdgcn_s_setprio(1); _Pragma("unroll") for (int m = 0; m < 4; ++m) _Pragma("unroll") for (int n = 0; n < 2; ++n) _Pragma("unroll") for (int k = 0; k < 2; ++k) \
;         acc[ai][bj][m][n] = __builtin_amdgcn_mfma_f32_16x16x32_bf16(Bt[n][k], At[m][k], acc[ai][bj][m][n], 0, 0, 0); __builtin_amdgcn_s_setprio(0); } while (0)
; #define PG8_WAIT_V(n) asm volatile("s_waitcnt vmcnt(" #n ")" ::: "memory")
; #define PG8_WAIT_L(n) asm volatile("s_waitcnt lgkmcnt(" #n ")" ::: "memory")
; #define PG8_BAR __builtin_amdgcn_s_barrier()
; #define PG8_SCHED __builtin_amdgcn_sched_barrier(0)
; template <class Epi, class Sched>
; DI void gemm_phase(LAS unsigned char* lds, const int K, const Sched& S, const Epi& E) {
;     ...
;         for (int t = 0; t < nt; t += 2) {
;             const bool last = (t == nt - 2);
;             const char* a1 = cA + (size_t)(t + 1) * kstep;
;             const char* a2 = last ? nA : cA + (size_t)(t + 2) * kstep; const char* b2 = last ? nB : cB + (size_t)(t + 2) * kstep;
;             const char* a3 = a2 + kstep; const char* b3 = b2 + kstep;
;             PG8_LDB(B0, 0, 0); PG8_LDB(B1, 0, 1); PG8_SCHED; PG8_LDA(At, 0, 0); PG8_STAGE(PG8_SA(1, 1), a1 + hstep, voffA);
;             PG8_WAIT_V(8); PG8_WAIT_L(0); PG8_BAR; PG8_MMA(0, 0, At, B0); PG8_MMA(0, 1, At, B1); PG8_BAR; PG8_SCHED;
;             PG8_LDA(At, 0, 1); PG8_STAGE(PG8_SB(0, 0), b2, voffB); PG8_STAGE(PG8_SB(0, 1), b2 + hstep, voffB); PG8_STAGE(PG8_SA(0, 0), a2, voffA);
;             PG8_WAIT_V(8); PG8_WAIT_L(0); PG8_BAR; PG8_MMA(1, 0, At, B0); PG8_MMA(1, 1, At, B1); PG8_BAR; PG8_SCHED;
.LBB0_1086:
	s_add_u32 s48, s68, 0xfffc0080
	s_addc_u32 s49, s69, -1
	s_add_i32 vcc_hi, 0, 0x10000
	s_cmp_eq_u32 vcc_lo, 12
	s_cselect_b32 s73, s65, s49
	s_cselect_b32 s72, s64, s48
	v_add_u32_e32 v145, vcc_hi, v143
	s_cselect_b32 s71, s67, s63
	s_cselect_b32 s70, s66, s61
	s_add_i32 s94, 0, 0x14000
	ds_read_b128 v[146:149], v145
	ds_read_b128 v[150:153], v145 offset:1024
	ds_read_b128 v[154:157], v145 offset:2048
	ds_read_b128 v[158:161], v145 offset:3072
	v_add_u32_e32 v145, s94, v143
	ds_read_b128 v[162:165], v145
	ds_read_b128 v[166:169], v145 offset:1024
	ds_read_b128 v[170:173], v145 offset:2048
	ds_read_b128 v[174:177], v145 offset:3072
	s_nop 0
	s_add_i32 m0, s59, 0xc000
	ds_read_b128 v[182:185], v144
	ds_read_b128 v[190:193], v144 offset:1024
	ds_read_b128 v[194:197], v144 offset:2048
	ds_read_b128 v[198:201], v144 offset:3072
	ds_read_b128 v[202:205], v144 offset:4096
	ds_read_b128 v[212:215], v144 offset:5120
	ds_read_b128 v[216:219], v144 offset:6144
	ds_read_b128 v[220:223], v144 offset:7168
	global_load_lds_dwordx4 v140, s[68:69]
	s_nop 0
	s_add_i32 m0, s59, 0xe000
	s_nop 0
	global_load_lds_dwordx4 v138, s[68:69]
	s_waitcnt vmcnt(8)
	s_waitcnt lgkmcnt(0)
	s_barrier
	s_nop 0
	s_waitcnt lgkmcnt(0)
	v_mfma_f32_16x16x32_bf16 v[126:129], v[146:149], v[182:185], v[126:129]
	v_mfma_f32_16x16x32_bf16 v[122:125], v[154:157], v[182:185], v[122:125]
	v_mfma_f32_16x16x32_bf16 v[118:121], v[146:149], v[194:197], v[118:121]
	v_mfma_f32_16x16x32_bf16 v[114:117], v[154:157], v[194:197], v[114:117]
	v_mfma_f32_16x16x32_bf16 v[102:105], v[146:149], v[202:205], v[102:105]
	v_mfma_f32_16x16x32_bf16 v[98:101], v[154:157], v[202:205], v[98:101]
	v_mfma_f32_16x16x32_bf16 v[86:89], v[146:149], v[216:219], v[86:89]
	v_mfma_f32_16x16x32_bf16 v[82:85], v[154:157], v[216:219], v[82:85]
	v_mfma_f32_16x16x32_bf16 v[126:129], v[150:153], v[190:193], v[126:129]
	v_mfma_f32_16x16x32_bf16 v[122:125], v[158:161], v[190:193], v[122:125]
	v_mfma_f32_16x16x32_bf16 v[118:121], v[150:153], v[198:201], v[118:121]
	v_mfma_f32_16x16x32_bf16 v[114:117], v[158:161], v[198:201], v[114:117]
	v_mfma_f32_16x16x32_bf16 v[102:105], v[150:153], v[212:215], v[102:105]
	v_mfma_f32_16x16x32_bf16 v[98:101], v[158:161], v[212:215], v[98:101]
	v_mfma_f32_16x16x32_bf16 v[86:89], v[150:153], v[220:223], v[86:89]
	v_mfma_f32_16x16x32_bf16 v[82:85], v[158:161], v[220:223], v[82:85]
	s_nop 0
	s_nop 0
	v_mfma_f32_16x16x32_bf16 v[110:113], v[162:165], v[182:185], v[110:113]
	v_mfma_f32_16x16x32_bf16 v[106:109], v[170:173], v[182:185], v[106:109]
	v_mfma_f32_16x16x32_bf16 v[94:97], v[162:165], v[194:197], v[94:97]
	v_mfma_f32_16x16x32_bf16 v[90:93], v[170:173], v[194:197], v[90:93]
	v_mfma_f32_16x16x32_bf16 v[78:81], v[162:165], v[202:205], v[78:81]
	v_mfma_f32_16x16x32_bf16 v[74:77], v[170:173], v[202:205], v[74:77]
	v_mfma_f32_16x16x32_bf16 v[70:73], v[162:165], v[216:219], v[70:73]
	v_mfma_f32_16x16x32_bf16 v[66:69], v[170:173], v[216:219], v[66:69]
	v_mfma_f32_16x16x32_bf16 v[110:113], v[166:169], v[190:193], v[110:113]
	v_mfma_f32_16x16x32_bf16 v[106:109], v[174:177], v[190:193], v[106:109]
	v_mfma_f32_16x16x32_bf16 v[94:97], v[166:169], v[198:201], v[94:97]
	v_mfma_f32_16x16x32_bf16 v[90:93], v[174:177], v[198:201], v[90:93]
	v_mfma_f32_16x16x32_bf16 v[78:81], v[166:169], v[212:215], v[78:81]
	v_mfma_f32_16x16x32_bf16 v[74:77], v[174:177], v[212:215], v[74:77]
	v_mfma_f32_16x16x32_bf16 v[70:73], v[166:169], v[220:223], v[70:73]
	v_mfma_f32_16x16x32_bf16 v[66:69], v[174:177], v[220:223], v[66:69]
	s_nop 0
	s_barrier
	s_add_i32 s48, vcc_hi, s78
	v_lshl_add_u64 v[224:225], s[70:71], 0, v[134:135]
	s_mov_b32 m0, s48
	ds_read_b128 v[182:185], v144 offset:16384
	ds_read_b128 v[190:193], v144 offset:17408
	ds_read_b128 v[194:197], v144 offset:18432
	ds_read_b128 v[198:201], v144 offset:19456
	ds_read_b128 v[202:205], v144 offset:20480
	ds_read_b128 v[212:215], v144 offset:21504
	ds_read_b128 v[216:219], v144 offset:22528
	ds_read_b128 v[220:223], v144 offset:23552
	global_load_lds_dwordx4 v[224:225], off
	s_add_i32 m0, s48, 0x2000
	s_add_u32 s48, s70, 0x40000
	v_lshl_add_u64 v[226:227], s[70:71], 0, v[130:131]
	s_addc_u32 s49, s71, 0
	s_add_i32 s94, s94, s78
	global_load_lds_dwordx4 v[226:227], off
	s_nop 0
	s_mov_b32 m0, s94
	s_nop 0
	global_load_lds_dwordx4 v134, s[48:49]
	s_nop 0
	s_add_i32 m0, s94, 0x2000
	s_nop 0
	global_load_lds_dwordx4 v130, s[48:49]
	s_nop 0
	s_add_u32 s98, s72, s90
	s_addc_u32 s99, s73, s91
	s_mov_b32 m0, s59
	s_nop 0
	global_load_lds_dwordx4 v136, s[72:73]
	s_mov_b32 m0, s80
	s_nop 0
	global_load_lds_dwordx4 v132, s[72:73]
	s_waitcnt vmcnt(8)
	s_waitcnt lgkmcnt(0)
	s_barrier
; #define PG8_STAGE(bufoff, gbase, voff) do { _Pragma("unroll") for (int _i = 0; _i < 2; ++_i) \
;         __builtin_amdgcn_global_load_lds((const unsigned*)((const char*)(gbase) + (voff)[_i]), (LAS unsigned*)(lds + (bufoff) + ldsw + _i * 8192), 16, 0, 0); } while (0)
; #define PG8_LDA(dst, b, h) do { _Pragma("unroll") for (int m = 0; m < 4; ++m) _Pragma("unroll") for (int k = 0; k < 2; ++k) dst[m][k] = *(const LAS bf16x8*)(lds + PG8_SA(b, h) + aoff + m * 2048 + k * 1024); } while (0)
; #define PG8_LDB(dst, b, h) do { _Pragma("unroll") for (int n = 0; n < 2; ++n) _Pragma("unroll") for (int k = 0; k < 2; ++k) dst[n][k] = *(const LAS bf16x8*)(lds + PG8_SB(b, h) + boff + n * 2048 + k * 1024); } while (0)
; #define PG8_MMA(ai, bj, At, Bt) do { __builtin_amdgcn_s_setprio(1); _Pragma("unroll") for (int m = 0; m < 4; ++m) _Pragma("unroll") for (int n = 0; n < 2; ++n) _Pragma("unroll") for (int k = 0; k < 2; ++k) \
;         acc[ai][bj][m][n] = __builtin_amdgcn_mfma_f32_16x16x32_bf16(Bt[n][k], At[m][k], acc[ai][bj][m][n], 0, 0, 0); __builtin_amdgcn_s_setprio(0); } while (0)
; #define PG8_WAIT_V(n) asm volatile("s_waitcnt vmcnt(" #n ")" ::: "memory")
; #define PG8_WAIT_L(n) asm volatile("s_waitcnt lgkmcnt(" #n ")" ::: "memory")
; #define PG8_BAR __builtin_amdgcn_s_barrier()
; #define PG8_SCHED __builtin_amdgcn_sched_barrier(0)
; template <class Epi, class Sched>
; DI void gemm_phase(LAS unsigned char* lds, const int K, const Sched& S, const Epi& E) {
;     ...
;             PG8_WAIT_V(8); PG8_WAIT_L(0); PG8_BAR; PG8_MMA(1, 0, At, B0); PG8_MMA(1, 1, At, B1); PG8_BAR; PG8_SCHED;
;             PG8_LDB(B0, 1, 0); PG8_LDB(B1, 1, 1); PG8_SCHED; PG8_LDA(At, 1, 0); PG8_STAGE(PG8_SA(0, 1), a2 + hstep, voffA);
;             PG8_WAIT_V(8); PG8_WAIT_L(0); PG8_BAR; PG8_MMA(0, 0, At, B0); PG8_MMA(0, 1, At, B1); PG8_BAR; PG8_SCHED;
	s_nop 0
	s_waitcnt lgkmcnt(0)
	v_mfma_f32_16x16x32_bf16 v[62:65], v[146:149], v[182:185], v[62:65]
	v_mfma_f32_16x16x32_bf16 v[58:61], v[154:157], v[182:185], v[58:61]
	v_mfma_f32_16x16x32_bf16 v[54:57], v[146:149], v[194:197], v[54:57]
	v_mfma_f32_16x16x32_bf16 v[50:53], v[154:157], v[194:197], v[50:53]
	v_mfma_f32_16x16x32_bf16 v[38:41], v[146:149], v[202:205], v[38:41]
	v_mfma_f32_16x16x32_bf16 v[34:37], v[154:157], v[202:205], v[34:37]
	v_mfma_f32_16x16x32_bf16 v[22:25], v[146:149], v[216:219], v[22:25]
	v_mfma_f32_16x16x32_bf16 v[18:21], v[154:157], v[216:219], v[18:21]
	v_mfma_f32_16x16x32_bf16 v[62:65], v[150:153], v[190:193], v[62:65]
	v_mfma_f32_16x16x32_bf16 v[58:61], v[158:161], v[190:193], v[58:61]
	v_mfma_f32_16x16x32_bf16 v[54:57], v[150:153], v[198:201], v[54:57]
	v_mfma_f32_16x16x32_bf16 v[50:53], v[158:161], v[198:201], v[50:53]
	v_mfma_f32_16x16x32_bf16 v[38:41], v[150:153], v[212:215], v[38:41]
	v_mfma_f32_16x16x32_bf16 v[34:37], v[158:161], v[212:215], v[34:37]
	v_mfma_f32_16x16x32_bf16 v[22:25], v[150:153], v[220:223], v[22:25]
	v_mfma_f32_16x16x32_bf16 v[18:21], v[158:161], v[220:223], v[18:21]
	s_nop 0
	s_nop 0
	v_mfma_f32_16x16x32_bf16 v[46:49], v[162:165], v[182:185], v[46:49]
	v_mfma_f32_16x16x32_bf16 v[42:45], v[170:173], v[182:185], v[42:45]
	v_mfma_f32_16x16x32_bf16 v[30:33], v[162:165], v[194:197], v[30:33]
	v_mfma_f32_16x16x32_bf16 v[26:29], v[170:173], v[194:197], v[26:29]
	v_mfma_f32_16x16x32_bf16 v[14:17], v[162:165], v[202:205], v[14:17]
	v_mfma_f32_16x16x32_bf16 v[10:13], v[170:173], v[202:205], v[10:13]
	v_mfma_f32_16x16x32_bf16 v[6:9], v[162:165], v[216:219], v[6:9]
	v_mfma_f32_16x16x32_bf16 v[2:5], v[170:173], v[216:219], v[2:5]
	v_mfma_f32_16x16x32_bf16 v[46:49], v[166:169], v[190:193], v[46:49]
	v_mfma_f32_16x16x32_bf16 v[42:45], v[174:177], v[190:193], v[42:45]
	v_mfma_f32_16x16x32_bf16 v[30:33], v[166:169], v[198:201], v[30:33]
	v_mfma_f32_16x16x32_bf16 v[26:29], v[174:177], v[198:201], v[26:29]
	v_mfma_f32_16x16x32_bf16 v[14:17], v[166:169], v[212:215], v[14:17]
	v_mfma_f32_16x16x32_bf16 v[10:13], v[174:177], v[212:215], v[10:13]
	v_mfma_f32_16x16x32_bf16 v[6:9], v[166:169], v[220:223], v[6:9]
	v_mfma_f32_16x16x32_bf16 v[2:5], v[174:177], v[220:223], v[2:5]
	s_nop 0
	s_barrier
	s_add_i32 s94, 0, 0x18000
	v_add_u32_e32 v145, s94, v143
	s_add_i32 vcc_hi, 0, 0x1c000
	ds_read_b128 v[146:149], v145
	ds_read_b128 v[150:153], v145 offset:1024
	ds_read_b128 v[154:157], v145 offset:2048
	ds_read_b128 v[158:161], v145 offset:3072
	v_add_u32_e32 v145, vcc_hi, v143
	ds_read_b128 v[162:165], v145
	ds_read_b128 v[166:169], v145 offset:1024
	ds_read_b128 v[170:173], v145 offset:2048
	ds_read_b128 v[174:177], v145 offset:3072
	s_add_u32 s48, s72, 0x40000
	s_addc_u32 s49, s73, 0
	s_mov_b32 m0, s81
	s_nop 0
	ds_read_b128 v[182:185], v144 offset:32768
	ds_read_b128 v[190:193], v144 offset:33792
	ds_read_b128 v[194:197], v144 offset:34816
	ds_read_b128 v[198:201], v144 offset:35840
	ds_read_b128 v[202:205], v144 offset:36864
	ds_read_b128 v[212:215], v144 offset:37888
	ds_read_b128 v[216:219], v144 offset:38912
	ds_read_b128 v[220:223], v144 offset:39936
	global_load_lds_dwordx4 v136, s[48:49]
	s_nop 0
	s_mov_b32 m0, s83
	s_nop 0
	global_load_lds_dwordx4 v132, s[48:49]
	s_waitcnt vmcnt(8)
	s_waitcnt lgkmcnt(0)
	s_barrier
	s_nop 0
	s_waitcnt lgkmcnt(0)
	v_mfma_f32_16x16x32_bf16 v[126:129], v[146:149], v[182:185], v[126:129]
	v_mfma_f32_16x16x32_bf16 v[122:125], v[154:157], v[182:185], v[122:125]
	v_mfma_f32_16x16x32_bf16 v[118:121], v[146:149], v[194:197], v[118:121]
	v_mfma_f32_16x16x32_bf16 v[114:117], v[154:157], v[194:197], v[114:117]
	v_mfma_f32_16x16x32_bf16 v[102:105], v[146:149], v[202:205], v[102:105]
	v_mfma_f32_16x16x32_bf16 v[98:101], v[154:157], v[202:205], v[98:101]
	v_mfma_f32_16x16x32_bf16 v[86:89], v[146:149], v[216:219], v[86:89]
	v_mfma_f32_16x16x32_bf16 v[82:85], v[154:157], v[216:219], v[82:85]
	v_mfma_f32_16x16x32_bf16 v[126:129], v[150:153], v[190:193], v[126:129]
	v_mfma_f32_16x16x32_bf16 v[122:125], v[158:161], v[190:193], v[122:125]
	v_mfma_f32_16x16x32_bf16 v[118:121], v[150:153], v[198:201], v[118:121]
	v_mfma_f32_16x16x32_bf16 v[114:117], v[158:161], v[198:201], v[114:117]
	v_mfma_f32_16x16x32_bf16 v[102:105], v[150:153], v[212:215], v[102:105]
	v_mfma_f32_16x16x32_bf16 v[98:101], v[158:161], v[212:215], v[98:101]
	v_mfma_f32_16x16x32_bf16 v[86:89], v[150:153], v[220:223], v[86:89]
	v_mfma_f32_16x16x32_bf16 v[82:85], v[158:161], v[220:223], v[82:85]
	s_nop 0
	s_nop 0
	v_mfma_f32_16x16x32_bf16 v[110:113], v[162:165], v[182:185], v[110:113]
	v_mfma_f32_16x16x32_bf16 v[106:109], v[170:173], v[182:185], v[106:109]
	v_mfma_f32_16x16x32_bf16 v[94:97], v[162:165], v[194:197], v[94:97]
	v_mfma_f32_16x16x32_bf16 v[90:93], v[170:173], v[194:197], v[90:93]
	v_mfma_f32_16x16x32_bf16 v[78:81], v[162:165], v[202:205], v[78:81]
	v_mfma_f32_16x16x32_bf16 v[74:77], v[170:173], v[202:205], v[74:77]
	v_mfma_f32_16x16x32_bf16 v[70:73], v[162:165], v[216:219], v[70:73]
	v_mfma_f32_16x16x32_bf16 v[66:69], v[170:173], v[216:219], v[66:69]
	v_mfma_f32_16x16x32_bf16 v[110:113], v[166:169], v[190:193], v[110:113]
	v_mfma_f32_16x16x32_bf16 v[106:109], v[174:177], v[190:193], v[106:109]
	v_mfma_f32_16x16x32_bf16 v[94:97], v[166:169], v[198:201], v[94:97]
	v_mfma_f32_16x16x32_bf16 v[90:93], v[174:177], v[198:201], v[90:93]
	v_mfma_f32_16x16x32_bf16 v[78:81], v[166:169], v[212:215], v[78:81]
	v_mfma_f32_16x16x32_bf16 v[74:77], v[174:177], v[212:215], v[74:77]
	v_mfma_f32_16x16x32_bf16 v[70:73], v[166:169], v[220:223], v[70:73]
	v_mfma_f32_16x16x32_bf16 v[66:69], v[174:177], v[220:223], v[66:69]
	s_nop 0
	s_barrier
; #define PG8_STAGE(bufoff, gbase, voff) do { _Pragma("unroll") for (int _i = 0; _i < 2; ++_i) \
;         __builtin_amdgcn_global_load_lds((const unsigned*)((const char*)(gbase) + (voff)[_i]), (LAS unsigned*)(lds + (bufoff) + ldsw + _i * 8192), 16, 0, 0); } while (0)
; #define PG8_LDA(dst, b, h) do { _Pragma("unroll") for (int m = 0; m < 4; ++m) _Pragma("unroll") for (int k = 0; k < 2; ++k) dst[m][k] = *(const LAS bf16x8*)(lds + PG8_SA(b, h) + aoff + m * 2048 + k * 1024); } while (0)
; #define PG8_MMA(ai, bj, At, Bt) do { __builtin_amdgcn_s_setprio(1); _Pragma("unroll") for (int m = 0; m < 4; ++m) _Pragma("unroll") for (int n = 0; n < 2; ++n) _Pragma("unroll") for (int k = 0; k < 2; ++k) \
;         acc[ai][bj][m][n] = __builtin_amdgcn_mfma_f32_16x16x32_bf16(Bt[n][k], At[m][k], acc[ai][bj][m][n], 0, 0, 0); __builtin_amdgcn_s_setprio(0); } while (0)
; #define PG8_WAIT_V(n) asm volatile("s_waitcnt vmcnt(" #n ")" ::: "memory")
; #define PG8_WAIT_L(n) asm volatile("s_waitcnt lgkmcnt(" #n ")" ::: "memory")
; #define PG8_BAR __builtin_amdgcn_s_barrier()
; #define PG8_SCHED __builtin_amdgcn_sched_barrier(0)
; template <class Epi, class Sched>
; DI void gemm_phase(LAS unsigned char* lds, const int K, const Sched& S, const Epi& E) {
;     ...
;             PG8_LDA(At, 1, 1); PG8_STAGE(PG8_SB(1, 0), b3, voffB); PG8_STAGE(PG8_SB(1, 1), b3 + hstep, voffB); PG8_STAGE(PG8_SA(1, 0), a3, voffA);
;             PG8_WAIT_V(8); PG8_WAIT_L(0); PG8_BAR; PG8_MMA(1, 0, At, B0); PG8_MMA(1, 1, At, B1); PG8_BAR; PG8_SCHED;
;         }
;         if (wr == 0) PG8_BAR;
	s_add_i32 s48, s94, s78
	v_lshl_add_u64 v[224:225], v[224:225], 0, s[90:91]
	s_mov_b32 m0, s48
	ds_read_b128 v[182:185], v144 offset:49152
	ds_read_b128 v[190:193], v144 offset:50176
	ds_read_b128 v[194:197], v144 offset:51200
	ds_read_b128 v[198:201], v144 offset:52224
	ds_read_b128 v[202:205], v144 offset:53248
	ds_read_b128 v[212:215], v144 offset:54272
	ds_read_b128 v[216:219], v144 offset:55296
	ds_read_b128 v[220:223], v144 offset:56320
	global_load_lds_dwordx4 v[224:225], off
	s_add_i32 m0, s48, 0x2000
	s_add_u32 s48, s70, 0x40080
	v_lshl_add_u64 v[224:225], v[226:227], 0, s[90:91]
	s_addc_u32 s49, s71, 0
	s_add_i32 s70, vcc_hi, s78
	global_load_lds_dwordx4 v[224:225], off
	s_nop 0
	s_mov_b32 m0, s70
	s_nop 0
	global_load_lds_dwordx4 v134, s[48:49]
	s_nop 0
	s_add_i32 m0, s70, 0x2000
	s_nop 0
	global_load_lds_dwordx4 v130, s[48:49]
	s_nop 0
	s_mov_b32 m0, s95
	s_nop 0
	global_load_lds_dwordx4 v136, s[98:99]
	s_nop 0
	s_mov_b32 m0, s42
	s_nop 0
	global_load_lds_dwordx4 v132, s[98:99]
	s_waitcnt vmcnt(8)
	s_waitcnt lgkmcnt(0)
	s_barrier
	s_nop 0
	s_waitcnt lgkmcnt(0)
	v_mfma_f32_16x16x32_bf16 v[62:65], v[146:149], v[182:185], v[62:65]
	v_mfma_f32_16x16x32_bf16 v[58:61], v[154:157], v[182:185], v[58:61]
	v_mfma_f32_16x16x32_bf16 v[54:57], v[146:149], v[194:197], v[54:57]
	v_mfma_f32_16x16x32_bf16 v[50:53], v[154:157], v[194:197], v[50:53]
	v_mfma_f32_16x16x32_bf16 v[38:41], v[146:149], v[202:205], v[38:41]
	v_mfma_f32_16x16x32_bf16 v[34:37], v[154:157], v[202:205], v[34:37]
	v_mfma_f32_16x16x32_bf16 v[22:25], v[146:149], v[216:219], v[22:25]
	v_mfma_f32_16x16x32_bf16 v[18:21], v[154:157], v[216:219], v[18:21]
	v_mfma_f32_16x16x32_bf16 v[62:65], v[150:153], v[190:193], v[62:65]
	v_mfma_f32_16x16x32_bf16 v[58:61], v[158:161], v[190:193], v[58:61]
	v_mfma_f32_16x16x32_bf16 v[54:57], v[150:153], v[198:201], v[54:57]
	v_mfma_f32_16x16x32_bf16 v[50:53], v[158:161], v[198:201], v[50:53]
	v_mfma_f32_16x16x32_bf16 v[38:41], v[150:153], v[212:215], v[38:41]
	v_mfma_f32_16x16x32_bf16 v[34:37], v[158:161], v[212:215], v[34:37]
	v_mfma_f32_16x16x32_bf16 v[22:25], v[150:153], v[220:223], v[22:25]
	v_mfma_f32_16x16x32_bf16 v[18:21], v[158:161], v[220:223], v[18:21]
	s_nop 0
	s_nop 0
	v_mfma_f32_16x16x32_bf16 v[46:49], v[162:165], v[182:185], v[46:49]
	v_mfma_f32_16x16x32_bf16 v[42:45], v[170:173], v[182:185], v[42:45]
	v_mfma_f32_16x16x32_bf16 v[30:33], v[162:165], v[194:197], v[30:33]
	v_mfma_f32_16x16x32_bf16 v[26:29], v[170:173], v[194:197], v[26:29]
	v_mfma_f32_16x16x32_bf16 v[14:17], v[162:165], v[202:205], v[14:17]
	v_mfma_f32_16x16x32_bf16 v[10:13], v[170:173], v[202:205], v[10:13]
	v_mfma_f32_16x16x32_bf16 v[6:9], v[162:165], v[216:219], v[6:9]
	v_mfma_f32_16x16x32_bf16 v[2:5], v[170:173], v[216:219], v[2:5]
	v_mfma_f32_16x16x32_bf16 v[46:49], v[166:169], v[190:193], v[46:49]
	v_mfma_f32_16x16x32_bf16 v[42:45], v[174:177], v[190:193], v[42:45]
	v_mfma_f32_16x16x32_bf16 v[30:33], v[166:169], v[198:201], v[30:33]
	v_mfma_f32_16x16x32_bf16 v[26:29], v[174:177], v[198:201], v[26:29]
	v_mfma_f32_16x16x32_bf16 v[14:17], v[166:169], v[212:215], v[14:17]
	v_mfma_f32_16x16x32_bf16 v[10:13], v[174:177], v[212:215], v[10:13]
	v_mfma_f32_16x16x32_bf16 v[6:9], v[166:169], v[220:223], v[6:9]
	v_mfma_f32_16x16x32_bf16 v[2:5], v[174:177], v[220:223], v[2:5]
	s_nop 0
	s_barrier
	s_add_i32 vcc_lo, vcc_lo, 2
	s_add_u32 s61, s61, 0x100
	s_addc_u32 s63, s63, 0
	s_add_u32 s68, s68, 0x100
	s_addc_u32 s69, s69, 0
	s_cmp_gt_u32 vcc_lo, 13
	s_cbranch_scc0 .LBB0_1086
	s_and_b64 vcc, exec, s[56:57]
	s_cbranch_vccz .LBB0_1089
	s_barrier

; #define PG8_STAGE(bufoff, gbase, voff) do { _Pragma("unroll") for (int _i = 0; _i < 2; ++_i) \
;         __builtin_amdgcn_global_load_lds((const unsigned*)((const char*)(gbase) + (voff)[_i]), (LAS unsigned*)(lds + (bufoff) + ldsw + _i * 8192), 16, 0, 0); } while (0)
; #define PG8_LDA(dst, b, h) do { _Pragma("unroll") for (int m = 0; m < 4; ++m) _Pragma("unroll") for (int k = 0; k < 2; ++k) dst[m][k] = *(const LAS bf16x8*)(lds + PG8_SA(b, h) + aoff + m * 2048 + k * 1024); } while (0)
; #define PG8_LDB(dst, b, h) do { _Pragma("unroll") for (int n = 0; n < 2; ++n) _Pragma("unroll") for (int k = 0; k < 2; ++k) dst[n][k] = *(const LAS bf16x8*)(lds + PG8_SB(b, h) + boff + n * 2048 + k * 1024); } while (0)
; #define PG8_MMA(ai, bj, At, Bt) do { __builtin_amdgcn_s_setprio(1); _Pragma("unroll") for (int m = 0; m < 4; ++m) _Pragma("unroll") for (int n = 0; n < 2; ++n) _Pragma("unroll") for (int k = 0; k < 2; ++k) \
;         acc[ai][bj][m][n] = __builtin_amdgcn_mfma_f32_16x16x32_bf16(Bt[n][k], At[m][k], acc[ai][bj][m][n], 0, 0, 0); __builtin_amdgcn_s_setprio(0); } while (0)
; #define PG8_WAIT_V(n) asm volatile("s_waitcnt vmcnt(" #n ")" ::: "memory")
; #define PG8_WAIT_L(n) asm volatile("s_waitcnt lgkmcnt(" #n ")" ::: "memory")
; #define PG8_BAR __builtin_amdgcn_s_barrier()
; #define PG8_SCHED __builtin_amdgcn_sched_barrier(0)
; template <class Epi, class Sched>
; DI void gemm_phase(LAS unsigned char* lds, const int K, const Sched& S, const Epi& E) {
;     ...
;         for (int t = 0; t < nt; t += 2) {
;             const bool last = (t == nt - 2);
;             const char* a1 = cA + (size_t)(t + 1) * kstep;
;             const char* a2 = last ? nA : cA + (size_t)(t + 2) * kstep; const char* b2 = last ? nB : cB + (size_t)(t + 2) * kstep;
;             const char* a3 = a2 + kstep; const char* b3 = b2 + kstep;
;             PG8_LDB(B0, 0, 0); PG8_LDB(B1, 0, 1); PG8_SCHED; PG8_LDA(At, 0, 0); PG8_STAGE(PG8_SA(1, 1), a1 + hstep, voffA);
;             PG8_WAIT_V(8); PG8_WAIT_L(0); PG8_BAR; PG8_MMA(0, 0, At, B0); PG8_MMA(0, 1, At, B1); PG8_BAR; PG8_SCHED;
;             PG8_LDA(At, 0, 1); PG8_STAGE(PG8_SB(0, 0), b2, voffB); PG8_STAGE(PG8_SB(0, 1), b2 + hstep, voffB); PG8_STAGE(PG8_SA(0, 0), a2, voffA);
;             PG8_WAIT_V(8); PG8_WAIT_L(0); PG8_BAR; PG8_MMA(1, 0, At, B0); PG8_MMA(1, 1, At, B1); PG8_BAR; PG8_SCHED;
.LBB0_1204:
	s_add_u32 s60, s58, 0x100
	s_addc_u32 s61, s59, 0
	s_add_i32 s48, 0, 0x10000
	s_cmp_eq_u32 s85, 40
	s_cselect_b32 s65, s55, s61
	s_cselect_b32 s64, s54, s60
	v_add_u32_e32 v145, s48, v143
	s_cselect_b32 s63, s57, s84
	s_cselect_b32 s62, s56, s83
	s_add_i32 s86, 0, 0x14000
	ds_read_b128 v[146:149], v145
	ds_read_b128 v[150:153], v145 offset:1024
	ds_read_b128 v[154:157], v145 offset:2048
	ds_read_b128 v[158:161], v145 offset:3072
	v_add_u32_e32 v145, s86, v143
	ds_read_b128 v[162:165], v145
	ds_read_b128 v[166:169], v145 offset:1024
	ds_read_b128 v[170:173], v145 offset:2048
	ds_read_b128 v[174:177], v145 offset:3072
	s_nop 0
	s_add_i32 m0, s71, 0xc000
	ds_read_b128 v[182:185], v144
	ds_read_b128 v[190:193], v144 offset:1024
	ds_read_b128 v[194:197], v144 offset:2048
	ds_read_b128 v[198:201], v144 offset:3072
	ds_read_b128 v[202:205], v144 offset:4096
	ds_read_b128 v[212:215], v144 offset:5120
	ds_read_b128 v[216:219], v144 offset:6144
	ds_read_b128 v[220:223], v144 offset:7168
	global_load_lds_dwordx4 v140, s[58:59]
	s_nop 0
	s_add_i32 m0, s71, 0xe000
	s_nop 0
	global_load_lds_dwordx4 v138, s[58:59]
	s_waitcnt vmcnt(8)
	s_waitcnt lgkmcnt(0)
	s_barrier
	s_nop 0
	s_waitcnt lgkmcnt(0)
	v_mfma_f32_16x16x32_bf16 v[126:129], v[146:149], v[182:185], v[126:129]
	v_mfma_f32_16x16x32_bf16 v[122:125], v[154:157], v[182:185], v[122:125]
	v_mfma_f32_16x16x32_bf16 v[118:121], v[146:149], v[194:197], v[118:121]
	v_mfma_f32_16x16x32_bf16 v[114:117], v[154:157], v[194:197], v[114:117]
	v_mfma_f32_16x16x32_bf16 v[102:105], v[146:149], v[202:205], v[102:105]
	v_mfma_f32_16x16x32_bf16 v[98:101], v[154:157], v[202:205], v[98:101]
	v_mfma_f32_16x16x32_bf16 v[86:89], v[146:149], v[216:219], v[86:89]
	v_mfma_f32_16x16x32_bf16 v[82:85], v[154:157], v[216:219], v[82:85]
	v_mfma_f32_16x16x32_bf16 v[126:129], v[150:153], v[190:193], v[126:129]
	v_mfma_f32_16x16x32_bf16 v[122:125], v[158:161], v[190:193], v[122:125]
	v_mfma_f32_16x16x32_bf16 v[118:121], v[150:153], v[198:201], v[118:121]
	v_mfma_f32_16x16x32_bf16 v[114:117], v[158:161], v[198:201], v[114:117]
	v_mfma_f32_16x16x32_bf16 v[102:105], v[150:153], v[212:215], v[102:105]
	v_mfma_f32_16x16x32_bf16 v[98:101], v[158:161], v[212:215], v[98:101]
	v_mfma_f32_16x16x32_bf16 v[86:89], v[150:153], v[220:223], v[86:89]
	v_mfma_f32_16x16x32_bf16 v[82:85], v[158:161], v[220:223], v[82:85]
	s_nop 0
	s_nop 0
	v_mfma_f32_16x16x32_bf16 v[110:113], v[162:165], v[182:185], v[110:113]
	v_mfma_f32_16x16x32_bf16 v[106:109], v[170:173], v[182:185], v[106:109]
	v_mfma_f32_16x16x32_bf16 v[94:97], v[162:165], v[194:197], v[94:97]
	v_mfma_f32_16x16x32_bf16 v[90:93], v[170:173], v[194:197], v[90:93]
	v_mfma_f32_16x16x32_bf16 v[78:81], v[162:165], v[202:205], v[78:81]
	v_mfma_f32_16x16x32_bf16 v[74:77], v[170:173], v[202:205], v[74:77]
	v_mfma_f32_16x16x32_bf16 v[70:73], v[162:165], v[216:219], v[70:73]
	v_mfma_f32_16x16x32_bf16 v[66:69], v[170:173], v[216:219], v[66:69]
	v_mfma_f32_16x16x32_bf16 v[110:113], v[166:169], v[190:193], v[110:113]
	v_mfma_f32_16x16x32_bf16 v[106:109], v[174:177], v[190:193], v[106:109]
	v_mfma_f32_16x16x32_bf16 v[94:97], v[166:169], v[198:201], v[94:97]
	v_mfma_f32_16x16x32_bf16 v[90:93], v[174:177], v[198:201], v[90:93]
	v_mfma_f32_16x16x32_bf16 v[78:81], v[166:169], v[212:215], v[78:81]
	v_mfma_f32_16x16x32_bf16 v[74:77], v[174:177], v[212:215], v[74:77]
	v_mfma_f32_16x16x32_bf16 v[70:73], v[166:169], v[220:223], v[70:73]
	v_mfma_f32_16x16x32_bf16 v[66:69], v[174:177], v[220:223], v[66:69]
	s_nop 0
	s_barrier
	s_add_i32 s48, s48, s69
	v_lshl_add_u64 v[224:225], s[62:63], 0, v[134:135]
	s_mov_b32 m0, s48
	ds_read_b128 v[182:185], v144 offset:16384
	ds_read_b128 v[190:193], v144 offset:17408
	ds_read_b128 v[194:197], v144 offset:18432
	ds_read_b128 v[198:201], v144 offset:19456
	ds_read_b128 v[202:205], v144 offset:20480
	ds_read_b128 v[212:215], v144 offset:21504
	ds_read_b128 v[216:219], v144 offset:22528
	ds_read_b128 v[220:223], v144 offset:23552
	global_load_lds_dwordx4 v[224:225], off
	s_add_i32 m0, s48, 0x2000
	s_add_u32 s48, s62, 0xb0000
	v_lshl_add_u64 v[226:227], s[62:63], 0, v[130:131]
	s_addc_u32 s49, s63, 0
	s_add_i32 s58, s86, s69
	global_load_lds_dwordx4 v[226:227], off
	s_nop 0
	s_mov_b32 m0, s58
	s_nop 0
	global_load_lds_dwordx4 v134, s[48:49]
	s_nop 0
	s_add_i32 m0, s58, 0x2000
	s_nop 0
	global_load_lds_dwordx4 v130, s[48:49]
	s_nop 0
	s_add_u32 s98, s64, s90
	s_addc_u32 s99, s65, s91
	s_mov_b32 m0, s71
	s_nop 0
	global_load_lds_dwordx4 v136, s[64:65]
	s_mov_b32 m0, s72
	s_nop 0
	global_load_lds_dwordx4 v132, s[64:65]
	s_waitcnt vmcnt(8)
	s_waitcnt lgkmcnt(0)
	s_barrier
; #define PG8_STAGE(bufoff, gbase, voff) do { _Pragma("unroll") for (int _i = 0; _i < 2; ++_i) \
;         __builtin_amdgcn_global_load_lds((const unsigned*)((const char*)(gbase) + (voff)[_i]), (LAS unsigned*)(lds + (bufoff) + ldsw + _i * 8192), 16, 0, 0); } while (0)
; #define PG8_LDA(dst, b, h) do { _Pragma("unroll") for (int m = 0; m < 4; ++m) _Pragma("unroll") for (int k = 0; k < 2; ++k) dst[m][k] = *(const LAS bf16x8*)(lds + PG8_SA(b, h) + aoff + m * 2048 + k * 1024); } while (0)
; #define PG8_LDB(dst, b, h) do { _Pragma("unroll") for (int n = 0; n < 2; ++n) _Pragma("unroll") for (int k = 0; k < 2; ++k) dst[n][k] = *(const LAS bf16x8*)(lds + PG8_SB(b, h) + boff + n * 2048 + k * 1024); } while (0)
; #define PG8_MMA(ai, bj, At, Bt) do { __builtin_amdgcn_s_setprio(1); _Pragma("unroll") for (int m = 0; m < 4; ++m) _Pragma("unroll") for (int n = 0; n < 2; ++n) _Pragma("unroll") for (int k = 0; k < 2; ++k) \
;         acc[ai][bj][m][n] = __builtin_amdgcn_mfma_f32_16x16x32_bf16(Bt[n][k], At[m][k], acc[ai][bj][m][n], 0, 0, 0); __builtin_amdgcn_s_setprio(0); } while (0)
; #define PG8_WAIT_V(n) asm volatile("s_waitcnt vmcnt(" #n ")" ::: "memory")
; #define PG8_WAIT_L(n) asm volatile("s_waitcnt lgkmcnt(" #n ")" ::: "memory")
; #define PG8_BAR __builtin_amdgcn_s_barrier()
; #define PG8_SCHED __builtin_amdgcn_sched_barrier(0)
; template <class Epi, class Sched>
; DI void gemm_phase(LAS unsigned char* lds, const int K, const Sched& S, const Epi& E) {
;     ...
;             PG8_WAIT_V(8); PG8_WAIT_L(0); PG8_BAR; PG8_MMA(1, 0, At, B0); PG8_MMA(1, 1, At, B1); PG8_BAR; PG8_SCHED;
;             PG8_LDB(B0, 1, 0); PG8_LDB(B1, 1, 1); PG8_SCHED; PG8_LDA(At, 1, 0); PG8_STAGE(PG8_SA(0, 1), a2 + hstep, voffA);
;             PG8_WAIT_V(8); PG8_WAIT_L(0); PG8_BAR; PG8_MMA(0, 0, At, B0); PG8_MMA(0, 1, At, B1); PG8_BAR; PG8_SCHED;
	s_nop 0
	s_waitcnt lgkmcnt(0)
	v_mfma_f32_16x16x32_bf16 v[62:65], v[146:149], v[182:185], v[62:65]
	v_mfma_f32_16x16x32_bf16 v[58:61], v[154:157], v[182:185], v[58:61]
	v_mfma_f32_16x16x32_bf16 v[54:57], v[146:149], v[194:197], v[54:57]
	v_mfma_f32_16x16x32_bf16 v[50:53], v[154:157], v[194:197], v[50:53]
	v_mfma_f32_16x16x32_bf16 v[38:41], v[146:149], v[202:205], v[38:41]
	v_mfma_f32_16x16x32_bf16 v[34:37], v[154:157], v[202:205], v[34:37]
	v_mfma_f32_16x16x32_bf16 v[22:25], v[146:149], v[216:219], v[22:25]
	v_mfma_f32_16x16x32_bf16 v[18:21], v[154:157], v[216:219], v[18:21]
	v_mfma_f32_16x16x32_bf16 v[62:65], v[150:153], v[190:193], v[62:65]
	v_mfma_f32_16x16x32_bf16 v[58:61], v[158:161], v[190:193], v[58:61]
	v_mfma_f32_16x16x32_bf16 v[54:57], v[150:153], v[198:201], v[54:57]
	v_mfma_f32_16x16x32_bf16 v[50:53], v[158:161], v[198:201], v[50:53]
	v_mfma_f32_16x16x32_bf16 v[38:41], v[150:153], v[212:215], v[38:41]
	v_mfma_f32_16x16x32_bf16 v[34:37], v[158:161], v[212:215], v[34:37]
	v_mfma_f32_16x16x32_bf16 v[22:25], v[150:153], v[220:223], v[22:25]
	v_mfma_f32_16x16x32_bf16 v[18:21], v[158:161], v[220:223], v[18:21]
	s_nop 0
	s_nop 0
	v_mfma_f32_16x16x32_bf16 v[46:49], v[162:165], v[182:185], v[46:49]
	v_mfma_f32_16x16x32_bf16 v[42:45], v[170:173], v[182:185], v[42:45]
	v_mfma_f32_16x16x32_bf16 v[30:33], v[162:165], v[194:197], v[30:33]
	v_mfma_f32_16x16x32_bf16 v[26:29], v[170:173], v[194:197], v[26:29]
	v_mfma_f32_16x16x32_bf16 v[14:17], v[162:165], v[202:205], v[14:17]
	v_mfma_f32_16x16x32_bf16 v[10:13], v[170:173], v[202:205], v[10:13]
	v_mfma_f32_16x16x32_bf16 v[6:9], v[162:165], v[216:219], v[6:9]
	v_mfma_f32_16x16x32_bf16 v[2:5], v[170:173], v[216:219], v[2:5]
	v_mfma_f32_16x16x32_bf16 v[46:49], v[166:169], v[190:193], v[46:49]
	v_mfma_f32_16x16x32_bf16 v[42:45], v[174:177], v[190:193], v[42:45]
	v_mfma_f32_16x16x32_bf16 v[30:33], v[166:169], v[198:201], v[30:33]
	v_mfma_f32_16x16x32_bf16 v[26:29], v[174:177], v[198:201], v[26:29]
	v_mfma_f32_16x16x32_bf16 v[14:17], v[166:169], v[212:215], v[14:17]
	v_mfma_f32_16x16x32_bf16 v[10:13], v[174:177], v[212:215], v[10:13]
	v_mfma_f32_16x16x32_bf16 v[6:9], v[166:169], v[220:223], v[6:9]
	v_mfma_f32_16x16x32_bf16 v[2:5], v[174:177], v[220:223], v[2:5]
	s_nop 0
	s_barrier
	s_add_i32 s58, 0, 0x18000
	v_add_u32_e32 v145, s58, v143
	s_add_i32 s59, 0, 0x1c000
	ds_read_b128 v[146:149], v145
	ds_read_b128 v[150:153], v145 offset:1024
	ds_read_b128 v[154:157], v145 offset:2048
	ds_read_b128 v[158:161], v145 offset:3072
	v_add_u32_e32 v145, s59, v143
	ds_read_b128 v[162:165], v145
	ds_read_b128 v[166:169], v145 offset:1024
	ds_read_b128 v[170:173], v145 offset:2048
	ds_read_b128 v[174:177], v145 offset:3072
	s_add_u32 s48, s64, 0xb0000
	s_addc_u32 s49, s65, 0
	s_mov_b32 m0, s73
	s_nop 0
	ds_read_b128 v[182:185], v144 offset:32768
	ds_read_b128 v[190:193], v144 offset:33792
	ds_read_b128 v[194:197], v144 offset:34816
	ds_read_b128 v[198:201], v144 offset:35840
	ds_read_b128 v[202:205], v144 offset:36864
	ds_read_b128 v[212:215], v144 offset:37888
	ds_read_b128 v[216:219], v144 offset:38912
	ds_read_b128 v[220:223], v144 offset:39936
	global_load_lds_dwordx4 v136, s[48:49]
	s_nop 0
	s_mov_b32 m0, s74
	s_nop 0
	global_load_lds_dwordx4 v132, s[48:49]
	s_waitcnt vmcnt(8)
	s_waitcnt lgkmcnt(0)
	s_barrier
	s_nop 0
	s_waitcnt lgkmcnt(0)
	v_mfma_f32_16x16x32_bf16 v[126:129], v[146:149], v[182:185], v[126:129]
	v_mfma_f32_16x16x32_bf16 v[122:125], v[154:157], v[182:185], v[122:125]
	v_mfma_f32_16x16x32_bf16 v[118:121], v[146:149], v[194:197], v[118:121]
	v_mfma_f32_16x16x32_bf16 v[114:117], v[154:157], v[194:197], v[114:117]
	v_mfma_f32_16x16x32_bf16 v[102:105], v[146:149], v[202:205], v[102:105]
	v_mfma_f32_16x16x32_bf16 v[98:101], v[154:157], v[202:205], v[98:101]
	v_mfma_f32_16x16x32_bf16 v[86:89], v[146:149], v[216:219], v[86:89]
	v_mfma_f32_16x16x32_bf16 v[82:85], v[154:157], v[216:219], v[82:85]
	v_mfma_f32_16x16x32_bf16 v[126:129], v[150:153], v[190:193], v[126:129]
	v_mfma_f32_16x16x32_bf16 v[122:125], v[158:161], v[190:193], v[122:125]
	v_mfma_f32_16x16x32_bf16 v[118:121], v[150:153], v[198:201], v[118:121]
	v_mfma_f32_16x16x32_bf16 v[114:117], v[158:161], v[198:201], v[114:117]
	v_mfma_f32_16x16x32_bf16 v[102:105], v[150:153], v[212:215], v[102:105]
	v_mfma_f32_16x16x32_bf16 v[98:101], v[158:161], v[212:215], v[98:101]
	v_mfma_f32_16x16x32_bf16 v[86:89], v[150:153], v[220:223], v[86:89]
	v_mfma_f32_16x16x32_bf16 v[82:85], v[158:161], v[220:223], v[82:85]
	s_nop 0
	s_nop 0
	v_mfma_f32_16x16x32_bf16 v[110:113], v[162:165], v[182:185], v[110:113]
	v_mfma_f32_16x16x32_bf16 v[106:109], v[170:173], v[182:185], v[106:109]
	v_mfma_f32_16x16x32_bf16 v[94:97], v[162:165], v[194:197], v[94:97]
	v_mfma_f32_16x16x32_bf16 v[90:93], v[170:173], v[194:197], v[90:93]
	v_mfma_f32_16x16x32_bf16 v[78:81], v[162:165], v[202:205], v[78:81]
	v_mfma_f32_16x16x32_bf16 v[74:77], v[170:173], v[202:205], v[74:77]
	v_mfma_f32_16x16x32_bf16 v[70:73], v[162:165], v[216:219], v[70:73]
	v_mfma_f32_16x16x32_bf16 v[66:69], v[170:173], v[216:219], v[66:69]
	v_mfma_f32_16x16x32_bf16 v[110:113], v[166:169], v[190:193], v[110:113]
	v_mfma_f32_16x16x32_bf16 v[106:109], v[174:177], v[190:193], v[106:109]
	v_mfma_f32_16x16x32_bf16 v[94:97], v[166:169], v[198:201], v[94:97]
	v_mfma_f32_16x16x32_bf16 v[90:93], v[174:177], v[198:201], v[90:93]
	v_mfma_f32_16x16x32_bf16 v[78:81], v[166:169], v[212:215], v[78:81]
	v_mfma_f32_16x16x32_bf16 v[74:77], v[174:177], v[212:215], v[74:77]
	v_mfma_f32_16x16x32_bf16 v[70:73], v[166:169], v[220:223], v[70:73]
	v_mfma_f32_16x16x32_bf16 v[66:69], v[174:177], v[220:223], v[66:69]
	s_nop 0
	s_barrier
; #define PG8_STAGE(bufoff, gbase, voff) do { _Pragma("unroll") for (int _i = 0; _i < 2; ++_i) \
;         __builtin_amdgcn_global_load_lds((const unsigned*)((const char*)(gbase) + (voff)[_i]), (LAS unsigned*)(lds + (bufoff) + ldsw + _i * 8192), 16, 0, 0); } while (0)
; #define PG8_LDA(dst, b, h) do { _Pragma("unroll") for (int m = 0; m < 4; ++m) _Pragma("unroll") for (int k = 0; k < 2; ++k) dst[m][k] = *(const LAS bf16x8*)(lds + PG8_SA(b, h) + aoff + m * 2048 + k * 1024); } while (0)
; #define PG8_MMA(ai, bj, At, Bt) do { __builtin_amdgcn_s_setprio(1); _Pragma("unroll") for (int m = 0; m < 4; ++m) _Pragma("unroll") for (int n = 0; n < 2; ++n) _Pragma("unroll") for (int k = 0; k < 2; ++k) \
;         acc[ai][bj][m][n] = __builtin_amdgcn_mfma_f32_16x16x32_bf16(Bt[n][k], At[m][k], acc[ai][bj][m][n], 0, 0, 0); __builtin_amdgcn_s_setprio(0); } while (0)
; #define PG8_WAIT_V(n) asm volatile("s_waitcnt vmcnt(" #n ")" ::: "memory")
; #define PG8_WAIT_L(n) asm volatile("s_waitcnt lgkmcnt(" #n ")" ::: "memory")
; #define PG8_BAR __builtin_amdgcn_s_barrier()
; #define PG8_SCHED __builtin_amdgcn_sched_barrier(0)
; template <class Epi, class Sched>
; DI void gemm_phase(LAS unsigned char* lds, const int K, const Sched& S, const Epi& E) {
;     ...
;             PG8_LDA(At, 1, 1); PG8_STAGE(PG8_SB(1, 0), b3, voffB); PG8_STAGE(PG8_SB(1, 1), b3 + hstep, voffB); PG8_STAGE(PG8_SA(1, 0), a3, voffA);
;             PG8_WAIT_V(8); PG8_WAIT_L(0); PG8_BAR; PG8_MMA(1, 0, At, B0); PG8_MMA(1, 1, At, B1); PG8_BAR; PG8_SCHED;
;         }
;         if (wr == 0) PG8_BAR;
	s_add_i32 s48, s58, s69
	v_lshl_add_u64 v[224:225], v[224:225], 0, s[90:91]
	s_mov_b32 m0, s48
	ds_read_b128 v[182:185], v144 offset:49152
	ds_read_b128 v[190:193], v144 offset:50176
	ds_read_b128 v[194:197], v144 offset:51200
	ds_read_b128 v[198:201], v144 offset:52224
	ds_read_b128 v[202:205], v144 offset:53248
	ds_read_b128 v[212:215], v144 offset:54272
	ds_read_b128 v[216:219], v144 offset:55296
	ds_read_b128 v[220:223], v144 offset:56320
	global_load_lds_dwordx4 v[224:225], off
	s_add_i32 m0, s48, 0x2000
	s_add_u32 s48, s62, 0xb0080
	v_lshl_add_u64 v[224:225], v[226:227], 0, s[90:91]
	s_addc_u32 s49, s63, 0
	s_add_i32 s58, s59, s69
	global_load_lds_dwordx4 v[224:225], off
	s_nop 0
	s_mov_b32 m0, s58
	s_nop 0
	global_load_lds_dwordx4 v134, s[48:49]
	s_nop 0
	s_add_i32 m0, s58, 0x2000
	s_nop 0
	global_load_lds_dwordx4 v130, s[48:49]
	s_nop 0
	s_mov_b32 m0, s77
	s_nop 0
	global_load_lds_dwordx4 v136, s[98:99]
	s_nop 0
	s_mov_b32 m0, s78
	s_nop 0
	global_load_lds_dwordx4 v132, s[98:99]
	s_waitcnt vmcnt(8)
	s_waitcnt lgkmcnt(0)
	s_barrier
	s_nop 0
	s_waitcnt lgkmcnt(0)
	v_mfma_f32_16x16x32_bf16 v[62:65], v[146:149], v[182:185], v[62:65]
	v_mfma_f32_16x16x32_bf16 v[58:61], v[154:157], v[182:185], v[58:61]
	v_mfma_f32_16x16x32_bf16 v[54:57], v[146:149], v[194:197], v[54:57]
	v_mfma_f32_16x16x32_bf16 v[50:53], v[154:157], v[194:197], v[50:53]
	v_mfma_f32_16x16x32_bf16 v[38:41], v[146:149], v[202:205], v[38:41]
	v_mfma_f32_16x16x32_bf16 v[34:37], v[154:157], v[202:205], v[34:37]
	v_mfma_f32_16x16x32_bf16 v[22:25], v[146:149], v[216:219], v[22:25]
	v_mfma_f32_16x16x32_bf16 v[18:21], v[154:157], v[216:219], v[18:21]
	v_mfma_f32_16x16x32_bf16 v[62:65], v[150:153], v[190:193], v[62:65]
	v_mfma_f32_16x16x32_bf16 v[58:61], v[158:161], v[190:193], v[58:61]
	v_mfma_f32_16x16x32_bf16 v[54:57], v[150:153], v[198:201], v[54:57]
	v_mfma_f32_16x16x32_bf16 v[50:53], v[158:161], v[198:201], v[50:53]
	v_mfma_f32_16x16x32_bf16 v[38:41], v[150:153], v[212:215], v[38:41]
	v_mfma_f32_16x16x32_bf16 v[34:37], v[158:161], v[212:215], v[34:37]
	v_mfma_f32_16x16x32_bf16 v[22:25], v[150:153], v[220:223], v[22:25]
	v_mfma_f32_16x16x32_bf16 v[18:21], v[158:161], v[220:223], v[18:21]
	s_nop 0
	s_nop 0
	v_mfma_f32_16x16x32_bf16 v[46:49], v[162:165], v[182:185], v[46:49]
	v_mfma_f32_16x16x32_bf16 v[42:45], v[170:173], v[182:185], v[42:45]
	v_mfma_f32_16x16x32_bf16 v[30:33], v[162:165], v[194:197], v[30:33]
	v_mfma_f32_16x16x32_bf16 v[26:29], v[170:173], v[194:197], v[26:29]
	v_mfma_f32_16x16x32_bf16 v[14:17], v[162:165], v[202:205], v[14:17]
	v_mfma_f32_16x16x32_bf16 v[10:13], v[170:173], v[202:205], v[10:13]
	v_mfma_f32_16x16x32_bf16 v[6:9], v[162:165], v[216:219], v[6:9]
	v_mfma_f32_16x16x32_bf16 v[2:5], v[170:173], v[216:219], v[2:5]
	v_mfma_f32_16x16x32_bf16 v[46:49], v[166:169], v[190:193], v[46:49]
	v_mfma_f32_16x16x32_bf16 v[42:45], v[174:177], v[190:193], v[42:45]
	v_mfma_f32_16x16x32_bf16 v[30:33], v[166:169], v[198:201], v[30:33]
	v_mfma_f32_16x16x32_bf16 v[26:29], v[174:177], v[198:201], v[26:29]
	v_mfma_f32_16x16x32_bf16 v[14:17], v[166:169], v[212:215], v[14:17]
	v_mfma_f32_16x16x32_bf16 v[10:13], v[174:177], v[212:215], v[10:13]
	v_mfma_f32_16x16x32_bf16 v[6:9], v[166:169], v[220:223], v[6:9]
	v_mfma_f32_16x16x32_bf16 v[2:5], v[174:177], v[220:223], v[2:5]
	s_nop 0
	s_barrier
	s_add_i32 s85, s85, 2
	s_add_u32 s83, s83, 0x100
	s_addc_u32 s84, s84, 0
	s_cmp_gt_u32 s85, 41
	s_mov_b64 s[58:59], s[60:61]
	s_cbranch_scc0 .LBB0_1204
	s_and_b64 vcc, exec, s[52:53]
	s_cbranch_vccz .LBB0_1207
	s_barrier
